# v57 + per-segment s_setprio toggles removed from the nine K-loops (lever 4: per-segment toggling does not pay; 16 fewer SALU per body)
# speedup vs baseline: 1.0044x; 1.0044x over previous
;     __host__ __device__ bool next(int i, Unit& u) const { const int P = (i >> 1) * G + c; if (P >= 256) return false; u.pm = P >> 3; u.pn = (P & 7) + 8 * (i & 1); return true; }
; #define PG8_STAGE(bufoff, gbase, voff) do { _Pragma("unroll") for (int _i = 0; _i < 2; ++_i) \
;         __builtin_amdgcn_global_load_lds((const unsigned*)((const char*)(gbase) + (voff)[_i]), (PG8_LAS unsigned*)(lds + (bufoff) + ldsw + _i * 8192), 16, 0, 0); } while (0)
; #define PG8_LDA(dst, b, h) do { _Pragma("unroll") for (int m = 0; m < 4; ++m) _Pragma("unroll") for (int k = 0; k < 2; ++k) dst[m][k] = *(const PG8_LAS bf16x8*)(lds + PG8_SA(b, h) + aoff + m * 2048 + k * 1024); } while (0)
; #define PG8_LDB(dst, b, h) do { _Pragma("unroll") for (int n = 0; n < 2; ++n) _Pragma("unroll") for (int k = 0; k < 2; ++k) dst[n][k] = *(const PG8_LAS bf16x8*)(lds + PG8_SB(b, h) + boff + n * 2048 + k * 1024); } while (0)
; #define PG8_BAR __builtin_amdgcn_s_barrier()
; template <class Epi, class Sched, bool ALIGN_EPI = false, bool SP2 = false>
; __device__ __forceinline__ void gemm_phase(PG8_LAS unsigned char* lds, const Gemm g, const Sched& S, const Epi& E, const int wv) {
;     ...
;         const bool has_next = S.next(ui + 1, nxt);
;         const char* nA = has_next ? (const char*)g.A + (size_t)nxt.pm * tstepA + (g.amod ? (size_t)(nxt.pn % g.amod) * K * 2 : (size_t)0) : cA; const char* nB = has_next ? (const char*)g.Bt + (size_t)nxt.pn * tstepB : cB;
;         for (int t = 0; t < nt; t += 2) {
;             const bool last = (t == nt - 2);
;             const char* a1 = cA + (size_t)(t + 1) * kstep;
;             const char* a2 = last ? nA : cA + (size_t)(t + 2) * kstep; const char* b2 = last ? nB : cB + (size_t)(t + 2) * kstep;
;             const char* a3 = a2 + kstep; const char* b3 = b2 + kstep;
;             if (last && has_next) S.a_ready(nxt);
;             if constexpr (SP2) {
;             PG8_LDB(B0, 0, 0); PG8_LDB(B1, 0, 1); PG8_SCHED; PG8_LDA(At, 0, 0); PG8_STAGE(PG8_SA(1, 1), a1 + hstepA, voffA);
;             PG8_WAIT_V(8); PG8_WAIT_L(0); PG8_BAR; PG8_MMA(0, 0, At, B0); PG8_MMA(0, 1, At, B1); PG8_BAR; PG8_SCHED;
;             PG8_LDA(At, 0, 1); PG8_STAGE(PG8_SB(0, 0), b2, voffB); PG8_STAGE(PG8_SB(0, 1), b2 + hstepB, voffB); PG8_STAGE(PG8_SA(0, 0), a2, voffA);
;             PG8_WAIT_V(8); PG8_WAIT_L(0); PG8_BAR; PG8_MMA(1, 0, At, B0); PG8_MMA(1, 1, At, B1); PG8_BAR; PG8_SCHED;
.LBB0_176:
	s_add_i32 s67, s14, 2
	s_add_u32 s68, s12, 0xfff80080
	s_addc_u32 s15, s13, -1
	s_add_i32 s70, 0, 0x10000
	s_cmp_eq_u32 s61, s14
	s_cselect_b32 s15, s11, s15
	s_cselect_b32 s14, s35, s68
	v_add_u32_e32 v59, s70, v185
	s_cselect_b32 s69, s45, s43
	s_cselect_b32 s68, s44, s42
	s_add_i32 s71, 0, 0x14000
	ds_read_b128 v[66:69], v59
	ds_read_b128 v[74:77], v59 offset:1024
	ds_read_b128 v[82:85], v59 offset:2048
	ds_read_b128 v[86:89], v59 offset:3072
	v_add_u32_e32 v59, s71, v185
	ds_read_b128 v[154:157], v59
	ds_read_b128 v[158:161], v59 offset:1024
	ds_read_b128 v[174:177], v59 offset:2048
	ds_read_b128 v[178:181], v59 offset:3072
	v_lshl_add_u64 v[60:61], s[12:13], 0, v[170:171]
	s_add_i32 m0, s54, 0xc000
	ds_read_b128 v[202:205], v200
	ds_read_b128 v[206:209], v200 offset:1024
	ds_read_b128 v[210:213], v200 offset:2048
	ds_read_b128 v[214:217], v200 offset:3072
	ds_read_b128 v[228:231], v200 offset:4096
	ds_read_b128 v[232:235], v200 offset:5120
	ds_read_b128 v[236:239], v200 offset:6144
	ds_read_b128 v[240:243], v200 offset:7168
	global_load_lds_dwordx4 v[60:61], off
	v_lshl_add_u64 v[60:61], s[12:13], 0, v[172:173]
	s_add_i32 m0, s54, 0xe000
	s_nop 0
	global_load_lds_dwordx4 v[60:61], off
	s_waitcnt vmcnt(8)
	s_waitcnt lgkmcnt(0)
	s_barrier
	s_waitcnt lgkmcnt(0)
	v_mfma_f32_16x16x32_bf16 v[150:153], v[66:69], v[202:205], v[150:153]
	v_mfma_f32_16x16x32_bf16 v[146:149], v[82:85], v[202:205], v[146:149]
	v_mfma_f32_16x16x32_bf16 v[134:137], v[66:69], v[210:213], v[134:137]
	v_mfma_f32_16x16x32_bf16 v[130:133], v[82:85], v[210:213], v[130:133]
	v_mfma_f32_16x16x32_bf16 v[118:121], v[66:69], v[228:231], v[118:121]
	v_mfma_f32_16x16x32_bf16 v[114:117], v[82:85], v[228:231], v[114:117]
	v_mfma_f32_16x16x32_bf16 v[102:105], v[66:69], v[236:239], v[102:105]
	v_mfma_f32_16x16x32_bf16 v[98:101], v[82:85], v[236:239], v[98:101]
	v_mfma_f32_16x16x32_bf16 v[150:153], v[74:77], v[206:209], v[150:153]
	v_mfma_f32_16x16x32_bf16 v[146:149], v[86:89], v[206:209], v[146:149]
	v_mfma_f32_16x16x32_bf16 v[134:137], v[74:77], v[214:217], v[134:137]
	v_mfma_f32_16x16x32_bf16 v[130:133], v[86:89], v[214:217], v[130:133]
	v_mfma_f32_16x16x32_bf16 v[118:121], v[74:77], v[232:235], v[118:121]
	v_mfma_f32_16x16x32_bf16 v[114:117], v[86:89], v[232:235], v[114:117]
	v_mfma_f32_16x16x32_bf16 v[102:105], v[74:77], v[240:243], v[102:105]
	v_mfma_f32_16x16x32_bf16 v[98:101], v[86:89], v[240:243], v[98:101]
	v_mfma_f32_16x16x32_bf16 v[142:145], v[154:157], v[202:205], v[142:145]
	v_mfma_f32_16x16x32_bf16 v[138:141], v[174:177], v[202:205], v[138:141]
	v_mfma_f32_16x16x32_bf16 v[126:129], v[154:157], v[210:213], v[126:129]
	v_mfma_f32_16x16x32_bf16 v[122:125], v[174:177], v[210:213], v[122:125]
	v_mfma_f32_16x16x32_bf16 v[110:113], v[154:157], v[228:231], v[110:113]
	v_mfma_f32_16x16x32_bf16 v[106:109], v[174:177], v[228:231], v[106:109]
	v_mfma_f32_16x16x32_bf16 v[94:97], v[154:157], v[236:239], v[94:97]
	v_mfma_f32_16x16x32_bf16 v[90:93], v[174:177], v[236:239], v[90:93]
	v_mfma_f32_16x16x32_bf16 v[142:145], v[158:161], v[206:209], v[142:145]
	v_mfma_f32_16x16x32_bf16 v[138:141], v[178:181], v[206:209], v[138:141]
	v_mfma_f32_16x16x32_bf16 v[126:129], v[158:161], v[214:217], v[126:129]
	v_mfma_f32_16x16x32_bf16 v[122:125], v[178:181], v[214:217], v[122:125]
	v_mfma_f32_16x16x32_bf16 v[110:113], v[158:161], v[232:235], v[110:113]
	v_mfma_f32_16x16x32_bf16 v[106:109], v[178:181], v[232:235], v[106:109]
	v_mfma_f32_16x16x32_bf16 v[94:97], v[158:161], v[240:243], v[94:97]
	v_mfma_f32_16x16x32_bf16 v[90:93], v[178:181], v[240:243], v[90:93]
	s_barrier
	s_add_i32 s70, s70, s53
	v_lshl_add_u64 v[218:219], s[68:69], 0, v[0:1]
	s_mov_b32 m0, s70
	ds_read_b128 v[202:205], v200 offset:16384
	ds_read_b128 v[206:209], v200 offset:17408
	ds_read_b128 v[210:213], v200 offset:18432
	ds_read_b128 v[214:217], v200 offset:19456
	ds_read_b128 v[228:231], v200 offset:20480
	ds_read_b128 v[232:235], v200 offset:21504
	ds_read_b128 v[236:239], v200 offset:22528
	ds_read_b128 v[240:243], v200 offset:23552
	global_load_lds_dwordx4 v[218:219], off
	s_add_i32 m0, s70, 0x2000
	v_lshl_add_u64 v[244:245], s[68:69], 0, v[166:167]
	s_add_u32 s68, s68, s24
	s_addc_u32 s69, s69, s25
	s_add_i32 s70, s71, s53
	global_load_lds_dwordx4 v[244:245], off
	v_lshl_add_u64 v[246:247], s[68:69], 0, v[0:1]
	s_mov_b32 m0, s70
	v_lshl_add_u64 v[248:249], s[68:69], 0, v[166:167]
	global_load_lds_dwordx4 v[246:247], off
	s_add_i32 m0, s70, 0x2000
	v_lshl_add_u64 v[250:251], s[14:15], 0, v[162:163]
	global_load_lds_dwordx4 v[248:249], off
	s_mov_b32 m0, s54
	v_lshl_add_u64 v[252:253], s[14:15], 0, v[164:165]
	global_load_lds_dwordx4 v[250:251], off
	s_mov_b32 m0, s55
	s_nop 0
	global_load_lds_dwordx4 v[252:253], off
	s_waitcnt vmcnt(8)
	s_waitcnt lgkmcnt(0)
	s_barrier
; #define PG8_STAGE(bufoff, gbase, voff) do { _Pragma("unroll") for (int _i = 0; _i < 2; ++_i) \
;         __builtin_amdgcn_global_load_lds((const unsigned*)((const char*)(gbase) + (voff)[_i]), (PG8_LAS unsigned*)(lds + (bufoff) + ldsw + _i * 8192), 16, 0, 0); } while (0)
; #define PG8_LDA(dst, b, h) do { _Pragma("unroll") for (int m = 0; m < 4; ++m) _Pragma("unroll") for (int k = 0; k < 2; ++k) dst[m][k] = *(const PG8_LAS bf16x8*)(lds + PG8_SA(b, h) + aoff + m * 2048 + k * 1024); } while (0)
; #define PG8_LDB(dst, b, h) do { _Pragma("unroll") for (int n = 0; n < 2; ++n) _Pragma("unroll") for (int k = 0; k < 2; ++k) dst[n][k] = *(const PG8_LAS bf16x8*)(lds + PG8_SB(b, h) + boff + n * 2048 + k * 1024); } while (0)
; #define PG8_MMA(ai, bj, At, Bt) do { __builtin_amdgcn_s_setprio(1); _Pragma("unroll") for (int m = 0; m < 4; ++m) _Pragma("unroll") for (int n = 0; n < 2; ++n) _Pragma("unroll") for (int k = 0; k < 2; ++k) \
;         acc[ai][bj][m][n] = __builtin_amdgcn_mfma_f32_16x16x32_bf16(Bt[n][k], At[m][k], acc[ai][bj][m][n], 0, 0, 0); __builtin_amdgcn_s_setprio(0); } while (0)
; #define PG8_WAIT_V(n) asm volatile("s_waitcnt vmcnt(" #n ")" ::: "memory")
; #define PG8_WAIT_L(n) asm volatile("s_waitcnt lgkmcnt(" #n ")" ::: "memory")
; #define PG8_BAR __builtin_amdgcn_s_barrier()
; #define PG8_SCHED __builtin_amdgcn_sched_barrier(0)
; template <class Epi, class Sched, bool ALIGN_EPI = false, bool SP2 = false>
; __device__ __forceinline__ void gemm_phase(PG8_LAS unsigned char* lds, const Gemm g, const Sched& S, const Epi& E, const int wv) {
;     ...
;             PG8_WAIT_V(8); PG8_WAIT_L(0); PG8_BAR; PG8_MMA(1, 0, At, B0); PG8_MMA(1, 1, At, B1); PG8_BAR; PG8_SCHED;
;             PG8_LDB(B0, 1, 0); PG8_LDB(B1, 1, 1); PG8_SCHED; PG8_LDA(At, 1, 0); PG8_STAGE(PG8_SA(0, 1), a2 + hstepA, voffA);
;             PG8_WAIT_V(8); PG8_WAIT_L(0); PG8_BAR; PG8_MMA(0, 0, At, B0); PG8_MMA(0, 1, At, B1); PG8_BAR; PG8_SCHED;
	s_waitcnt lgkmcnt(0)
	v_mfma_f32_16x16x32_bf16 v[78:81], v[66:69], v[202:205], v[78:81]
	v_mfma_f32_16x16x32_bf16 v[70:73], v[82:85], v[202:205], v[70:73]
	v_mfma_f32_16x16x32_bf16 v[46:49], v[66:69], v[210:213], v[46:49]
	v_mfma_f32_16x16x32_bf16 v[42:45], v[82:85], v[210:213], v[42:45]
	v_mfma_f32_16x16x32_bf16 v[30:33], v[66:69], v[228:231], v[30:33]
	v_mfma_f32_16x16x32_bf16 v[26:29], v[82:85], v[228:231], v[26:29]
	v_mfma_f32_16x16x32_bf16 v[14:17], v[66:69], v[236:239], v[14:17]
	v_mfma_f32_16x16x32_bf16 v[10:13], v[82:85], v[236:239], v[10:13]
	v_mfma_f32_16x16x32_bf16 v[78:81], v[74:77], v[206:209], v[78:81]
	v_mfma_f32_16x16x32_bf16 v[70:73], v[86:89], v[206:209], v[70:73]
	v_mfma_f32_16x16x32_bf16 v[46:49], v[74:77], v[214:217], v[46:49]
	v_mfma_f32_16x16x32_bf16 v[42:45], v[86:89], v[214:217], v[42:45]
	v_mfma_f32_16x16x32_bf16 v[30:33], v[74:77], v[232:235], v[30:33]
	v_mfma_f32_16x16x32_bf16 v[26:29], v[86:89], v[232:235], v[26:29]
	v_mfma_f32_16x16x32_bf16 v[14:17], v[74:77], v[240:243], v[14:17]
	v_mfma_f32_16x16x32_bf16 v[10:13], v[86:89], v[240:243], v[10:13]
	v_mfma_f32_16x16x32_bf16 v[60:63], v[154:157], v[202:205], v[62:65]
	v_mfma_f32_16x16x32_bf16 v[54:57], v[174:177], v[202:205], v[54:57]
	v_mfma_f32_16x16x32_bf16 v[38:41], v[154:157], v[210:213], v[38:41]
	v_mfma_f32_16x16x32_bf16 v[34:37], v[174:177], v[210:213], v[34:37]
	v_mfma_f32_16x16x32_bf16 v[22:25], v[154:157], v[228:231], v[22:25]
	v_mfma_f32_16x16x32_bf16 v[18:21], v[174:177], v[228:231], v[18:21]
	v_mfma_f32_16x16x32_bf16 v[6:9], v[154:157], v[236:239], v[6:9]
	v_mfma_f32_16x16x32_bf16 v[2:5], v[174:177], v[236:239], v[2:5]
	v_mfma_f32_16x16x32_bf16 v[60:63], v[158:161], v[206:209], v[60:63]
	v_mfma_f32_16x16x32_bf16 v[54:57], v[178:181], v[206:209], v[54:57]
	v_mfma_f32_16x16x32_bf16 v[38:41], v[158:161], v[214:217], v[38:41]
	v_mfma_f32_16x16x32_bf16 v[34:37], v[178:181], v[214:217], v[34:37]
	v_mfma_f32_16x16x32_bf16 v[22:25], v[158:161], v[232:235], v[22:25]
	v_mfma_f32_16x16x32_bf16 v[18:21], v[178:181], v[232:235], v[18:21]
	v_mfma_f32_16x16x32_bf16 v[6:9], v[158:161], v[240:243], v[6:9]
	v_mfma_f32_16x16x32_bf16 v[2:5], v[178:181], v[240:243], v[2:5]
	s_barrier
	s_add_i32 s68, 0, 0x18000
	v_add_u32_e32 v59, s68, v185
	s_add_i32 s69, 0, 0x1c000
	ds_read_b128 v[64:67], v59
	ds_read_b128 v[74:77], v59 offset:1024
	ds_read_b128 v[82:85], v59 offset:2048
	ds_read_b128 v[86:89], v59 offset:3072
	v_add_u32_e32 v59, s69, v185
	ds_read_b128 v[154:157], v59
	ds_read_b128 v[158:161], v59 offset:1024
	ds_read_b128 v[174:177], v59 offset:2048
	ds_read_b128 v[178:181], v59 offset:3072
	s_add_u32 s14, s14, 0x80000
	s_addc_u32 s15, s15, 0
	s_mov_b32 m0, s56
	v_lshl_add_u64 v[68:69], s[14:15], 0, v[162:163]
	ds_read_b128 v[202:205], v200 offset:32768
	ds_read_b128 v[206:209], v200 offset:33792
	ds_read_b128 v[210:213], v200 offset:34816
	ds_read_b128 v[214:217], v200 offset:35840
	ds_read_b128 v[228:231], v200 offset:36864
	ds_read_b128 v[232:235], v200 offset:37888
	ds_read_b128 v[236:239], v200 offset:38912
	ds_read_b128 v[240:243], v200 offset:39936
	global_load_lds_dwordx4 v[68:69], off
	v_lshl_add_u64 v[68:69], s[14:15], 0, v[164:165]
	s_mov_b32 m0, s57
	s_nop 0
	global_load_lds_dwordx4 v[68:69], off
	s_waitcnt vmcnt(8)
	s_waitcnt lgkmcnt(0)
	s_barrier
	s_waitcnt lgkmcnt(0)
	v_mfma_f32_16x16x32_bf16 v[150:153], v[64:67], v[202:205], v[150:153]
	v_mfma_f32_16x16x32_bf16 v[146:149], v[82:85], v[202:205], v[146:149]
	v_mfma_f32_16x16x32_bf16 v[134:137], v[64:67], v[210:213], v[134:137]
	v_mfma_f32_16x16x32_bf16 v[130:133], v[82:85], v[210:213], v[130:133]
	v_mfma_f32_16x16x32_bf16 v[118:121], v[64:67], v[228:231], v[118:121]
	v_mfma_f32_16x16x32_bf16 v[114:117], v[82:85], v[228:231], v[114:117]
	v_mfma_f32_16x16x32_bf16 v[102:105], v[64:67], v[236:239], v[102:105]
	v_mfma_f32_16x16x32_bf16 v[98:101], v[82:85], v[236:239], v[98:101]
	v_mfma_f32_16x16x32_bf16 v[150:153], v[74:77], v[206:209], v[150:153]
	v_mfma_f32_16x16x32_bf16 v[146:149], v[86:89], v[206:209], v[146:149]
	v_mfma_f32_16x16x32_bf16 v[134:137], v[74:77], v[214:217], v[134:137]
	v_mfma_f32_16x16x32_bf16 v[130:133], v[86:89], v[214:217], v[130:133]
	v_mfma_f32_16x16x32_bf16 v[118:121], v[74:77], v[232:235], v[118:121]
	v_mfma_f32_16x16x32_bf16 v[114:117], v[86:89], v[232:235], v[114:117]
	v_mfma_f32_16x16x32_bf16 v[102:105], v[74:77], v[240:243], v[102:105]
	v_mfma_f32_16x16x32_bf16 v[98:101], v[86:89], v[240:243], v[98:101]
	v_mfma_f32_16x16x32_bf16 v[142:145], v[154:157], v[202:205], v[142:145]
	v_mfma_f32_16x16x32_bf16 v[138:141], v[174:177], v[202:205], v[138:141]
	v_mfma_f32_16x16x32_bf16 v[126:129], v[154:157], v[210:213], v[126:129]
	v_mfma_f32_16x16x32_bf16 v[122:125], v[174:177], v[210:213], v[122:125]
	v_mfma_f32_16x16x32_bf16 v[110:113], v[154:157], v[228:231], v[110:113]
	v_mfma_f32_16x16x32_bf16 v[106:109], v[174:177], v[228:231], v[106:109]
	v_mfma_f32_16x16x32_bf16 v[94:97], v[154:157], v[236:239], v[94:97]
	v_mfma_f32_16x16x32_bf16 v[90:93], v[174:177], v[236:239], v[90:93]
	v_mfma_f32_16x16x32_bf16 v[142:145], v[158:161], v[206:209], v[142:145]
	v_mfma_f32_16x16x32_bf16 v[138:141], v[178:181], v[206:209], v[138:141]
	v_mfma_f32_16x16x32_bf16 v[126:129], v[158:161], v[214:217], v[126:129]
	v_mfma_f32_16x16x32_bf16 v[122:125], v[178:181], v[214:217], v[122:125]
	v_mfma_f32_16x16x32_bf16 v[110:113], v[158:161], v[232:235], v[110:113]
	v_mfma_f32_16x16x32_bf16 v[106:109], v[178:181], v[232:235], v[106:109]
	v_mfma_f32_16x16x32_bf16 v[94:97], v[158:161], v[240:243], v[94:97]
	v_mfma_f32_16x16x32_bf16 v[90:93], v[178:181], v[240:243], v[90:93]
	s_barrier
; #define PG8_STAGE(bufoff, gbase, voff) do { _Pragma("unroll") for (int _i = 0; _i < 2; ++_i) \
;         __builtin_amdgcn_global_load_lds((const unsigned*)((const char*)(gbase) + (voff)[_i]), (PG8_LAS unsigned*)(lds + (bufoff) + ldsw + _i * 8192), 16, 0, 0); } while (0)
; #define PG8_LDA(dst, b, h) do { _Pragma("unroll") for (int m = 0; m < 4; ++m) _Pragma("unroll") for (int k = 0; k < 2; ++k) dst[m][k] = *(const PG8_LAS bf16x8*)(lds + PG8_SA(b, h) + aoff + m * 2048 + k * 1024); } while (0)
; #define PG8_MMA(ai, bj, At, Bt) do { __builtin_amdgcn_s_setprio(1); _Pragma("unroll") for (int m = 0; m < 4; ++m) _Pragma("unroll") for (int n = 0; n < 2; ++n) _Pragma("unroll") for (int k = 0; k < 2; ++k) \
;         acc[ai][bj][m][n] = __builtin_amdgcn_mfma_f32_16x16x32_bf16(Bt[n][k], At[m][k], acc[ai][bj][m][n], 0, 0, 0); __builtin_amdgcn_s_setprio(0); } while (0)
; #define PG8_WAIT_V(n) asm volatile("s_waitcnt vmcnt(" #n ")" ::: "memory")
; #define PG8_WAIT_L(n) asm volatile("s_waitcnt lgkmcnt(" #n ")" ::: "memory")
; #define PG8_BAR __builtin_amdgcn_s_barrier()
; #define PG8_SCHED __builtin_amdgcn_sched_barrier(0)
; template <class Epi, class Sched, bool ALIGN_EPI = false, bool SP2 = false>
; __device__ __forceinline__ void gemm_phase(PG8_LAS unsigned char* lds, const Gemm g, const Sched& S, const Epi& E, const int wv) {
;     ...
;         for (int t = 0; t < nt; t += 2) {
;             const bool last = (t == nt - 2);
;             const char* a1 = cA + (size_t)(t + 1) * kstep;
;             const char* a2 = last ? nA : cA + (size_t)(t + 2) * kstep; const char* b2 = last ? nB : cB + (size_t)(t + 2) * kstep;
;             const char* a3 = a2 + kstep; const char* b3 = b2 + kstep;
;     ...
;             PG8_LDA(At, 1, 1); PG8_STAGE(PG8_SB(1, 0), b3, voffB); PG8_STAGE(PG8_SB(1, 1), b3 + hstepB, voffB); PG8_STAGE(PG8_SA(1, 0), a3, voffA);
;             PG8_WAIT_V(8); PG8_WAIT_L(0); PG8_BAR; PG8_MMA(1, 0, At, B0); PG8_MMA(1, 1, At, B1); PG8_BAR; PG8_SCHED;
	s_add_i32 s14, s68, s53
	v_lshl_add_u64 v[68:69], v[218:219], 0, s[4:5]
	s_mov_b32 m0, s14
	ds_read_b128 v[202:205], v200 offset:49152
	ds_read_b128 v[206:209], v200 offset:50176
	ds_read_b128 v[210:213], v200 offset:51200
	ds_read_b128 v[214:217], v200 offset:52224
	ds_read_b128 v[228:231], v200 offset:53248
	ds_read_b128 v[232:235], v200 offset:54272
	ds_read_b128 v[236:239], v200 offset:55296
	ds_read_b128 v[240:243], v200 offset:56320
	global_load_lds_dwordx4 v[68:69], off
	v_lshl_add_u64 v[68:69], v[244:245], 0, s[4:5]
	s_add_i32 m0, s14, 0x2000
	s_add_i32 s14, s69, s53
	global_load_lds_dwordx4 v[68:69], off
	v_lshl_add_u64 v[68:69], v[246:247], 0, s[4:5]
	s_mov_b32 m0, s14
	s_nop 0
	global_load_lds_dwordx4 v[68:69], off
	v_lshl_add_u64 v[68:69], v[248:249], 0, s[4:5]
	s_add_i32 m0, s14, 0x2000
	s_nop 0
	global_load_lds_dwordx4 v[68:69], off
	v_lshl_add_u64 v[68:69], v[250:251], 0, s[4:5]
	s_mov_b32 m0, s58
	s_nop 0
	global_load_lds_dwordx4 v[68:69], off
	v_lshl_add_u64 v[68:69], v[252:253], 0, s[4:5]
	s_mov_b32 m0, s59
	s_nop 0
	global_load_lds_dwordx4 v[68:69], off
	s_waitcnt vmcnt(8)
	s_waitcnt lgkmcnt(0)
	s_barrier
	s_waitcnt lgkmcnt(0)
	v_mfma_f32_16x16x32_bf16 v[78:81], v[64:67], v[202:205], v[78:81]
	v_mfma_f32_16x16x32_bf16 v[68:71], v[82:85], v[202:205], v[70:73]
	v_mfma_f32_16x16x32_bf16 v[46:49], v[64:67], v[210:213], v[46:49]
	v_mfma_f32_16x16x32_bf16 v[42:45], v[82:85], v[210:213], v[42:45]
	v_mfma_f32_16x16x32_bf16 v[30:33], v[64:67], v[228:231], v[30:33]
	v_mfma_f32_16x16x32_bf16 v[26:29], v[82:85], v[228:231], v[26:29]
	v_mfma_f32_16x16x32_bf16 v[14:17], v[64:67], v[236:239], v[14:17]
	v_mfma_f32_16x16x32_bf16 v[10:13], v[82:85], v[236:239], v[10:13]
	v_mfma_f32_16x16x32_bf16 v[78:81], v[74:77], v[206:209], v[78:81]
	v_mfma_f32_16x16x32_bf16 v[70:73], v[86:89], v[206:209], v[68:71]
	v_mfma_f32_16x16x32_bf16 v[46:49], v[74:77], v[214:217], v[46:49]
	v_mfma_f32_16x16x32_bf16 v[42:45], v[86:89], v[214:217], v[42:45]
	v_mfma_f32_16x16x32_bf16 v[30:33], v[74:77], v[232:235], v[30:33]
	v_mfma_f32_16x16x32_bf16 v[26:29], v[86:89], v[232:235], v[26:29]
	v_mfma_f32_16x16x32_bf16 v[14:17], v[74:77], v[240:243], v[14:17]
	v_mfma_f32_16x16x32_bf16 v[10:13], v[86:89], v[240:243], v[10:13]
	v_mfma_f32_16x16x32_bf16 v[60:63], v[154:157], v[202:205], v[60:63]
	v_mfma_f32_16x16x32_bf16 v[54:57], v[174:177], v[202:205], v[54:57]
	v_mfma_f32_16x16x32_bf16 v[38:41], v[154:157], v[210:213], v[38:41]
	v_mfma_f32_16x16x32_bf16 v[34:37], v[174:177], v[210:213], v[34:37]
	v_mfma_f32_16x16x32_bf16 v[22:25], v[154:157], v[228:231], v[22:25]
	v_mfma_f32_16x16x32_bf16 v[18:21], v[174:177], v[228:231], v[18:21]
	v_mfma_f32_16x16x32_bf16 v[6:9], v[154:157], v[236:239], v[6:9]
	v_mfma_f32_16x16x32_bf16 v[2:5], v[174:177], v[236:239], v[2:5]
	v_mfma_f32_16x16x32_bf16 v[62:65], v[158:161], v[206:209], v[60:63]
	v_mfma_f32_16x16x32_bf16 v[54:57], v[178:181], v[206:209], v[54:57]
	v_mfma_f32_16x16x32_bf16 v[38:41], v[158:161], v[214:217], v[38:41]
	v_mfma_f32_16x16x32_bf16 v[34:37], v[178:181], v[214:217], v[34:37]
	v_mfma_f32_16x16x32_bf16 v[22:25], v[158:161], v[232:235], v[22:25]
	v_mfma_f32_16x16x32_bf16 v[18:21], v[178:181], v[232:235], v[18:21]
	v_mfma_f32_16x16x32_bf16 v[6:9], v[158:161], v[240:243], v[6:9]
	v_mfma_f32_16x16x32_bf16 v[2:5], v[178:181], v[240:243], v[2:5]
	s_barrier
	s_add_u32 s12, s12, 0x100
	s_addc_u32 s13, s13, 0
	s_add_u32 s42, s42, 0x100
	s_addc_u32 s43, s43, 0
	s_cmp_ge_i32 s67, s60
	s_mov_b32 s14, s67
	s_cbranch_scc0 .LBB0_176
	s_movk_i32 s68, 0x4000
	s_movk_i32 s69, 0x6000
	s_mov_b32 s70, 0x18000
	s_mov_b32 s71, 0x3f317217

;     __host__ __device__ bool next(int i, Unit& u) const { const int P = (i >> 1) * G + c; if (P >= 256) return false; u.pm = P >> 3; u.pn = (P & 7) + 8 * (i & 1); return true; }
; #define PG8_STAGE(bufoff, gbase, voff) do { _Pragma("unroll") for (int _i = 0; _i < 2; ++_i) \
;         __builtin_amdgcn_global_load_lds((const unsigned*)((const char*)(gbase) + (voff)[_i]), (PG8_LAS unsigned*)(lds + (bufoff) + ldsw + _i * 8192), 16, 0, 0); } while (0)
; #define PG8_LDA(dst, b, h) do { _Pragma("unroll") for (int m = 0; m < 4; ++m) _Pragma("unroll") for (int k = 0; k < 2; ++k) dst[m][k] = *(const PG8_LAS bf16x8*)(lds + PG8_SA(b, h) + aoff + m * 2048 + k * 1024); } while (0)
; #define PG8_LDB(dst, b, h) do { _Pragma("unroll") for (int n = 0; n < 2; ++n) _Pragma("unroll") for (int k = 0; k < 2; ++k) dst[n][k] = *(const PG8_LAS bf16x8*)(lds + PG8_SB(b, h) + boff + n * 2048 + k * 1024); } while (0)
; #define PG8_BAR __builtin_amdgcn_s_barrier()
; template <class Epi, class Sched, bool ALIGN_EPI = false, bool SP2 = false>
; __device__ __forceinline__ void gemm_phase(PG8_LAS unsigned char* lds, const Gemm g, const Sched& S, const Epi& E, const int wv) {
;     ...
;         const bool has_next = S.next(ui + 1, nxt);
;         const char* nA = has_next ? (const char*)g.A + (size_t)nxt.pm * tstepA + (g.amod ? (size_t)(nxt.pn % g.amod) * K * 2 : (size_t)0) : cA; const char* nB = has_next ? (const char*)g.Bt + (size_t)nxt.pn * tstepB : cB;
;         for (int t = 0; t < nt; t += 2) {
;             const bool last = (t == nt - 2);
;             const char* a1 = cA + (size_t)(t + 1) * kstep;
;             const char* a2 = last ? nA : cA + (size_t)(t + 2) * kstep; const char* b2 = last ? nB : cB + (size_t)(t + 2) * kstep;
;             const char* a3 = a2 + kstep; const char* b3 = b2 + kstep;
;             if (last && has_next) S.a_ready(nxt);
;             if constexpr (SP2) {
;             PG8_LDB(B0, 0, 0); PG8_LDB(B1, 0, 1); PG8_SCHED; PG8_LDA(At, 0, 0); PG8_STAGE(PG8_SA(1, 1), a1 + hstepA, voffA);
;             PG8_WAIT_V(8); PG8_WAIT_L(0); PG8_BAR; PG8_MMA(0, 0, At, B0); PG8_MMA(0, 1, At, B1); PG8_BAR; PG8_SCHED;
;             PG8_LDA(At, 0, 1); PG8_STAGE(PG8_SB(0, 0), b2, voffB); PG8_STAGE(PG8_SB(0, 1), b2 + hstepB, voffB); PG8_STAGE(PG8_SA(0, 0), a2, voffA);
;             PG8_WAIT_V(8); PG8_WAIT_L(0); PG8_BAR; PG8_MMA(1, 0, At, B0); PG8_MMA(1, 1, At, B1); PG8_BAR; PG8_SCHED;
.LBB0_336:
	s_add_i32 s40, s14, 2
	s_add_u32 s41, s12, 0xfff80080
	s_addc_u32 s15, s13, -1
	s_add_i32 s65, 0, 0x10000
	s_cmp_eq_u32 s62, s14
	s_cselect_b32 s15, s93, s15
	s_cselect_b32 s14, s92, s41
	s_cselect_b32 s45, s25, s17
	s_cselect_b32 s44, s24, s11
	s_add_i32 s41, 0, 0x14000
	v_add_u32_e32 v46, s65, v197
	v_add_u32_e32 v158, s41, v197
	ds_read_b128 v[26:29], v46
	ds_read_b128 v[30:33], v46 offset:1024
	ds_read_b128 v[42:45], v46 offset:2048
	ds_read_b128 v[46:49], v46 offset:3072
	ds_read_b128 v[146:149], v158
	ds_read_b128 v[150:153], v158 offset:1024
	ds_read_b128 v[154:157], v158 offset:2048
	ds_read_b128 v[158:161], v158 offset:3072
	v_lshl_add_u64 v[184:185], s[12:13], 0, v[168:169]
	s_add_i32 m0, s55, 0xc000
	ds_read_b128 v[172:175], v199
	ds_read_b128 v[176:179], v199 offset:1024
	ds_read_b128 v[180:183], v199 offset:2048
	ds_read_b128 v[200:203], v199 offset:3072
	ds_read_b128 v[204:207], v199 offset:4096
	ds_read_b128 v[208:211], v199 offset:5120
	ds_read_b128 v[212:215], v199 offset:6144
	ds_read_b128 v[216:219], v199 offset:7168
	global_load_lds_dwordx4 v[184:185], off
	v_lshl_add_u64 v[184:185], s[12:13], 0, v[170:171]
	s_add_i32 m0, s55, 0xe000
	s_nop 0
	global_load_lds_dwordx4 v[184:185], off
	s_waitcnt vmcnt(8)
	s_waitcnt lgkmcnt(0)
	s_barrier
	s_waitcnt lgkmcnt(0)
	v_mfma_f32_16x16x32_bf16 v[138:141], v[26:29], v[172:175], v[138:141]
	v_mfma_f32_16x16x32_bf16 v[142:145], v[42:45], v[172:175], v[142:145]
	v_mfma_f32_16x16x32_bf16 v[126:129], v[26:29], v[180:183], v[126:129]
	v_mfma_f32_16x16x32_bf16 v[122:125], v[42:45], v[180:183], v[122:125]
	v_mfma_f32_16x16x32_bf16 v[110:113], v[26:29], v[204:207], v[110:113]
	v_mfma_f32_16x16x32_bf16 v[106:109], v[42:45], v[204:207], v[106:109]
	v_mfma_f32_16x16x32_bf16 v[94:97], v[26:29], v[212:215], v[94:97]
	v_mfma_f32_16x16x32_bf16 v[90:93], v[42:45], v[212:215], v[90:93]
	v_mfma_f32_16x16x32_bf16 v[138:141], v[30:33], v[176:179], v[138:141]
	v_mfma_f32_16x16x32_bf16 v[142:145], v[46:49], v[176:179], v[142:145]
	v_mfma_f32_16x16x32_bf16 v[126:129], v[30:33], v[200:203], v[126:129]
	v_mfma_f32_16x16x32_bf16 v[122:125], v[46:49], v[200:203], v[122:125]
	v_mfma_f32_16x16x32_bf16 v[110:113], v[30:33], v[208:211], v[110:113]
	v_mfma_f32_16x16x32_bf16 v[106:109], v[46:49], v[208:211], v[106:109]
	v_mfma_f32_16x16x32_bf16 v[94:97], v[30:33], v[216:219], v[94:97]
	v_mfma_f32_16x16x32_bf16 v[90:93], v[46:49], v[216:219], v[90:93]
	v_mfma_f32_16x16x32_bf16 v[134:137], v[146:149], v[172:175], v[134:137]
	v_mfma_f32_16x16x32_bf16 v[130:133], v[154:157], v[172:175], v[130:133]
	v_mfma_f32_16x16x32_bf16 v[118:121], v[146:149], v[180:183], v[118:121]
	v_mfma_f32_16x16x32_bf16 v[114:117], v[154:157], v[180:183], v[114:117]
	v_mfma_f32_16x16x32_bf16 v[102:105], v[146:149], v[204:207], v[102:105]
	v_mfma_f32_16x16x32_bf16 v[98:101], v[154:157], v[204:207], v[98:101]
	v_mfma_f32_16x16x32_bf16 v[86:89], v[146:149], v[212:215], v[86:89]
	v_mfma_f32_16x16x32_bf16 v[82:85], v[154:157], v[212:215], v[82:85]
	v_mfma_f32_16x16x32_bf16 v[134:137], v[150:153], v[176:179], v[134:137]
	v_mfma_f32_16x16x32_bf16 v[130:133], v[158:161], v[176:179], v[130:133]
	v_mfma_f32_16x16x32_bf16 v[118:121], v[150:153], v[200:203], v[118:121]
	v_mfma_f32_16x16x32_bf16 v[114:117], v[158:161], v[200:203], v[114:117]
	v_mfma_f32_16x16x32_bf16 v[102:105], v[150:153], v[208:211], v[102:105]
	v_mfma_f32_16x16x32_bf16 v[98:101], v[158:161], v[208:211], v[98:101]
	v_mfma_f32_16x16x32_bf16 v[86:89], v[150:153], v[216:219], v[86:89]
	v_mfma_f32_16x16x32_bf16 v[82:85], v[158:161], v[216:219], v[82:85]
	s_barrier
	s_add_i32 s65, s65, s54
	v_lshl_add_u64 v[184:185], s[44:45], 0, v[0:1]
	s_mov_b32 m0, s65
	ds_read_b128 v[172:175], v199 offset:16384
	ds_read_b128 v[176:179], v199 offset:17408
	ds_read_b128 v[180:183], v199 offset:18432
	ds_read_b128 v[200:203], v199 offset:19456
	ds_read_b128 v[204:207], v199 offset:20480
	ds_read_b128 v[208:211], v199 offset:21504
	ds_read_b128 v[212:215], v199 offset:22528
	ds_read_b128 v[216:219], v199 offset:23552
	global_load_lds_dwordx4 v[184:185], off
	s_add_i32 m0, s65, 0x2000
	v_lshl_add_u64 v[194:195], s[44:45], 0, v[162:163]
	s_add_u32 s44, s44, s28
	s_addc_u32 s45, s45, s29
	s_add_i32 s41, s41, s54
	global_load_lds_dwordx4 v[194:195], off
	v_lshl_add_u64 v[228:229], s[44:45], 0, v[0:1]
	s_mov_b32 m0, s41
	v_lshl_add_u64 v[230:231], s[44:45], 0, v[162:163]
	global_load_lds_dwordx4 v[228:229], off
	s_add_i32 m0, s41, 0x2000
	v_lshl_add_u64 v[232:233], s[14:15], 0, v[166:167]
	global_load_lds_dwordx4 v[230:231], off
	s_mov_b32 m0, s55
	v_lshl_add_u64 v[234:235], s[14:15], 0, v[164:165]
	global_load_lds_dwordx4 v[232:233], off
	s_mov_b32 m0, s56
	s_nop 0
	global_load_lds_dwordx4 v[234:235], off
	s_waitcnt vmcnt(8)
	s_waitcnt lgkmcnt(0)
	s_barrier
; #define PG8_STAGE(bufoff, gbase, voff) do { _Pragma("unroll") for (int _i = 0; _i < 2; ++_i) \
;         __builtin_amdgcn_global_load_lds((const unsigned*)((const char*)(gbase) + (voff)[_i]), (PG8_LAS unsigned*)(lds + (bufoff) + ldsw + _i * 8192), 16, 0, 0); } while (0)
; #define PG8_LDA(dst, b, h) do { _Pragma("unroll") for (int m = 0; m < 4; ++m) _Pragma("unroll") for (int k = 0; k < 2; ++k) dst[m][k] = *(const PG8_LAS bf16x8*)(lds + PG8_SA(b, h) + aoff + m * 2048 + k * 1024); } while (0)
; #define PG8_LDB(dst, b, h) do { _Pragma("unroll") for (int n = 0; n < 2; ++n) _Pragma("unroll") for (int k = 0; k < 2; ++k) dst[n][k] = *(const PG8_LAS bf16x8*)(lds + PG8_SB(b, h) + boff + n * 2048 + k * 1024); } while (0)
; #define PG8_MMA(ai, bj, At, Bt) do { __builtin_amdgcn_s_setprio(1); _Pragma("unroll") for (int m = 0; m < 4; ++m) _Pragma("unroll") for (int n = 0; n < 2; ++n) _Pragma("unroll") for (int k = 0; k < 2; ++k) \
;         acc[ai][bj][m][n] = __builtin_amdgcn_mfma_f32_16x16x32_bf16(Bt[n][k], At[m][k], acc[ai][bj][m][n], 0, 0, 0); __builtin_amdgcn_s_setprio(0); } while (0)
; #define PG8_WAIT_V(n) asm volatile("s_waitcnt vmcnt(" #n ")" ::: "memory")
; #define PG8_WAIT_L(n) asm volatile("s_waitcnt lgkmcnt(" #n ")" ::: "memory")
; #define PG8_BAR __builtin_amdgcn_s_barrier()
; #define PG8_SCHED __builtin_amdgcn_sched_barrier(0)
; template <class Epi, class Sched, bool ALIGN_EPI = false, bool SP2 = false>
; __device__ __forceinline__ void gemm_phase(PG8_LAS unsigned char* lds, const Gemm g, const Sched& S, const Epi& E, const int wv) {
;     ...
;             PG8_WAIT_V(8); PG8_WAIT_L(0); PG8_BAR; PG8_MMA(1, 0, At, B0); PG8_MMA(1, 1, At, B1); PG8_BAR; PG8_SCHED;
;             PG8_LDB(B0, 1, 0); PG8_LDB(B1, 1, 1); PG8_SCHED; PG8_LDA(At, 1, 0); PG8_STAGE(PG8_SA(0, 1), a2 + hstepA, voffA);
;             PG8_WAIT_V(8); PG8_WAIT_L(0); PG8_BAR; PG8_MMA(0, 0, At, B0); PG8_MMA(0, 1, At, B1); PG8_BAR; PG8_SCHED;
	s_waitcnt lgkmcnt(0)
	v_mfma_f32_16x16x32_bf16 v[78:81], v[26:29], v[172:175], v[78:81]
	v_mfma_f32_16x16x32_bf16 v[74:77], v[42:45], v[172:175], v[74:77]
	v_mfma_f32_16x16x32_bf16 v[62:65], v[26:29], v[180:183], v[62:65]
	v_mfma_f32_16x16x32_bf16 v[58:61], v[42:45], v[180:183], v[58:61]
	v_mfma_f32_16x16x32_bf16 v[38:41], v[26:29], v[204:207], v[38:41]
	v_mfma_f32_16x16x32_bf16 v[34:37], v[42:45], v[204:207], v[34:37]
	v_mfma_f32_16x16x32_bf16 v[14:17], v[26:29], v[212:215], v[14:17]
	v_mfma_f32_16x16x32_bf16 v[10:13], v[42:45], v[212:215], v[10:13]
	v_mfma_f32_16x16x32_bf16 v[78:81], v[30:33], v[176:179], v[78:81]
	v_mfma_f32_16x16x32_bf16 v[74:77], v[46:49], v[176:179], v[74:77]
	v_mfma_f32_16x16x32_bf16 v[62:65], v[30:33], v[200:203], v[62:65]
	v_mfma_f32_16x16x32_bf16 v[58:61], v[46:49], v[200:203], v[58:61]
	v_mfma_f32_16x16x32_bf16 v[38:41], v[30:33], v[208:211], v[38:41]
	v_mfma_f32_16x16x32_bf16 v[34:37], v[46:49], v[208:211], v[34:37]
	v_mfma_f32_16x16x32_bf16 v[14:17], v[30:33], v[216:219], v[14:17]
	v_mfma_f32_16x16x32_bf16 v[10:13], v[46:49], v[216:219], v[10:13]
	v_mfma_f32_16x16x32_bf16 v[22:25], v[146:149], v[204:207], v[22:25]
	v_mfma_f32_16x16x32_bf16 v[18:21], v[154:157], v[204:207], v[18:21]
	v_mfma_f32_16x16x32_bf16 v[6:9], v[146:149], v[212:215], v[6:9]
	v_mfma_f32_16x16x32_bf16 v[2:5], v[154:157], v[212:215], v[2:5]
	v_mfma_f32_16x16x32_bf16 v[26:29], v[146:149], v[172:175], v[70:73]
	v_mfma_f32_16x16x32_bf16 v[30:33], v[154:157], v[172:175], v[66:69]
	v_mfma_f32_16x16x32_bf16 v[42:45], v[146:149], v[180:183], v[54:57]
	v_mfma_f32_16x16x32_bf16 v[46:49], v[154:157], v[180:183], v[50:53]
	v_mfma_f32_16x16x32_bf16 v[22:25], v[150:153], v[208:211], v[22:25]
	v_mfma_f32_16x16x32_bf16 v[18:21], v[158:161], v[208:211], v[18:21]
	v_mfma_f32_16x16x32_bf16 v[6:9], v[150:153], v[216:219], v[6:9]
	v_mfma_f32_16x16x32_bf16 v[2:5], v[158:161], v[216:219], v[2:5]
	v_mfma_f32_16x16x32_bf16 v[26:29], v[150:153], v[176:179], v[26:29]
	v_mfma_f32_16x16x32_bf16 v[30:33], v[158:161], v[176:179], v[30:33]
	v_mfma_f32_16x16x32_bf16 v[42:45], v[150:153], v[200:203], v[42:45]
	v_mfma_f32_16x16x32_bf16 v[46:49], v[158:161], v[200:203], v[46:49]
	s_barrier
	s_add_i32 s41, 0, 0x18000
	s_add_i32 s44, 0, 0x1c000
	v_add_u32_e32 v70, s41, v197
	v_add_u32_e32 v158, s44, v197
	ds_read_b128 v[50:53], v70
	ds_read_b128 v[54:57], v70 offset:1024
	ds_read_b128 v[66:69], v70 offset:2048
	ds_read_b128 v[70:73], v70 offset:3072
	ds_read_b128 v[146:149], v158
	ds_read_b128 v[150:153], v158 offset:1024
	ds_read_b128 v[154:157], v158 offset:2048
	ds_read_b128 v[158:161], v158 offset:3072
	s_add_u32 s14, s14, 0x80000
	s_addc_u32 s15, s15, 0
	s_mov_b32 m0, s57
	v_lshl_add_u64 v[236:237], s[14:15], 0, v[166:167]
	ds_read_b128 v[172:175], v199 offset:32768
	ds_read_b128 v[176:179], v199 offset:33792
	ds_read_b128 v[180:183], v199 offset:34816
	ds_read_b128 v[200:203], v199 offset:35840
	ds_read_b128 v[204:207], v199 offset:36864
	ds_read_b128 v[208:211], v199 offset:37888
	ds_read_b128 v[212:215], v199 offset:38912
	ds_read_b128 v[216:219], v199 offset:39936
	global_load_lds_dwordx4 v[236:237], off
	v_lshl_add_u64 v[236:237], s[14:15], 0, v[164:165]
	s_mov_b32 m0, s58
	s_nop 0
	global_load_lds_dwordx4 v[236:237], off
	s_waitcnt vmcnt(8)
	s_waitcnt lgkmcnt(0)
	s_barrier
	s_waitcnt lgkmcnt(0)
	v_mfma_f32_16x16x32_bf16 v[138:141], v[50:53], v[172:175], v[138:141]
	v_mfma_f32_16x16x32_bf16 v[142:145], v[66:69], v[172:175], v[142:145]
	v_mfma_f32_16x16x32_bf16 v[126:129], v[50:53], v[180:183], v[126:129]
	v_mfma_f32_16x16x32_bf16 v[122:125], v[66:69], v[180:183], v[122:125]
	v_mfma_f32_16x16x32_bf16 v[110:113], v[50:53], v[204:207], v[110:113]
	v_mfma_f32_16x16x32_bf16 v[106:109], v[66:69], v[204:207], v[106:109]
	v_mfma_f32_16x16x32_bf16 v[94:97], v[50:53], v[212:215], v[94:97]
	v_mfma_f32_16x16x32_bf16 v[90:93], v[66:69], v[212:215], v[90:93]
	v_mfma_f32_16x16x32_bf16 v[138:141], v[54:57], v[176:179], v[138:141]
	v_mfma_f32_16x16x32_bf16 v[142:145], v[70:73], v[176:179], v[142:145]
	v_mfma_f32_16x16x32_bf16 v[126:129], v[54:57], v[200:203], v[126:129]
	v_mfma_f32_16x16x32_bf16 v[122:125], v[70:73], v[200:203], v[122:125]
	v_mfma_f32_16x16x32_bf16 v[110:113], v[54:57], v[208:211], v[110:113]
	v_mfma_f32_16x16x32_bf16 v[106:109], v[70:73], v[208:211], v[106:109]
	v_mfma_f32_16x16x32_bf16 v[94:97], v[54:57], v[216:219], v[94:97]
	v_mfma_f32_16x16x32_bf16 v[90:93], v[70:73], v[216:219], v[90:93]
	v_mfma_f32_16x16x32_bf16 v[134:137], v[146:149], v[172:175], v[134:137]
	v_mfma_f32_16x16x32_bf16 v[130:133], v[154:157], v[172:175], v[130:133]
	v_mfma_f32_16x16x32_bf16 v[118:121], v[146:149], v[180:183], v[118:121]
	v_mfma_f32_16x16x32_bf16 v[114:117], v[154:157], v[180:183], v[114:117]
	v_mfma_f32_16x16x32_bf16 v[102:105], v[146:149], v[204:207], v[102:105]
	v_mfma_f32_16x16x32_bf16 v[98:101], v[154:157], v[204:207], v[98:101]
	v_mfma_f32_16x16x32_bf16 v[86:89], v[146:149], v[212:215], v[86:89]
	v_mfma_f32_16x16x32_bf16 v[82:85], v[154:157], v[212:215], v[82:85]
	v_mfma_f32_16x16x32_bf16 v[134:137], v[150:153], v[176:179], v[134:137]
	v_mfma_f32_16x16x32_bf16 v[130:133], v[158:161], v[176:179], v[130:133]
	v_mfma_f32_16x16x32_bf16 v[118:121], v[150:153], v[200:203], v[118:121]
	v_mfma_f32_16x16x32_bf16 v[114:117], v[158:161], v[200:203], v[114:117]
	v_mfma_f32_16x16x32_bf16 v[102:105], v[150:153], v[208:211], v[102:105]
	v_mfma_f32_16x16x32_bf16 v[98:101], v[158:161], v[208:211], v[98:101]
	v_mfma_f32_16x16x32_bf16 v[86:89], v[150:153], v[216:219], v[86:89]
	v_mfma_f32_16x16x32_bf16 v[82:85], v[158:161], v[216:219], v[82:85]
	s_barrier
; #define PG8_STAGE(bufoff, gbase, voff) do { _Pragma("unroll") for (int _i = 0; _i < 2; ++_i) \
;         __builtin_amdgcn_global_load_lds((const unsigned*)((const char*)(gbase) + (voff)[_i]), (PG8_LAS unsigned*)(lds + (bufoff) + ldsw + _i * 8192), 16, 0, 0); } while (0)
; #define PG8_LDA(dst, b, h) do { _Pragma("unroll") for (int m = 0; m < 4; ++m) _Pragma("unroll") for (int k = 0; k < 2; ++k) dst[m][k] = *(const PG8_LAS bf16x8*)(lds + PG8_SA(b, h) + aoff + m * 2048 + k * 1024); } while (0)
; #define PG8_MMA(ai, bj, At, Bt) do { __builtin_amdgcn_s_setprio(1); _Pragma("unroll") for (int m = 0; m < 4; ++m) _Pragma("unroll") for (int n = 0; n < 2; ++n) _Pragma("unroll") for (int k = 0; k < 2; ++k) \
;         acc[ai][bj][m][n] = __builtin_amdgcn_mfma_f32_16x16x32_bf16(Bt[n][k], At[m][k], acc[ai][bj][m][n], 0, 0, 0); __builtin_amdgcn_s_setprio(0); } while (0)
; #define PG8_WAIT_V(n) asm volatile("s_waitcnt vmcnt(" #n ")" ::: "memory")
; #define PG8_WAIT_L(n) asm volatile("s_waitcnt lgkmcnt(" #n ")" ::: "memory")
; #define PG8_BAR __builtin_amdgcn_s_barrier()
; #define PG8_SCHED __builtin_amdgcn_sched_barrier(0)
; template <class Epi, class Sched, bool ALIGN_EPI = false, bool SP2 = false>
; __device__ __forceinline__ void gemm_phase(PG8_LAS unsigned char* lds, const Gemm g, const Sched& S, const Epi& E, const int wv) {
;     ...
;         for (int t = 0; t < nt; t += 2) {
;             const bool last = (t == nt - 2);
;             const char* a1 = cA + (size_t)(t + 1) * kstep;
;             const char* a2 = last ? nA : cA + (size_t)(t + 2) * kstep; const char* b2 = last ? nB : cB + (size_t)(t + 2) * kstep;
;             const char* a3 = a2 + kstep; const char* b3 = b2 + kstep;
;     ...
;             PG8_LDA(At, 1, 1); PG8_STAGE(PG8_SB(1, 0), b3, voffB); PG8_STAGE(PG8_SB(1, 1), b3 + hstepB, voffB); PG8_STAGE(PG8_SA(1, 0), a3, voffA);
;             PG8_WAIT_V(8); PG8_WAIT_L(0); PG8_BAR; PG8_MMA(1, 0, At, B0); PG8_MMA(1, 1, At, B1); PG8_BAR; PG8_SCHED;
	s_add_i32 s14, s41, s54
	v_lshl_add_u64 v[184:185], v[184:185], 0, s[4:5]
	s_mov_b32 m0, s14
	ds_read_b128 v[172:175], v199 offset:49152
	ds_read_b128 v[176:179], v199 offset:50176
	ds_read_b128 v[180:183], v199 offset:51200
	ds_read_b128 v[200:203], v199 offset:52224
	ds_read_b128 v[204:207], v199 offset:53248
	ds_read_b128 v[208:211], v199 offset:54272
	ds_read_b128 v[212:215], v199 offset:55296
	ds_read_b128 v[216:219], v199 offset:56320
	global_load_lds_dwordx4 v[184:185], off
	v_lshl_add_u64 v[184:185], v[194:195], 0, s[4:5]
	s_add_i32 m0, s14, 0x2000
	s_add_i32 s14, s44, s54
	global_load_lds_dwordx4 v[184:185], off
	v_lshl_add_u64 v[184:185], v[228:229], 0, s[4:5]
	s_mov_b32 m0, s14
	s_nop 0
	global_load_lds_dwordx4 v[184:185], off
	v_lshl_add_u64 v[184:185], v[230:231], 0, s[4:5]
	s_add_i32 m0, s14, 0x2000
	s_nop 0
	global_load_lds_dwordx4 v[184:185], off
	v_lshl_add_u64 v[184:185], v[232:233], 0, s[4:5]
	s_mov_b32 m0, s60
	s_nop 0
	global_load_lds_dwordx4 v[184:185], off
	v_lshl_add_u64 v[184:185], v[234:235], 0, s[4:5]
	s_mov_b32 m0, s61
	s_nop 0
	global_load_lds_dwordx4 v[184:185], off
	s_waitcnt vmcnt(8)
	s_waitcnt lgkmcnt(0)
	s_barrier
	s_waitcnt lgkmcnt(0)
	v_mfma_f32_16x16x32_bf16 v[78:81], v[50:53], v[172:175], v[78:81]
	v_mfma_f32_16x16x32_bf16 v[74:77], v[66:69], v[172:175], v[74:77]
	v_mfma_f32_16x16x32_bf16 v[62:65], v[50:53], v[180:183], v[62:65]
	v_mfma_f32_16x16x32_bf16 v[58:61], v[66:69], v[180:183], v[58:61]
	v_mfma_f32_16x16x32_bf16 v[38:41], v[50:53], v[204:207], v[38:41]
	v_mfma_f32_16x16x32_bf16 v[34:37], v[66:69], v[204:207], v[34:37]
	v_mfma_f32_16x16x32_bf16 v[14:17], v[50:53], v[212:215], v[14:17]
	v_mfma_f32_16x16x32_bf16 v[10:13], v[66:69], v[212:215], v[10:13]
	v_mfma_f32_16x16x32_bf16 v[78:81], v[54:57], v[176:179], v[78:81]
	v_mfma_f32_16x16x32_bf16 v[74:77], v[70:73], v[176:179], v[74:77]
	v_mfma_f32_16x16x32_bf16 v[62:65], v[54:57], v[200:203], v[62:65]
	v_mfma_f32_16x16x32_bf16 v[58:61], v[70:73], v[200:203], v[58:61]
	v_mfma_f32_16x16x32_bf16 v[38:41], v[54:57], v[208:211], v[38:41]
	v_mfma_f32_16x16x32_bf16 v[34:37], v[70:73], v[208:211], v[34:37]
	v_mfma_f32_16x16x32_bf16 v[14:17], v[54:57], v[216:219], v[14:17]
	v_mfma_f32_16x16x32_bf16 v[10:13], v[70:73], v[216:219], v[10:13]
	v_mfma_f32_16x16x32_bf16 v[26:29], v[146:149], v[172:175], v[26:29]
	v_mfma_f32_16x16x32_bf16 v[70:73], v[150:153], v[176:179], v[26:29]
	v_mfma_f32_16x16x32_bf16 v[26:29], v[154:157], v[172:175], v[30:33]
	v_mfma_f32_16x16x32_bf16 v[66:69], v[158:161], v[176:179], v[26:29]
	v_mfma_f32_16x16x32_bf16 v[26:29], v[146:149], v[180:183], v[42:45]
	v_mfma_f32_16x16x32_bf16 v[54:57], v[150:153], v[200:203], v[26:29]
	v_mfma_f32_16x16x32_bf16 v[26:29], v[154:157], v[180:183], v[46:49]
	v_mfma_f32_16x16x32_bf16 v[22:25], v[146:149], v[204:207], v[22:25]
	v_mfma_f32_16x16x32_bf16 v[18:21], v[154:157], v[204:207], v[18:21]
	v_mfma_f32_16x16x32_bf16 v[6:9], v[146:149], v[212:215], v[6:9]
	v_mfma_f32_16x16x32_bf16 v[2:5], v[154:157], v[212:215], v[2:5]
	v_mfma_f32_16x16x32_bf16 v[50:53], v[158:161], v[200:203], v[26:29]
	v_mfma_f32_16x16x32_bf16 v[22:25], v[150:153], v[208:211], v[22:25]
	v_mfma_f32_16x16x32_bf16 v[18:21], v[158:161], v[208:211], v[18:21]
	v_mfma_f32_16x16x32_bf16 v[6:9], v[150:153], v[216:219], v[6:9]
	v_mfma_f32_16x16x32_bf16 v[2:5], v[158:161], v[216:219], v[2:5]
	s_barrier
	s_add_u32 s12, s12, 0x100
	s_addc_u32 s13, s13, 0
	s_add_u32 s11, s11, 0x100
	s_addc_u32 s17, s17, 0
	s_cmp_ge_i32 s40, s59
	s_mov_b32 s14, s40
	s_cbranch_scc0 .LBB0_336

;     __host__ __device__ bool next(int i, Unit& u) const { const int P = (i >> 1) * G + c; if (P >= 256) return false; u.pm = P >> 3; u.pn = (P & 7) + 8 * (i & 1); return true; }
; #define PG8_STAGE(bufoff, gbase, voff) do { _Pragma("unroll") for (int _i = 0; _i < 2; ++_i) \
;         __builtin_amdgcn_global_load_lds((const unsigned*)((const char*)(gbase) + (voff)[_i]), (PG8_LAS unsigned*)(lds + (bufoff) + ldsw + _i * 8192), 16, 0, 0); } while (0)
; #define PG8_LDA(dst, b, h) do { _Pragma("unroll") for (int m = 0; m < 4; ++m) _Pragma("unroll") for (int k = 0; k < 2; ++k) dst[m][k] = *(const PG8_LAS bf16x8*)(lds + PG8_SA(b, h) + aoff + m * 2048 + k * 1024); } while (0)
; #define PG8_LDB(dst, b, h) do { _Pragma("unroll") for (int n = 0; n < 2; ++n) _Pragma("unroll") for (int k = 0; k < 2; ++k) dst[n][k] = *(const PG8_LAS bf16x8*)(lds + PG8_SB(b, h) + boff + n * 2048 + k * 1024); } while (0)
; #define PG8_BAR __builtin_amdgcn_s_barrier()
; template <class Epi, class Sched, bool ALIGN_EPI = false, bool SP2 = false>
; __device__ __forceinline__ void gemm_phase(PG8_LAS unsigned char* lds, const Gemm g, const Sched& S, const Epi& E, const int wv) {
;     ...
;         const bool has_next = S.next(ui + 1, nxt);
;         const char* nA = has_next ? (const char*)g.A + (size_t)nxt.pm * tstepA + (g.amod ? (size_t)(nxt.pn % g.amod) * K * 2 : (size_t)0) : cA; const char* nB = has_next ? (const char*)g.Bt + (size_t)nxt.pn * tstepB : cB;
;         for (int t = 0; t < nt; t += 2) {
;             const bool last = (t == nt - 2);
;             const char* a1 = cA + (size_t)(t + 1) * kstep;
;             const char* a2 = last ? nA : cA + (size_t)(t + 2) * kstep; const char* b2 = last ? nB : cB + (size_t)(t + 2) * kstep;
;             const char* a3 = a2 + kstep; const char* b3 = b2 + kstep;
;             if (last && has_next) S.a_ready(nxt);
;             if constexpr (SP2) {
;             PG8_LDB(B0, 0, 0); PG8_LDB(B1, 0, 1); PG8_SCHED; PG8_LDA(At, 0, 0); PG8_STAGE(PG8_SA(1, 1), a1 + hstepA, voffA);
;             PG8_WAIT_V(8); PG8_WAIT_L(0); PG8_BAR; PG8_MMA(0, 0, At, B0); PG8_MMA(0, 1, At, B1); PG8_BAR; PG8_SCHED;
;             PG8_LDA(At, 0, 1); PG8_STAGE(PG8_SB(0, 0), b2, voffB); PG8_STAGE(PG8_SB(0, 1), b2 + hstepB, voffB); PG8_STAGE(PG8_SA(0, 0), a2, voffA);
;             PG8_WAIT_V(8); PG8_WAIT_L(0); PG8_BAR; PG8_MMA(1, 0, At, B0); PG8_MMA(1, 1, At, B1); PG8_BAR; PG8_SCHED;
.LBB0_699:
	s_add_i32 s72, s54, 2
	s_add_u32 s73, s44, 0xfff80080
	s_addc_u32 s55, s45, -1
	s_add_i32 s76, 0, 0x10000
	s_cmp_eq_u32 s66, s54
	s_cselect_b32 s55, s31, s55
	s_cselect_b32 s54, s71, s73
	v_add_u32_e32 v115, s76, v230
	s_cselect_b32 s75, s13, s57
	s_cselect_b32 s74, s12, s56
	s_add_i32 s73, 0, 0x14000
	ds_read_b128 v[126:129], v115
	ds_read_b128 v[138:141], v115 offset:1024
	ds_read_b128 v[142:145], v115 offset:2048
	ds_read_b128 v[146:149], v115 offset:3072
	v_add_u32_e32 v115, s73, v230
	ds_read_b128 v[150:153], v115
	ds_read_b128 v[154:157], v115 offset:1024
	ds_read_b128 v[158:161], v115 offset:2048
	ds_read_b128 v[162:165], v115 offset:3072
	v_lshl_add_u64 v[116:117], s[44:45], 0, v[200:201]
	s_add_i32 m0, s59, 0xc000
	ds_read_b128 v[166:169], v235
	ds_read_b128 v[170:173], v235 offset:1024
	ds_read_b128 v[174:177], v235 offset:2048
	ds_read_b128 v[178:181], v235 offset:3072
	ds_read_b128 v[182:185], v235 offset:4096
	ds_read_b128 v[204:207], v235 offset:5120
	ds_read_b128 v[208:211], v235 offset:6144
	ds_read_b128 v[212:215], v235 offset:7168
	global_load_lds_dwordx4 v[116:117], off
	v_lshl_add_u64 v[116:117], s[44:45], 0, v[202:203]
	s_add_i32 m0, s59, 0xe000
	s_nop 0
	global_load_lds_dwordx4 v[116:117], off
	s_waitcnt vmcnt(8)
	s_waitcnt lgkmcnt(0)
	s_barrier
	s_waitcnt lgkmcnt(0)
	v_mfma_f32_16x16x32_bf16 v[134:137], v[126:129], v[166:169], v[134:137]
	v_mfma_f32_16x16x32_bf16 v[130:133], v[142:145], v[166:169], v[130:133]
	v_mfma_f32_16x16x32_bf16 v[110:113], v[126:129], v[174:177], v[110:113]
	v_mfma_f32_16x16x32_bf16 v[106:109], v[142:145], v[174:177], v[106:109]
	v_mfma_f32_16x16x32_bf16 v[94:97], v[126:129], v[182:185], v[94:97]
	v_mfma_f32_16x16x32_bf16 v[90:93], v[142:145], v[182:185], v[90:93]
	v_mfma_f32_16x16x32_bf16 v[78:81], v[126:129], v[208:211], v[78:81]
	v_mfma_f32_16x16x32_bf16 v[74:77], v[142:145], v[208:211], v[74:77]
	v_mfma_f32_16x16x32_bf16 v[134:137], v[138:141], v[170:173], v[134:137]
	v_mfma_f32_16x16x32_bf16 v[130:133], v[146:149], v[170:173], v[130:133]
	v_mfma_f32_16x16x32_bf16 v[110:113], v[138:141], v[178:181], v[110:113]
	v_mfma_f32_16x16x32_bf16 v[106:109], v[146:149], v[178:181], v[106:109]
	v_mfma_f32_16x16x32_bf16 v[94:97], v[138:141], v[204:207], v[94:97]
	v_mfma_f32_16x16x32_bf16 v[90:93], v[146:149], v[204:207], v[90:93]
	v_mfma_f32_16x16x32_bf16 v[78:81], v[138:141], v[212:215], v[78:81]
	v_mfma_f32_16x16x32_bf16 v[74:77], v[146:149], v[212:215], v[74:77]
	v_mfma_f32_16x16x32_bf16 v[122:125], v[150:153], v[166:169], v[122:125]
	v_mfma_f32_16x16x32_bf16 v[116:119], v[158:161], v[166:169], v[118:121]
	v_mfma_f32_16x16x32_bf16 v[102:105], v[150:153], v[174:177], v[102:105]
	v_mfma_f32_16x16x32_bf16 v[98:101], v[158:161], v[174:177], v[98:101]
	v_mfma_f32_16x16x32_bf16 v[86:89], v[150:153], v[182:185], v[86:89]
	v_mfma_f32_16x16x32_bf16 v[82:85], v[158:161], v[182:185], v[82:85]
	v_mfma_f32_16x16x32_bf16 v[70:73], v[150:153], v[208:211], v[70:73]
	v_mfma_f32_16x16x32_bf16 v[66:69], v[158:161], v[208:211], v[66:69]
	v_mfma_f32_16x16x32_bf16 v[122:125], v[154:157], v[170:173], v[122:125]
	v_mfma_f32_16x16x32_bf16 v[116:119], v[162:165], v[170:173], v[116:119]
	v_mfma_f32_16x16x32_bf16 v[102:105], v[154:157], v[178:181], v[102:105]
	v_mfma_f32_16x16x32_bf16 v[98:101], v[162:165], v[178:181], v[98:101]
	v_mfma_f32_16x16x32_bf16 v[86:89], v[154:157], v[204:207], v[86:89]
	v_mfma_f32_16x16x32_bf16 v[82:85], v[162:165], v[204:207], v[82:85]
	v_mfma_f32_16x16x32_bf16 v[70:73], v[154:157], v[212:215], v[70:73]
	v_mfma_f32_16x16x32_bf16 v[66:69], v[162:165], v[212:215], v[66:69]
	s_barrier
	s_add_i32 s76, s76, s53
	v_lshl_add_u64 v[216:217], s[74:75], 0, v[0:1]
	s_mov_b32 m0, s76
	ds_read_b128 v[166:169], v235 offset:16384
	ds_read_b128 v[170:173], v235 offset:17408
	ds_read_b128 v[174:177], v235 offset:18432
	ds_read_b128 v[178:181], v235 offset:19456
	ds_read_b128 v[182:185], v235 offset:20480
	ds_read_b128 v[204:207], v235 offset:21504
	ds_read_b128 v[208:211], v235 offset:22528
	ds_read_b128 v[212:215], v235 offset:23552
	global_load_lds_dwordx4 v[216:217], off
	s_add_i32 m0, s76, 0x2000
	v_lshl_add_u64 v[218:219], s[74:75], 0, v[198:199]
	s_add_u32 s74, s74, s34
	s_addc_u32 s75, s75, s35
	s_add_i32 s73, s73, s53
	global_load_lds_dwordx4 v[218:219], off
	v_lshl_add_u64 v[236:237], s[74:75], 0, v[0:1]
	s_mov_b32 m0, s73
	v_lshl_add_u64 v[238:239], s[74:75], 0, v[198:199]
	global_load_lds_dwordx4 v[236:237], off
	s_add_i32 m0, s73, 0x2000
	v_lshl_add_u64 v[240:241], s[54:55], 0, v[194:195]
	global_load_lds_dwordx4 v[238:239], off
	s_mov_b32 m0, s59
	v_lshl_add_u64 v[242:243], s[54:55], 0, v[196:197]
	global_load_lds_dwordx4 v[240:241], off
	s_mov_b32 m0, s60
	s_nop 0
	global_load_lds_dwordx4 v[242:243], off
	s_waitcnt vmcnt(8)
	s_waitcnt lgkmcnt(0)
	s_barrier
; #define PG8_STAGE(bufoff, gbase, voff) do { _Pragma("unroll") for (int _i = 0; _i < 2; ++_i) \
;         __builtin_amdgcn_global_load_lds((const unsigned*)((const char*)(gbase) + (voff)[_i]), (PG8_LAS unsigned*)(lds + (bufoff) + ldsw + _i * 8192), 16, 0, 0); } while (0)
; #define PG8_LDA(dst, b, h) do { _Pragma("unroll") for (int m = 0; m < 4; ++m) _Pragma("unroll") for (int k = 0; k < 2; ++k) dst[m][k] = *(const PG8_LAS bf16x8*)(lds + PG8_SA(b, h) + aoff + m * 2048 + k * 1024); } while (0)
; #define PG8_LDB(dst, b, h) do { _Pragma("unroll") for (int n = 0; n < 2; ++n) _Pragma("unroll") for (int k = 0; k < 2; ++k) dst[n][k] = *(const PG8_LAS bf16x8*)(lds + PG8_SB(b, h) + boff + n * 2048 + k * 1024); } while (0)
; #define PG8_MMA(ai, bj, At, Bt) do { __builtin_amdgcn_s_setprio(1); _Pragma("unroll") for (int m = 0; m < 4; ++m) _Pragma("unroll") for (int n = 0; n < 2; ++n) _Pragma("unroll") for (int k = 0; k < 2; ++k) \
;         acc[ai][bj][m][n] = __builtin_amdgcn_mfma_f32_16x16x32_bf16(Bt[n][k], At[m][k], acc[ai][bj][m][n], 0, 0, 0); __builtin_amdgcn_s_setprio(0); } while (0)
; #define PG8_WAIT_V(n) asm volatile("s_waitcnt vmcnt(" #n ")" ::: "memory")
; #define PG8_WAIT_L(n) asm volatile("s_waitcnt lgkmcnt(" #n ")" ::: "memory")
; #define PG8_BAR __builtin_amdgcn_s_barrier()
; #define PG8_SCHED __builtin_amdgcn_sched_barrier(0)
; template <class Epi, class Sched, bool ALIGN_EPI = false, bool SP2 = false>
; __device__ __forceinline__ void gemm_phase(PG8_LAS unsigned char* lds, const Gemm g, const Sched& S, const Epi& E, const int wv) {
;     ...
;             PG8_WAIT_V(8); PG8_WAIT_L(0); PG8_BAR; PG8_MMA(1, 0, At, B0); PG8_MMA(1, 1, At, B1); PG8_BAR; PG8_SCHED;
;             PG8_LDB(B0, 1, 0); PG8_LDB(B1, 1, 1); PG8_SCHED; PG8_LDA(At, 1, 0); PG8_STAGE(PG8_SA(0, 1), a2 + hstepA, voffA);
;             PG8_WAIT_V(8); PG8_WAIT_L(0); PG8_BAR; PG8_MMA(0, 0, At, B0); PG8_MMA(0, 1, At, B1); PG8_BAR; PG8_SCHED;
	s_waitcnt lgkmcnt(0)
	v_mfma_f32_16x16x32_bf16 v[62:65], v[126:129], v[166:169], v[62:65]
	v_mfma_f32_16x16x32_bf16 v[58:61], v[142:145], v[166:169], v[58:61]
	v_mfma_f32_16x16x32_bf16 v[46:49], v[126:129], v[174:177], v[46:49]
	v_mfma_f32_16x16x32_bf16 v[42:45], v[142:145], v[174:177], v[42:45]
	v_mfma_f32_16x16x32_bf16 v[30:33], v[126:129], v[182:185], v[30:33]
	v_mfma_f32_16x16x32_bf16 v[26:29], v[142:145], v[182:185], v[26:29]
	v_mfma_f32_16x16x32_bf16 v[14:17], v[126:129], v[208:211], v[14:17]
	v_mfma_f32_16x16x32_bf16 v[10:13], v[142:145], v[208:211], v[10:13]
	v_mfma_f32_16x16x32_bf16 v[62:65], v[138:141], v[170:173], v[62:65]
	v_mfma_f32_16x16x32_bf16 v[58:61], v[146:149], v[170:173], v[58:61]
	v_mfma_f32_16x16x32_bf16 v[46:49], v[138:141], v[178:181], v[46:49]
	v_mfma_f32_16x16x32_bf16 v[42:45], v[146:149], v[178:181], v[42:45]
	v_mfma_f32_16x16x32_bf16 v[30:33], v[138:141], v[204:207], v[30:33]
	v_mfma_f32_16x16x32_bf16 v[26:29], v[146:149], v[204:207], v[26:29]
	v_mfma_f32_16x16x32_bf16 v[14:17], v[138:141], v[212:215], v[14:17]
	v_mfma_f32_16x16x32_bf16 v[10:13], v[146:149], v[212:215], v[10:13]
	v_mfma_f32_16x16x32_bf16 v[54:57], v[150:153], v[166:169], v[54:57]
	v_mfma_f32_16x16x32_bf16 v[50:53], v[158:161], v[166:169], v[50:53]
	v_mfma_f32_16x16x32_bf16 v[38:41], v[150:153], v[174:177], v[38:41]
	v_mfma_f32_16x16x32_bf16 v[34:37], v[158:161], v[174:177], v[34:37]
	v_mfma_f32_16x16x32_bf16 v[22:25], v[150:153], v[182:185], v[22:25]
	v_mfma_f32_16x16x32_bf16 v[18:21], v[158:161], v[182:185], v[18:21]
	v_mfma_f32_16x16x32_bf16 v[6:9], v[150:153], v[208:211], v[6:9]
	v_mfma_f32_16x16x32_bf16 v[2:5], v[158:161], v[208:211], v[2:5]
	v_mfma_f32_16x16x32_bf16 v[54:57], v[154:157], v[170:173], v[54:57]
	v_mfma_f32_16x16x32_bf16 v[50:53], v[162:165], v[170:173], v[50:53]
	v_mfma_f32_16x16x32_bf16 v[38:41], v[154:157], v[178:181], v[38:41]
	v_mfma_f32_16x16x32_bf16 v[34:37], v[162:165], v[178:181], v[34:37]
	v_mfma_f32_16x16x32_bf16 v[22:25], v[154:157], v[204:207], v[22:25]
	v_mfma_f32_16x16x32_bf16 v[18:21], v[162:165], v[204:207], v[18:21]
	v_mfma_f32_16x16x32_bf16 v[6:9], v[154:157], v[212:215], v[6:9]
	v_mfma_f32_16x16x32_bf16 v[2:5], v[162:165], v[212:215], v[2:5]
	s_barrier
	s_add_i32 s73, 0, 0x18000
	v_add_u32_e32 v115, s73, v230
	s_add_i32 s74, 0, 0x1c000
	ds_read_b128 v[126:129], v115
	ds_read_b128 v[138:141], v115 offset:1024
	ds_read_b128 v[142:145], v115 offset:2048
	ds_read_b128 v[146:149], v115 offset:3072
	v_add_u32_e32 v115, s74, v230
	ds_read_b128 v[150:153], v115
	ds_read_b128 v[154:157], v115 offset:1024
	ds_read_b128 v[158:161], v115 offset:2048
	ds_read_b128 v[162:165], v115 offset:3072
	s_add_u32 s54, s54, 0x80000
	s_addc_u32 s55, s55, 0
	s_mov_b32 m0, s61
	v_lshl_add_u64 v[120:121], s[54:55], 0, v[194:195]
	ds_read_b128 v[166:169], v235 offset:32768
	ds_read_b128 v[170:173], v235 offset:33792
	ds_read_b128 v[174:177], v235 offset:34816
	ds_read_b128 v[178:181], v235 offset:35840
	ds_read_b128 v[182:185], v235 offset:36864
	ds_read_b128 v[204:207], v235 offset:37888
	ds_read_b128 v[208:211], v235 offset:38912
	ds_read_b128 v[212:215], v235 offset:39936
	global_load_lds_dwordx4 v[120:121], off
	v_lshl_add_u64 v[120:121], s[54:55], 0, v[196:197]
	s_mov_b32 m0, s62
	s_nop 0
	global_load_lds_dwordx4 v[120:121], off
	s_waitcnt vmcnt(8)
	s_waitcnt lgkmcnt(0)
	s_barrier
	s_waitcnt lgkmcnt(0)
	v_mfma_f32_16x16x32_bf16 v[134:137], v[126:129], v[166:169], v[134:137]
	v_mfma_f32_16x16x32_bf16 v[130:133], v[142:145], v[166:169], v[130:133]
	v_mfma_f32_16x16x32_bf16 v[110:113], v[126:129], v[174:177], v[110:113]
	v_mfma_f32_16x16x32_bf16 v[106:109], v[142:145], v[174:177], v[106:109]
	v_mfma_f32_16x16x32_bf16 v[94:97], v[126:129], v[182:185], v[94:97]
	v_mfma_f32_16x16x32_bf16 v[90:93], v[142:145], v[182:185], v[90:93]
	v_mfma_f32_16x16x32_bf16 v[78:81], v[126:129], v[208:211], v[78:81]
	v_mfma_f32_16x16x32_bf16 v[74:77], v[142:145], v[208:211], v[74:77]
	v_mfma_f32_16x16x32_bf16 v[134:137], v[138:141], v[170:173], v[134:137]
	v_mfma_f32_16x16x32_bf16 v[130:133], v[146:149], v[170:173], v[130:133]
	v_mfma_f32_16x16x32_bf16 v[110:113], v[138:141], v[178:181], v[110:113]
	v_mfma_f32_16x16x32_bf16 v[106:109], v[146:149], v[178:181], v[106:109]
	v_mfma_f32_16x16x32_bf16 v[94:97], v[138:141], v[204:207], v[94:97]
	v_mfma_f32_16x16x32_bf16 v[90:93], v[146:149], v[204:207], v[90:93]
	v_mfma_f32_16x16x32_bf16 v[78:81], v[138:141], v[212:215], v[78:81]
	v_mfma_f32_16x16x32_bf16 v[74:77], v[146:149], v[212:215], v[74:77]
	v_mfma_f32_16x16x32_bf16 v[120:123], v[150:153], v[166:169], v[122:125]
	v_mfma_f32_16x16x32_bf16 v[116:119], v[158:161], v[166:169], v[116:119]
	v_mfma_f32_16x16x32_bf16 v[102:105], v[150:153], v[174:177], v[102:105]
	v_mfma_f32_16x16x32_bf16 v[98:101], v[158:161], v[174:177], v[98:101]
	v_mfma_f32_16x16x32_bf16 v[86:89], v[150:153], v[182:185], v[86:89]
	v_mfma_f32_16x16x32_bf16 v[82:85], v[158:161], v[182:185], v[82:85]
	v_mfma_f32_16x16x32_bf16 v[70:73], v[150:153], v[208:211], v[70:73]
	v_mfma_f32_16x16x32_bf16 v[66:69], v[158:161], v[208:211], v[66:69]
	v_mfma_f32_16x16x32_bf16 v[122:125], v[154:157], v[170:173], v[120:123]
	v_mfma_f32_16x16x32_bf16 v[118:121], v[162:165], v[170:173], v[116:119]
	v_mfma_f32_16x16x32_bf16 v[102:105], v[154:157], v[178:181], v[102:105]
	v_mfma_f32_16x16x32_bf16 v[98:101], v[162:165], v[178:181], v[98:101]
	v_mfma_f32_16x16x32_bf16 v[86:89], v[154:157], v[204:207], v[86:89]
	v_mfma_f32_16x16x32_bf16 v[82:85], v[162:165], v[204:207], v[82:85]
	v_mfma_f32_16x16x32_bf16 v[70:73], v[154:157], v[212:215], v[70:73]
	v_mfma_f32_16x16x32_bf16 v[66:69], v[162:165], v[212:215], v[66:69]
	s_barrier
; #define PG8_STAGE(bufoff, gbase, voff) do { _Pragma("unroll") for (int _i = 0; _i < 2; ++_i) \
;         __builtin_amdgcn_global_load_lds((const unsigned*)((const char*)(gbase) + (voff)[_i]), (PG8_LAS unsigned*)(lds + (bufoff) + ldsw + _i * 8192), 16, 0, 0); } while (0)
; #define PG8_LDA(dst, b, h) do { _Pragma("unroll") for (int m = 0; m < 4; ++m) _Pragma("unroll") for (int k = 0; k < 2; ++k) dst[m][k] = *(const PG8_LAS bf16x8*)(lds + PG8_SA(b, h) + aoff + m * 2048 + k * 1024); } while (0)
; #define PG8_MMA(ai, bj, At, Bt) do { __builtin_amdgcn_s_setprio(1); _Pragma("unroll") for (int m = 0; m < 4; ++m) _Pragma("unroll") for (int n = 0; n < 2; ++n) _Pragma("unroll") for (int k = 0; k < 2; ++k) \
;         acc[ai][bj][m][n] = __builtin_amdgcn_mfma_f32_16x16x32_bf16(Bt[n][k], At[m][k], acc[ai][bj][m][n], 0, 0, 0); __builtin_amdgcn_s_setprio(0); } while (0)
; #define PG8_WAIT_V(n) asm volatile("s_waitcnt vmcnt(" #n ")" ::: "memory")
; #define PG8_WAIT_L(n) asm volatile("s_waitcnt lgkmcnt(" #n ")" ::: "memory")
; #define PG8_BAR __builtin_amdgcn_s_barrier()
; #define PG8_SCHED __builtin_amdgcn_sched_barrier(0)
; template <class Epi, class Sched, bool ALIGN_EPI = false, bool SP2 = false>
; __device__ __forceinline__ void gemm_phase(PG8_LAS unsigned char* lds, const Gemm g, const Sched& S, const Epi& E, const int wv) {
;     ...
;         for (int t = 0; t < nt; t += 2) {
;             const bool last = (t == nt - 2);
;             const char* a1 = cA + (size_t)(t + 1) * kstep;
;             const char* a2 = last ? nA : cA + (size_t)(t + 2) * kstep; const char* b2 = last ? nB : cB + (size_t)(t + 2) * kstep;
;             const char* a3 = a2 + kstep; const char* b3 = b2 + kstep;
;     ...
;             PG8_LDA(At, 1, 1); PG8_STAGE(PG8_SB(1, 0), b3, voffB); PG8_STAGE(PG8_SB(1, 1), b3 + hstepB, voffB); PG8_STAGE(PG8_SA(1, 0), a3, voffA);
;             PG8_WAIT_V(8); PG8_WAIT_L(0); PG8_BAR; PG8_MMA(1, 0, At, B0); PG8_MMA(1, 1, At, B1); PG8_BAR; PG8_SCHED;
	s_add_i32 s54, s73, s53
	v_lshl_add_u64 v[116:117], v[216:217], 0, s[4:5]
	s_mov_b32 m0, s54
	ds_read_b128 v[166:169], v235 offset:49152
	ds_read_b128 v[170:173], v235 offset:50176
	ds_read_b128 v[174:177], v235 offset:51200
	ds_read_b128 v[178:181], v235 offset:52224
	ds_read_b128 v[182:185], v235 offset:53248
	ds_read_b128 v[204:207], v235 offset:54272
	ds_read_b128 v[208:211], v235 offset:55296
	ds_read_b128 v[212:215], v235 offset:56320
	global_load_lds_dwordx4 v[116:117], off
	v_lshl_add_u64 v[116:117], v[218:219], 0, s[4:5]
	s_add_i32 m0, s54, 0x2000
	s_add_i32 s54, s74, s53
	global_load_lds_dwordx4 v[116:117], off
	v_lshl_add_u64 v[116:117], v[236:237], 0, s[4:5]
	s_mov_b32 m0, s54
	s_nop 0
	global_load_lds_dwordx4 v[116:117], off
	v_lshl_add_u64 v[116:117], v[238:239], 0, s[4:5]
	s_add_i32 m0, s54, 0x2000
	s_nop 0
	global_load_lds_dwordx4 v[116:117], off
	v_lshl_add_u64 v[116:117], v[240:241], 0, s[4:5]
	s_mov_b32 m0, s64
	s_nop 0
	global_load_lds_dwordx4 v[116:117], off
	v_lshl_add_u64 v[116:117], v[242:243], 0, s[4:5]
	s_mov_b32 m0, s65
	s_nop 0
	global_load_lds_dwordx4 v[116:117], off
	s_waitcnt vmcnt(8)
	s_waitcnt lgkmcnt(0)
	s_barrier
	s_waitcnt lgkmcnt(0)
	v_mfma_f32_16x16x32_bf16 v[62:65], v[126:129], v[166:169], v[62:65]
	v_mfma_f32_16x16x32_bf16 v[58:61], v[142:145], v[166:169], v[58:61]
	v_mfma_f32_16x16x32_bf16 v[46:49], v[126:129], v[174:177], v[46:49]
	v_mfma_f32_16x16x32_bf16 v[42:45], v[142:145], v[174:177], v[42:45]
	v_mfma_f32_16x16x32_bf16 v[30:33], v[126:129], v[182:185], v[30:33]
	v_mfma_f32_16x16x32_bf16 v[26:29], v[142:145], v[182:185], v[26:29]
	v_mfma_f32_16x16x32_bf16 v[14:17], v[126:129], v[208:211], v[14:17]
	v_mfma_f32_16x16x32_bf16 v[10:13], v[142:145], v[208:211], v[10:13]
	v_mfma_f32_16x16x32_bf16 v[62:65], v[138:141], v[170:173], v[62:65]
	v_mfma_f32_16x16x32_bf16 v[58:61], v[146:149], v[170:173], v[58:61]
	v_mfma_f32_16x16x32_bf16 v[46:49], v[138:141], v[178:181], v[46:49]
	v_mfma_f32_16x16x32_bf16 v[42:45], v[146:149], v[178:181], v[42:45]
	v_mfma_f32_16x16x32_bf16 v[30:33], v[138:141], v[204:207], v[30:33]
	v_mfma_f32_16x16x32_bf16 v[26:29], v[146:149], v[204:207], v[26:29]
	v_mfma_f32_16x16x32_bf16 v[14:17], v[138:141], v[212:215], v[14:17]
	v_mfma_f32_16x16x32_bf16 v[10:13], v[146:149], v[212:215], v[10:13]
	v_mfma_f32_16x16x32_bf16 v[54:57], v[150:153], v[166:169], v[54:57]
	v_mfma_f32_16x16x32_bf16 v[50:53], v[158:161], v[166:169], v[50:53]
	v_mfma_f32_16x16x32_bf16 v[38:41], v[150:153], v[174:177], v[38:41]
	v_mfma_f32_16x16x32_bf16 v[34:37], v[158:161], v[174:177], v[34:37]
	v_mfma_f32_16x16x32_bf16 v[22:25], v[150:153], v[182:185], v[22:25]
	v_mfma_f32_16x16x32_bf16 v[18:21], v[158:161], v[182:185], v[18:21]
	v_mfma_f32_16x16x32_bf16 v[6:9], v[150:153], v[208:211], v[6:9]
	v_mfma_f32_16x16x32_bf16 v[2:5], v[158:161], v[208:211], v[2:5]
	v_mfma_f32_16x16x32_bf16 v[54:57], v[154:157], v[170:173], v[54:57]
	v_mfma_f32_16x16x32_bf16 v[50:53], v[162:165], v[170:173], v[50:53]
	v_mfma_f32_16x16x32_bf16 v[38:41], v[154:157], v[178:181], v[38:41]
	v_mfma_f32_16x16x32_bf16 v[34:37], v[162:165], v[178:181], v[34:37]
	v_mfma_f32_16x16x32_bf16 v[22:25], v[154:157], v[204:207], v[22:25]
	v_mfma_f32_16x16x32_bf16 v[18:21], v[162:165], v[204:207], v[18:21]
	v_mfma_f32_16x16x32_bf16 v[6:9], v[154:157], v[212:215], v[6:9]
	v_mfma_f32_16x16x32_bf16 v[2:5], v[162:165], v[212:215], v[2:5]
	s_barrier
	s_add_u32 s44, s44, 0x100
	s_addc_u32 s45, s45, 0
	s_add_u32 s56, s56, 0x100
	s_addc_u32 s57, s57, 0
	s_cmp_ge_i32 s72, s63
	s_mov_b32 s54, s72
	s_cbranch_scc0 .LBB0_699
	s_movk_i32 s75, 0x2000
	s_mov_b32 s72, 0x10000
	s_mov_b32 s73, 0x12000
	s_mov_b32 s74, 0x14000
	s_mov_b32 s71, 0x3f317217
	s_and_b64 vcc, exec, s[48:49]
	s_cbranch_vccz .LBB0_673

;     __host__ __device__ bool next(int i, Unit& u) const { const int P = (i >> 1) * G + c; if (P >= 256) return false; u.pm = P >> 3; u.pn = (P & 7) + 8 * (i & 1); return true; }
; #define PG8_STAGE(bufoff, gbase, voff) do { _Pragma("unroll") for (int _i = 0; _i < 2; ++_i) \
;         __builtin_amdgcn_global_load_lds((const unsigned*)((const char*)(gbase) + (voff)[_i]), (PG8_LAS unsigned*)(lds + (bufoff) + ldsw + _i * 8192), 16, 0, 0); } while (0)
; #define PG8_LDA(dst, b, h) do { _Pragma("unroll") for (int m = 0; m < 4; ++m) _Pragma("unroll") for (int k = 0; k < 2; ++k) dst[m][k] = *(const PG8_LAS bf16x8*)(lds + PG8_SA(b, h) + aoff + m * 2048 + k * 1024); } while (0)
; #define PG8_LDB(dst, b, h) do { _Pragma("unroll") for (int n = 0; n < 2; ++n) _Pragma("unroll") for (int k = 0; k < 2; ++k) dst[n][k] = *(const PG8_LAS bf16x8*)(lds + PG8_SB(b, h) + boff + n * 2048 + k * 1024); } while (0)
; #define PG8_BAR __builtin_amdgcn_s_barrier()
; template <class Epi, class Sched, bool ALIGN_EPI = false, bool SP2 = false>
; __device__ __forceinline__ void gemm_phase(PG8_LAS unsigned char* lds, const Gemm g, const Sched& S, const Epi& E, const int wv) {
;     ...
;         const bool has_next = S.next(ui + 1, nxt);
;         const char* nA = has_next ? (const char*)g.A + (size_t)nxt.pm * tstepA + (g.amod ? (size_t)(nxt.pn % g.amod) * K * 2 : (size_t)0) : cA; const char* nB = has_next ? (const char*)g.Bt + (size_t)nxt.pn * tstepB : cB;
;         for (int t = 0; t < nt; t += 2) {
;             const bool last = (t == nt - 2);
;             const char* a1 = cA + (size_t)(t + 1) * kstep;
;             const char* a2 = last ? nA : cA + (size_t)(t + 2) * kstep; const char* b2 = last ? nB : cB + (size_t)(t + 2) * kstep;
;             const char* a3 = a2 + kstep; const char* b3 = b2 + kstep;
;             if (last && has_next) S.a_ready(nxt);
;             if constexpr (SP2) {
;             PG8_LDB(B0, 0, 0); PG8_LDB(B1, 0, 1); PG8_SCHED; PG8_LDA(At, 0, 0); PG8_STAGE(PG8_SA(1, 1), a1 + hstepA, voffA);
;             PG8_WAIT_V(8); PG8_WAIT_L(0); PG8_BAR; PG8_MMA(0, 0, At, B0); PG8_MMA(0, 1, At, B1); PG8_BAR; PG8_SCHED;
;             PG8_LDA(At, 0, 1); PG8_STAGE(PG8_SB(0, 0), b2, voffB); PG8_STAGE(PG8_SB(0, 1), b2 + hstepB, voffB); PG8_STAGE(PG8_SA(0, 0), a2, voffA);
;             PG8_WAIT_V(8); PG8_WAIT_L(0); PG8_BAR; PG8_MMA(1, 0, At, B0); PG8_MMA(1, 1, At, B1); PG8_BAR; PG8_SCHED;
.LBB0_809:
	s_add_i32 s52, s46, 2
	s_add_u32 s14, s48, 0x100
	s_addc_u32 s15, s49, 0
	s_add_i32 s53, 0, 0x10000
	s_cmp_eq_u32 s71, s46
	s_cselect_b32 s47, s11, s15
	s_cselect_b32 s46, s13, s14
	s_cselect_b32 s77, s87, s51
	s_cselect_b32 s76, s86, s35
	s_add_i32 s75, 0, 0x14000
	v_add_u32_e32 v150, s53, v208
	v_add_u32_e32 v166, s75, v208
	ds_read_b128 v[138:141], v150
	ds_read_b128 v[142:145], v150 offset:1024
	ds_read_b128 v[146:149], v150 offset:2048
	ds_read_b128 v[150:153], v150 offset:3072
	ds_read_b128 v[154:157], v166
	ds_read_b128 v[158:161], v166 offset:1024
	ds_read_b128 v[162:165], v166 offset:2048
	ds_read_b128 v[166:169], v166 offset:3072
	v_lshl_add_u64 v[190:191], s[48:49], 0, v[182:183]
	s_add_i32 m0, s63, 0xc000
	ds_read_b128 v[194:197], v211
	ds_read_b128 v[198:201], v211 offset:1024
	ds_read_b128 v[202:205], v211 offset:2048
	ds_read_b128 v[214:217], v211 offset:3072
	ds_read_b128 v[228:231], v211 offset:4096
	ds_read_b128 v[232:235], v211 offset:5120
	ds_read_b128 v[236:239], v211 offset:6144
	ds_read_b128 v[240:243], v211 offset:7168
	global_load_lds_dwordx4 v[190:191], off
	v_lshl_add_u64 v[190:191], s[48:49], 0, v[184:185]
	s_add_i32 m0, s63, 0xe000
	s_nop 0
	global_load_lds_dwordx4 v[190:191], off
	s_waitcnt vmcnt(8)
	s_waitcnt lgkmcnt(0)
	s_barrier
	s_waitcnt lgkmcnt(0)
	v_mfma_f32_16x16x32_bf16 v[118:121], v[138:141], v[194:197], v[118:121]
	v_mfma_f32_16x16x32_bf16 v[46:49], v[146:149], v[194:197], v[46:49]
	v_mfma_f32_16x16x32_bf16 v[110:113], v[138:141], v[202:205], v[110:113]
	v_mfma_f32_16x16x32_bf16 v[38:41], v[146:149], v[202:205], v[38:41]
	v_mfma_f32_16x16x32_bf16 v[134:137], v[138:141], v[228:231], v[134:137]
	v_mfma_f32_16x16x32_bf16 v[62:65], v[146:149], v[228:231], v[62:65]
	v_mfma_f32_16x16x32_bf16 v[130:133], v[138:141], v[236:239], v[130:133]
	v_mfma_f32_16x16x32_bf16 v[58:61], v[146:149], v[236:239], v[58:61]
	v_mfma_f32_16x16x32_bf16 v[118:121], v[142:145], v[198:201], v[118:121]
	v_mfma_f32_16x16x32_bf16 v[46:49], v[150:153], v[198:201], v[46:49]
	v_mfma_f32_16x16x32_bf16 v[110:113], v[142:145], v[214:217], v[110:113]
	v_mfma_f32_16x16x32_bf16 v[38:41], v[150:153], v[214:217], v[38:41]
	v_mfma_f32_16x16x32_bf16 v[134:137], v[142:145], v[232:235], v[134:137]
	v_mfma_f32_16x16x32_bf16 v[62:65], v[150:153], v[232:235], v[62:65]
	v_mfma_f32_16x16x32_bf16 v[130:133], v[142:145], v[240:243], v[130:133]
	v_mfma_f32_16x16x32_bf16 v[58:61], v[150:153], v[240:243], v[58:61]
	v_mfma_f32_16x16x32_bf16 v[114:117], v[154:157], v[194:197], v[114:117]
	v_mfma_f32_16x16x32_bf16 v[42:45], v[162:165], v[194:197], v[42:45]
	v_mfma_f32_16x16x32_bf16 v[106:109], v[154:157], v[202:205], v[106:109]
	v_mfma_f32_16x16x32_bf16 v[34:37], v[162:165], v[202:205], v[34:37]
	v_mfma_f32_16x16x32_bf16 v[126:129], v[154:157], v[228:231], v[126:129]
	v_mfma_f32_16x16x32_bf16 v[54:57], v[162:165], v[228:231], v[54:57]
	v_mfma_f32_16x16x32_bf16 v[122:125], v[154:157], v[236:239], v[122:125]
	v_mfma_f32_16x16x32_bf16 v[50:53], v[162:165], v[236:239], v[50:53]
	v_mfma_f32_16x16x32_bf16 v[114:117], v[158:161], v[198:201], v[114:117]
	v_mfma_f32_16x16x32_bf16 v[42:45], v[166:169], v[198:201], v[42:45]
	v_mfma_f32_16x16x32_bf16 v[106:109], v[158:161], v[214:217], v[106:109]
	v_mfma_f32_16x16x32_bf16 v[34:37], v[166:169], v[214:217], v[34:37]
	v_mfma_f32_16x16x32_bf16 v[126:129], v[158:161], v[232:235], v[126:129]
	v_mfma_f32_16x16x32_bf16 v[54:57], v[166:169], v[232:235], v[54:57]
	v_mfma_f32_16x16x32_bf16 v[122:125], v[158:161], v[240:243], v[122:125]
	v_mfma_f32_16x16x32_bf16 v[50:53], v[166:169], v[240:243], v[50:53]
	s_barrier
	s_add_i32 s48, s53, s62
	v_lshl_add_u64 v[190:191], s[76:77], 0, v[0:1]
	s_mov_b32 m0, s48
	ds_read_b128 v[194:197], v211 offset:16384
	ds_read_b128 v[198:201], v211 offset:17408
	ds_read_b128 v[202:205], v211 offset:18432
	ds_read_b128 v[214:217], v211 offset:19456
	ds_read_b128 v[228:231], v211 offset:20480
	ds_read_b128 v[232:235], v211 offset:21504
	ds_read_b128 v[236:239], v211 offset:22528
	ds_read_b128 v[240:243], v211 offset:23552
	global_load_lds_dwordx4 v[190:191], off
	s_add_i32 m0, s48, 0x2000
	s_add_u32 s48, s76, s16
	v_lshl_add_u64 v[192:193], s[76:77], 0, v[174:175]
	s_addc_u32 s49, s77, s17
	s_add_i32 s53, s75, s62
	global_load_lds_dwordx4 v[192:193], off
	v_lshl_add_u64 v[218:219], s[48:49], 0, v[0:1]
	s_mov_b32 m0, s53
	v_lshl_add_u64 v[244:245], s[48:49], 0, v[174:175]
	global_load_lds_dwordx4 v[218:219], off
	s_add_i32 m0, s53, 0x2000
	v_lshl_add_u64 v[246:247], s[46:47], 0, v[170:171]
	global_load_lds_dwordx4 v[244:245], off
	s_mov_b32 m0, s63
	v_lshl_add_u64 v[248:249], s[46:47], 0, v[172:173]
	global_load_lds_dwordx4 v[246:247], off
	s_mov_b32 m0, s64
	s_nop 0
	global_load_lds_dwordx4 v[248:249], off
	s_waitcnt vmcnt(8)
	s_waitcnt lgkmcnt(0)
	s_barrier
; #define PG8_STAGE(bufoff, gbase, voff) do { _Pragma("unroll") for (int _i = 0; _i < 2; ++_i) \
;         __builtin_amdgcn_global_load_lds((const unsigned*)((const char*)(gbase) + (voff)[_i]), (PG8_LAS unsigned*)(lds + (bufoff) + ldsw + _i * 8192), 16, 0, 0); } while (0)
; #define PG8_LDA(dst, b, h) do { _Pragma("unroll") for (int m = 0; m < 4; ++m) _Pragma("unroll") for (int k = 0; k < 2; ++k) dst[m][k] = *(const PG8_LAS bf16x8*)(lds + PG8_SA(b, h) + aoff + m * 2048 + k * 1024); } while (0)
; #define PG8_LDB(dst, b, h) do { _Pragma("unroll") for (int n = 0; n < 2; ++n) _Pragma("unroll") for (int k = 0; k < 2; ++k) dst[n][k] = *(const PG8_LAS bf16x8*)(lds + PG8_SB(b, h) + boff + n * 2048 + k * 1024); } while (0)
; #define PG8_MMA(ai, bj, At, Bt) do { __builtin_amdgcn_s_setprio(1); _Pragma("unroll") for (int m = 0; m < 4; ++m) _Pragma("unroll") for (int n = 0; n < 2; ++n) _Pragma("unroll") for (int k = 0; k < 2; ++k) \
;         acc[ai][bj][m][n] = __builtin_amdgcn_mfma_f32_16x16x32_bf16(Bt[n][k], At[m][k], acc[ai][bj][m][n], 0, 0, 0); __builtin_amdgcn_s_setprio(0); } while (0)
; #define PG8_WAIT_V(n) asm volatile("s_waitcnt vmcnt(" #n ")" ::: "memory")
; #define PG8_WAIT_L(n) asm volatile("s_waitcnt lgkmcnt(" #n ")" ::: "memory")
; #define PG8_BAR __builtin_amdgcn_s_barrier()
; #define PG8_SCHED __builtin_amdgcn_sched_barrier(0)
; template <class Epi, class Sched, bool ALIGN_EPI = false, bool SP2 = false>
; __device__ __forceinline__ void gemm_phase(PG8_LAS unsigned char* lds, const Gemm g, const Sched& S, const Epi& E, const int wv) {
;     ...
;             PG8_WAIT_V(8); PG8_WAIT_L(0); PG8_BAR; PG8_MMA(1, 0, At, B0); PG8_MMA(1, 1, At, B1); PG8_BAR; PG8_SCHED;
;             PG8_LDB(B0, 1, 0); PG8_LDB(B1, 1, 1); PG8_SCHED; PG8_LDA(At, 1, 0); PG8_STAGE(PG8_SA(0, 1), a2 + hstepA, voffA);
;             PG8_WAIT_V(8); PG8_WAIT_L(0); PG8_BAR; PG8_MMA(0, 0, At, B0); PG8_MMA(0, 1, At, B1); PG8_BAR; PG8_SCHED;
	s_waitcnt lgkmcnt(0)
	v_mfma_f32_16x16x32_bf16 v[86:89], v[138:141], v[194:197], v[86:89]
	v_mfma_f32_16x16x32_bf16 v[14:17], v[146:149], v[194:197], v[14:17]
	v_mfma_f32_16x16x32_bf16 v[70:73], v[138:141], v[202:205], v[70:73]
	v_mfma_f32_16x16x32_bf16 v[6:9], v[146:149], v[202:205], v[6:9]
	v_mfma_f32_16x16x32_bf16 v[102:105], v[138:141], v[228:231], v[102:105]
	v_mfma_f32_16x16x32_bf16 v[30:33], v[146:149], v[228:231], v[30:33]
	v_mfma_f32_16x16x32_bf16 v[98:101], v[138:141], v[236:239], v[98:101]
	v_mfma_f32_16x16x32_bf16 v[26:29], v[146:149], v[236:239], v[26:29]
	v_mfma_f32_16x16x32_bf16 v[86:89], v[142:145], v[198:201], v[86:89]
	v_mfma_f32_16x16x32_bf16 v[14:17], v[150:153], v[198:201], v[14:17]
	v_mfma_f32_16x16x32_bf16 v[70:73], v[142:145], v[214:217], v[70:73]
	v_mfma_f32_16x16x32_bf16 v[6:9], v[150:153], v[214:217], v[6:9]
	v_mfma_f32_16x16x32_bf16 v[102:105], v[142:145], v[232:235], v[102:105]
	v_mfma_f32_16x16x32_bf16 v[30:33], v[150:153], v[232:235], v[30:33]
	v_mfma_f32_16x16x32_bf16 v[98:101], v[142:145], v[240:243], v[98:101]
	v_mfma_f32_16x16x32_bf16 v[26:29], v[150:153], v[240:243], v[26:29]
	v_mfma_f32_16x16x32_bf16 v[82:85], v[154:157], v[194:197], v[82:85]
	v_mfma_f32_16x16x32_bf16 v[10:13], v[162:165], v[194:197], v[10:13]
	v_mfma_f32_16x16x32_bf16 v[66:69], v[154:157], v[202:205], v[66:69]
	v_mfma_f32_16x16x32_bf16 v[2:5], v[162:165], v[202:205], v[2:5]
	v_mfma_f32_16x16x32_bf16 v[94:97], v[154:157], v[228:231], v[94:97]
	v_mfma_f32_16x16x32_bf16 v[22:25], v[162:165], v[228:231], v[22:25]
	v_mfma_f32_16x16x32_bf16 v[90:93], v[154:157], v[236:239], v[90:93]
	v_mfma_f32_16x16x32_bf16 v[18:21], v[162:165], v[236:239], v[18:21]
	v_mfma_f32_16x16x32_bf16 v[82:85], v[158:161], v[198:201], v[82:85]
	v_mfma_f32_16x16x32_bf16 v[10:13], v[166:169], v[198:201], v[10:13]
	v_mfma_f32_16x16x32_bf16 v[66:69], v[158:161], v[214:217], v[66:69]
	v_mfma_f32_16x16x32_bf16 v[2:5], v[166:169], v[214:217], v[2:5]
	v_mfma_f32_16x16x32_bf16 v[94:97], v[158:161], v[232:235], v[94:97]
	v_mfma_f32_16x16x32_bf16 v[22:25], v[166:169], v[232:235], v[22:25]
	v_mfma_f32_16x16x32_bf16 v[90:93], v[158:161], v[240:243], v[90:93]
	v_mfma_f32_16x16x32_bf16 v[18:21], v[166:169], v[240:243], v[18:21]
	s_barrier
	s_add_i32 s48, 0, 0x18000
	s_add_i32 s49, 0, 0x1c000
	v_add_u32_e32 v150, s48, v208
	v_add_u32_e32 v166, s49, v208
	ds_read_b128 v[138:141], v150
	ds_read_b128 v[142:145], v150 offset:1024
	ds_read_b128 v[146:149], v150 offset:2048
	ds_read_b128 v[150:153], v150 offset:3072
	ds_read_b128 v[154:157], v166
	ds_read_b128 v[158:161], v166 offset:1024
	ds_read_b128 v[162:165], v166 offset:2048
	ds_read_b128 v[166:169], v166 offset:3072
	s_add_u32 s46, s46, 0x80000
	s_addc_u32 s47, s47, 0
	s_mov_b32 m0, s65
	v_lshl_add_u64 v[250:251], s[46:47], 0, v[170:171]
	ds_read_b128 v[194:197], v211 offset:32768
	ds_read_b128 v[198:201], v211 offset:33792
	ds_read_b128 v[202:205], v211 offset:34816
	ds_read_b128 v[214:217], v211 offset:35840
	ds_read_b128 v[228:231], v211 offset:36864
	ds_read_b128 v[232:235], v211 offset:37888
	ds_read_b128 v[236:239], v211 offset:38912
	ds_read_b128 v[240:243], v211 offset:39936
	global_load_lds_dwordx4 v[250:251], off
	v_lshl_add_u64 v[250:251], s[46:47], 0, v[172:173]
	s_mov_b32 m0, s66
	s_nop 0
	global_load_lds_dwordx4 v[250:251], off
	s_waitcnt vmcnt(8)
	s_waitcnt lgkmcnt(0)
	s_barrier
	s_waitcnt lgkmcnt(0)
	v_mfma_f32_16x16x32_bf16 v[118:121], v[138:141], v[194:197], v[118:121]
	v_mfma_f32_16x16x32_bf16 v[46:49], v[146:149], v[194:197], v[46:49]
	v_mfma_f32_16x16x32_bf16 v[110:113], v[138:141], v[202:205], v[110:113]
	v_mfma_f32_16x16x32_bf16 v[38:41], v[146:149], v[202:205], v[38:41]
	v_mfma_f32_16x16x32_bf16 v[134:137], v[138:141], v[228:231], v[134:137]
	v_mfma_f32_16x16x32_bf16 v[62:65], v[146:149], v[228:231], v[62:65]
	v_mfma_f32_16x16x32_bf16 v[130:133], v[138:141], v[236:239], v[130:133]
	v_mfma_f32_16x16x32_bf16 v[58:61], v[146:149], v[236:239], v[58:61]
	v_mfma_f32_16x16x32_bf16 v[118:121], v[142:145], v[198:201], v[118:121]
	v_mfma_f32_16x16x32_bf16 v[46:49], v[150:153], v[198:201], v[46:49]
	v_mfma_f32_16x16x32_bf16 v[110:113], v[142:145], v[214:217], v[110:113]
	v_mfma_f32_16x16x32_bf16 v[38:41], v[150:153], v[214:217], v[38:41]
	v_mfma_f32_16x16x32_bf16 v[134:137], v[142:145], v[232:235], v[134:137]
	v_mfma_f32_16x16x32_bf16 v[62:65], v[150:153], v[232:235], v[62:65]
	v_mfma_f32_16x16x32_bf16 v[130:133], v[142:145], v[240:243], v[130:133]
	v_mfma_f32_16x16x32_bf16 v[58:61], v[150:153], v[240:243], v[58:61]
	v_mfma_f32_16x16x32_bf16 v[114:117], v[154:157], v[194:197], v[114:117]
	v_mfma_f32_16x16x32_bf16 v[42:45], v[162:165], v[194:197], v[42:45]
	v_mfma_f32_16x16x32_bf16 v[106:109], v[154:157], v[202:205], v[106:109]
	v_mfma_f32_16x16x32_bf16 v[34:37], v[162:165], v[202:205], v[34:37]
	v_mfma_f32_16x16x32_bf16 v[126:129], v[154:157], v[228:231], v[126:129]
	v_mfma_f32_16x16x32_bf16 v[54:57], v[162:165], v[228:231], v[54:57]
	v_mfma_f32_16x16x32_bf16 v[122:125], v[154:157], v[236:239], v[122:125]
	v_mfma_f32_16x16x32_bf16 v[50:53], v[162:165], v[236:239], v[50:53]
	v_mfma_f32_16x16x32_bf16 v[114:117], v[158:161], v[198:201], v[114:117]
	v_mfma_f32_16x16x32_bf16 v[42:45], v[166:169], v[198:201], v[42:45]
	v_mfma_f32_16x16x32_bf16 v[106:109], v[158:161], v[214:217], v[106:109]
	v_mfma_f32_16x16x32_bf16 v[34:37], v[166:169], v[214:217], v[34:37]
	v_mfma_f32_16x16x32_bf16 v[126:129], v[158:161], v[232:235], v[126:129]
	v_mfma_f32_16x16x32_bf16 v[54:57], v[166:169], v[232:235], v[54:57]
	v_mfma_f32_16x16x32_bf16 v[122:125], v[158:161], v[240:243], v[122:125]
	v_mfma_f32_16x16x32_bf16 v[50:53], v[166:169], v[240:243], v[50:53]
	s_barrier
; #define PG8_STAGE(bufoff, gbase, voff) do { _Pragma("unroll") for (int _i = 0; _i < 2; ++_i) \
;         __builtin_amdgcn_global_load_lds((const unsigned*)((const char*)(gbase) + (voff)[_i]), (PG8_LAS unsigned*)(lds + (bufoff) + ldsw + _i * 8192), 16, 0, 0); } while (0)
; #define PG8_LDA(dst, b, h) do { _Pragma("unroll") for (int m = 0; m < 4; ++m) _Pragma("unroll") for (int k = 0; k < 2; ++k) dst[m][k] = *(const PG8_LAS bf16x8*)(lds + PG8_SA(b, h) + aoff + m * 2048 + k * 1024); } while (0)
; #define PG8_MMA(ai, bj, At, Bt) do { __builtin_amdgcn_s_setprio(1); _Pragma("unroll") for (int m = 0; m < 4; ++m) _Pragma("unroll") for (int n = 0; n < 2; ++n) _Pragma("unroll") for (int k = 0; k < 2; ++k) \
;         acc[ai][bj][m][n] = __builtin_amdgcn_mfma_f32_16x16x32_bf16(Bt[n][k], At[m][k], acc[ai][bj][m][n], 0, 0, 0); __builtin_amdgcn_s_setprio(0); } while (0)
; #define PG8_WAIT_V(n) asm volatile("s_waitcnt vmcnt(" #n ")" ::: "memory")
; #define PG8_WAIT_L(n) asm volatile("s_waitcnt lgkmcnt(" #n ")" ::: "memory")
; #define PG8_BAR __builtin_amdgcn_s_barrier()
; #define PG8_SCHED __builtin_amdgcn_sched_barrier(0)
; template <class Epi, class Sched, bool ALIGN_EPI = false, bool SP2 = false>
; __device__ __forceinline__ void gemm_phase(PG8_LAS unsigned char* lds, const Gemm g, const Sched& S, const Epi& E, const int wv) {
;     ...
;         for (int t = 0; t < nt; t += 2) {
;             const bool last = (t == nt - 2);
;             const char* a1 = cA + (size_t)(t + 1) * kstep;
;             const char* a2 = last ? nA : cA + (size_t)(t + 2) * kstep; const char* b2 = last ? nB : cB + (size_t)(t + 2) * kstep;
;             const char* a3 = a2 + kstep; const char* b3 = b2 + kstep;
;     ...
;             PG8_LDA(At, 1, 1); PG8_STAGE(PG8_SB(1, 0), b3, voffB); PG8_STAGE(PG8_SB(1, 1), b3 + hstepB, voffB); PG8_STAGE(PG8_SA(1, 0), a3, voffA);
;             PG8_WAIT_V(8); PG8_WAIT_L(0); PG8_BAR; PG8_MMA(1, 0, At, B0); PG8_MMA(1, 1, At, B1); PG8_BAR; PG8_SCHED;
	s_add_i32 s46, s48, s62
	v_lshl_add_u64 v[190:191], v[190:191], 0, s[4:5]
	s_mov_b32 m0, s46
	ds_read_b128 v[194:197], v211 offset:49152
	ds_read_b128 v[198:201], v211 offset:50176
	ds_read_b128 v[202:205], v211 offset:51200
	ds_read_b128 v[214:217], v211 offset:52224
	ds_read_b128 v[228:231], v211 offset:53248
	ds_read_b128 v[232:235], v211 offset:54272
	ds_read_b128 v[236:239], v211 offset:55296
	ds_read_b128 v[240:243], v211 offset:56320
	global_load_lds_dwordx4 v[190:191], off
	v_lshl_add_u64 v[190:191], v[192:193], 0, s[4:5]
	s_add_i32 m0, s46, 0x2000
	s_add_i32 s46, s49, s62
	global_load_lds_dwordx4 v[190:191], off
	v_lshl_add_u64 v[190:191], v[218:219], 0, s[4:5]
	s_mov_b32 m0, s46
	s_nop 0
	global_load_lds_dwordx4 v[190:191], off
	v_lshl_add_u64 v[190:191], v[244:245], 0, s[4:5]
	s_add_i32 m0, s46, 0x2000
	s_nop 0
	global_load_lds_dwordx4 v[190:191], off
	v_lshl_add_u64 v[190:191], v[246:247], 0, s[4:5]
	s_mov_b32 m0, s69
	s_nop 0
	global_load_lds_dwordx4 v[190:191], off
	v_lshl_add_u64 v[190:191], v[248:249], 0, s[4:5]
	s_mov_b32 m0, s70
	s_nop 0
	global_load_lds_dwordx4 v[190:191], off
	s_waitcnt vmcnt(8)
	s_waitcnt lgkmcnt(0)
	s_barrier
	s_waitcnt lgkmcnt(0)
	v_mfma_f32_16x16x32_bf16 v[86:89], v[138:141], v[194:197], v[86:89]
	v_mfma_f32_16x16x32_bf16 v[14:17], v[146:149], v[194:197], v[14:17]
	v_mfma_f32_16x16x32_bf16 v[70:73], v[138:141], v[202:205], v[70:73]
	v_mfma_f32_16x16x32_bf16 v[6:9], v[146:149], v[202:205], v[6:9]
	v_mfma_f32_16x16x32_bf16 v[102:105], v[138:141], v[228:231], v[102:105]
	v_mfma_f32_16x16x32_bf16 v[30:33], v[146:149], v[228:231], v[30:33]
	v_mfma_f32_16x16x32_bf16 v[98:101], v[138:141], v[236:239], v[98:101]
	v_mfma_f32_16x16x32_bf16 v[26:29], v[146:149], v[236:239], v[26:29]
	v_mfma_f32_16x16x32_bf16 v[86:89], v[142:145], v[198:201], v[86:89]
	v_mfma_f32_16x16x32_bf16 v[14:17], v[150:153], v[198:201], v[14:17]
	v_mfma_f32_16x16x32_bf16 v[70:73], v[142:145], v[214:217], v[70:73]
	v_mfma_f32_16x16x32_bf16 v[6:9], v[150:153], v[214:217], v[6:9]
	v_mfma_f32_16x16x32_bf16 v[102:105], v[142:145], v[232:235], v[102:105]
	v_mfma_f32_16x16x32_bf16 v[30:33], v[150:153], v[232:235], v[30:33]
	v_mfma_f32_16x16x32_bf16 v[98:101], v[142:145], v[240:243], v[98:101]
	v_mfma_f32_16x16x32_bf16 v[26:29], v[150:153], v[240:243], v[26:29]
	v_mfma_f32_16x16x32_bf16 v[82:85], v[154:157], v[194:197], v[82:85]
	v_mfma_f32_16x16x32_bf16 v[10:13], v[162:165], v[194:197], v[10:13]
	v_mfma_f32_16x16x32_bf16 v[66:69], v[154:157], v[202:205], v[66:69]
	v_mfma_f32_16x16x32_bf16 v[2:5], v[162:165], v[202:205], v[2:5]
	v_mfma_f32_16x16x32_bf16 v[94:97], v[154:157], v[228:231], v[94:97]
	v_mfma_f32_16x16x32_bf16 v[22:25], v[162:165], v[228:231], v[22:25]
	v_mfma_f32_16x16x32_bf16 v[90:93], v[154:157], v[236:239], v[90:93]
	v_mfma_f32_16x16x32_bf16 v[18:21], v[162:165], v[236:239], v[18:21]
	v_mfma_f32_16x16x32_bf16 v[82:85], v[158:161], v[198:201], v[82:85]
	v_mfma_f32_16x16x32_bf16 v[10:13], v[166:169], v[198:201], v[10:13]
	v_mfma_f32_16x16x32_bf16 v[66:69], v[158:161], v[214:217], v[66:69]
	v_mfma_f32_16x16x32_bf16 v[2:5], v[166:169], v[214:217], v[2:5]
	v_mfma_f32_16x16x32_bf16 v[94:97], v[158:161], v[232:235], v[94:97]
	v_mfma_f32_16x16x32_bf16 v[22:25], v[166:169], v[232:235], v[22:25]
	v_mfma_f32_16x16x32_bf16 v[90:93], v[158:161], v[240:243], v[90:93]
	v_mfma_f32_16x16x32_bf16 v[18:21], v[166:169], v[240:243], v[18:21]
	s_barrier
	s_add_u32 s35, s35, 0x100
	s_addc_u32 s51, s51, 0
	s_cmp_ge_i32 s52, s67
	s_mov_b64 s[48:49], s[14:15]
	s_mov_b32 s46, s52
	s_cbranch_scc0 .LBB0_809
	s_movk_i32 s75, 0x2000
	s_movk_i32 s76, 0x3000
	s_and_b64 vcc, exec, s[30:31]
	s_cbranch_vccz .LBB0_784

;     __host__ __device__ bool next(int i, Unit& u) const { const int P = (i >> 1) * G + c; if (P >= 256) return false; u.pm = P >> 3; u.pn = (P & 7) + 8 * (i & 1); return true; }
; #define PG8_STAGE(bufoff, gbase, voff) do { _Pragma("unroll") for (int _i = 0; _i < 2; ++_i) \
;         __builtin_amdgcn_global_load_lds((const unsigned*)((const char*)(gbase) + (voff)[_i]), (PG8_LAS unsigned*)(lds + (bufoff) + ldsw + _i * 8192), 16, 0, 0); } while (0)
; #define PG8_LDA(dst, b, h) do { _Pragma("unroll") for (int m = 0; m < 4; ++m) _Pragma("unroll") for (int k = 0; k < 2; ++k) dst[m][k] = *(const PG8_LAS bf16x8*)(lds + PG8_SA(b, h) + aoff + m * 2048 + k * 1024); } while (0)
; #define PG8_LDB(dst, b, h) do { _Pragma("unroll") for (int n = 0; n < 2; ++n) _Pragma("unroll") for (int k = 0; k < 2; ++k) dst[n][k] = *(const PG8_LAS bf16x8*)(lds + PG8_SB(b, h) + boff + n * 2048 + k * 1024); } while (0)
; #define PG8_BAR __builtin_amdgcn_s_barrier()
; template <class Epi, class Sched, bool ALIGN_EPI = false, bool SP2 = false>
; __device__ __forceinline__ void gemm_phase(PG8_LAS unsigned char* lds, const Gemm g, const Sched& S, const Epi& E, const int wv) {
;     ...
;         const bool has_next = S.next(ui + 1, nxt);
;         const char* nA = has_next ? (const char*)g.A + (size_t)nxt.pm * tstepA + (g.amod ? (size_t)(nxt.pn % g.amod) * K * 2 : (size_t)0) : cA; const char* nB = has_next ? (const char*)g.Bt + (size_t)nxt.pn * tstepB : cB;
;         for (int t = 0; t < nt; t += 2) {
;             const bool last = (t == nt - 2);
;             const char* a1 = cA + (size_t)(t + 1) * kstep;
;             const char* a2 = last ? nA : cA + (size_t)(t + 2) * kstep; const char* b2 = last ? nB : cB + (size_t)(t + 2) * kstep;
;             const char* a3 = a2 + kstep; const char* b3 = b2 + kstep;
;             if (last && has_next) S.a_ready(nxt);
;             if constexpr (SP2) {
;             PG8_LDB(B0, 0, 0); PG8_LDB(B1, 0, 1); PG8_SCHED; PG8_LDA(At, 0, 0); PG8_STAGE(PG8_SA(1, 1), a1 + hstepA, voffA);
;             PG8_WAIT_V(8); PG8_WAIT_L(0); PG8_BAR; PG8_MMA(0, 0, At, B0); PG8_MMA(0, 1, At, B1); PG8_BAR; PG8_SCHED;
;             PG8_LDA(At, 0, 1); PG8_STAGE(PG8_SB(0, 0), b2, voffB); PG8_STAGE(PG8_SB(0, 1), b2 + hstepB, voffB); PG8_STAGE(PG8_SA(0, 0), a2, voffA);
;             PG8_WAIT_V(8); PG8_WAIT_L(0); PG8_BAR; PG8_MMA(1, 0, At, B0); PG8_MMA(1, 1, At, B1); PG8_BAR; PG8_SCHED;
.LBB0_990:
	s_add_i32 s67, s44, 2
	s_add_u32 s34, s30, 0x100
	s_addc_u32 s35, s31, 0
	s_add_i32 s70, 0, 0x10000
	s_cmp_eq_u32 s59, s44
	s_cselect_b32 s45, s13, s35
	s_cselect_b32 s44, s12, s34
	s_cselect_b32 s69, s15, s66
	s_cselect_b32 s68, s14, s65
	s_add_i32 s71, 0, 0x14000
	v_add_u32_e32 v142, s70, v230
	v_add_u32_e32 v158, s71, v230
	ds_read_b128 v[114:117], v142
	ds_read_b128 v[126:129], v142 offset:1024
	ds_read_b128 v[138:141], v142 offset:2048
	ds_read_b128 v[142:145], v142 offset:3072
	ds_read_b128 v[146:149], v158
	ds_read_b128 v[150:153], v158 offset:1024
	ds_read_b128 v[154:157], v158 offset:2048
	ds_read_b128 v[158:161], v158 offset:3072
	v_lshl_add_u64 v[190:191], s[30:31], 0, v[200:201]
	s_add_i32 m0, s52, 0xc000
	ds_read_b128 v[162:165], v235
	ds_read_b128 v[166:169], v235 offset:1024
	ds_read_b128 v[170:173], v235 offset:2048
	ds_read_b128 v[174:177], v235 offset:3072
	ds_read_b128 v[178:181], v235 offset:4096
	ds_read_b128 v[182:185], v235 offset:5120
	ds_read_b128 v[204:207], v235 offset:6144
	ds_read_b128 v[208:211], v235 offset:7168
	global_load_lds_dwordx4 v[190:191], off
	v_lshl_add_u64 v[190:191], s[30:31], 0, v[202:203]
	s_add_i32 m0, s52, 0xe000
	s_nop 0
	global_load_lds_dwordx4 v[190:191], off
	s_waitcnt vmcnt(8)
	s_waitcnt lgkmcnt(0)
	s_barrier
	s_waitcnt lgkmcnt(0)
	v_mfma_f32_16x16x32_bf16 v[134:137], v[114:117], v[162:165], v[134:137]
	v_mfma_f32_16x16x32_bf16 v[130:133], v[138:141], v[162:165], v[130:133]
	v_mfma_f32_16x16x32_bf16 v[110:113], v[114:117], v[170:173], v[110:113]
	v_mfma_f32_16x16x32_bf16 v[106:109], v[138:141], v[170:173], v[106:109]
	v_mfma_f32_16x16x32_bf16 v[94:97], v[114:117], v[178:181], v[94:97]
	v_mfma_f32_16x16x32_bf16 v[90:93], v[138:141], v[178:181], v[90:93]
	v_mfma_f32_16x16x32_bf16 v[78:81], v[114:117], v[204:207], v[78:81]
	v_mfma_f32_16x16x32_bf16 v[74:77], v[138:141], v[204:207], v[74:77]
	v_mfma_f32_16x16x32_bf16 v[134:137], v[126:129], v[166:169], v[134:137]
	v_mfma_f32_16x16x32_bf16 v[130:133], v[142:145], v[166:169], v[130:133]
	v_mfma_f32_16x16x32_bf16 v[110:113], v[126:129], v[174:177], v[110:113]
	v_mfma_f32_16x16x32_bf16 v[106:109], v[142:145], v[174:177], v[106:109]
	v_mfma_f32_16x16x32_bf16 v[94:97], v[126:129], v[182:185], v[94:97]
	v_mfma_f32_16x16x32_bf16 v[90:93], v[142:145], v[182:185], v[90:93]
	v_mfma_f32_16x16x32_bf16 v[78:81], v[126:129], v[208:211], v[78:81]
	v_mfma_f32_16x16x32_bf16 v[74:77], v[142:145], v[208:211], v[74:77]
	v_mfma_f32_16x16x32_bf16 v[122:125], v[146:149], v[162:165], v[122:125]
	v_mfma_f32_16x16x32_bf16 v[118:121], v[154:157], v[162:165], v[118:121]
	v_mfma_f32_16x16x32_bf16 v[102:105], v[146:149], v[170:173], v[102:105]
	v_mfma_f32_16x16x32_bf16 v[98:101], v[154:157], v[170:173], v[98:101]
	v_mfma_f32_16x16x32_bf16 v[86:89], v[146:149], v[178:181], v[86:89]
	v_mfma_f32_16x16x32_bf16 v[82:85], v[154:157], v[178:181], v[82:85]
	v_mfma_f32_16x16x32_bf16 v[70:73], v[146:149], v[204:207], v[70:73]
	v_mfma_f32_16x16x32_bf16 v[66:69], v[154:157], v[204:207], v[66:69]
	v_mfma_f32_16x16x32_bf16 v[122:125], v[150:153], v[166:169], v[122:125]
	v_mfma_f32_16x16x32_bf16 v[118:121], v[158:161], v[166:169], v[118:121]
	v_mfma_f32_16x16x32_bf16 v[102:105], v[150:153], v[174:177], v[102:105]
	v_mfma_f32_16x16x32_bf16 v[98:101], v[158:161], v[174:177], v[98:101]
	v_mfma_f32_16x16x32_bf16 v[86:89], v[150:153], v[182:185], v[86:89]
	v_mfma_f32_16x16x32_bf16 v[82:85], v[158:161], v[182:185], v[82:85]
	v_mfma_f32_16x16x32_bf16 v[70:73], v[150:153], v[208:211], v[70:73]
	v_mfma_f32_16x16x32_bf16 v[66:69], v[158:161], v[208:211], v[66:69]
	s_barrier
	s_add_i32 s30, s70, s47
	v_lshl_add_u64 v[190:191], s[68:69], 0, v[0:1]
	s_mov_b32 m0, s30
	ds_read_b128 v[162:165], v235 offset:16384
	ds_read_b128 v[166:169], v235 offset:17408
	ds_read_b128 v[170:173], v235 offset:18432
	ds_read_b128 v[174:177], v235 offset:19456
	ds_read_b128 v[178:181], v235 offset:20480
	ds_read_b128 v[182:185], v235 offset:21504
	ds_read_b128 v[204:207], v235 offset:22528
	ds_read_b128 v[208:211], v235 offset:23552
	global_load_lds_dwordx4 v[190:191], off
	s_add_i32 m0, s30, 0x2000
	s_add_u32 s30, s68, s2
	v_lshl_add_u64 v[192:193], s[68:69], 0, v[198:199]
	s_addc_u32 s31, s69, s3
	s_add_i32 s68, s71, s47
	global_load_lds_dwordx4 v[192:193], off
	v_lshl_add_u64 v[212:213], s[30:31], 0, v[0:1]
	s_mov_b32 m0, s68
	v_lshl_add_u64 v[214:215], s[30:31], 0, v[198:199]
	global_load_lds_dwordx4 v[212:213], off
	s_add_i32 m0, s68, 0x2000
	v_lshl_add_u64 v[216:217], s[44:45], 0, v[194:195]
	global_load_lds_dwordx4 v[214:215], off
	s_mov_b32 m0, s52
	v_lshl_add_u64 v[218:219], s[44:45], 0, v[196:197]
	global_load_lds_dwordx4 v[216:217], off
	s_mov_b32 m0, s53
	s_nop 0
	global_load_lds_dwordx4 v[218:219], off
	s_waitcnt vmcnt(8)
	s_waitcnt lgkmcnt(0)
	s_barrier
; #define PG8_STAGE(bufoff, gbase, voff) do { _Pragma("unroll") for (int _i = 0; _i < 2; ++_i) \
;         __builtin_amdgcn_global_load_lds((const unsigned*)((const char*)(gbase) + (voff)[_i]), (PG8_LAS unsigned*)(lds + (bufoff) + ldsw + _i * 8192), 16, 0, 0); } while (0)
; #define PG8_LDA(dst, b, h) do { _Pragma("unroll") for (int m = 0; m < 4; ++m) _Pragma("unroll") for (int k = 0; k < 2; ++k) dst[m][k] = *(const PG8_LAS bf16x8*)(lds + PG8_SA(b, h) + aoff + m * 2048 + k * 1024); } while (0)
; #define PG8_LDB(dst, b, h) do { _Pragma("unroll") for (int n = 0; n < 2; ++n) _Pragma("unroll") for (int k = 0; k < 2; ++k) dst[n][k] = *(const PG8_LAS bf16x8*)(lds + PG8_SB(b, h) + boff + n * 2048 + k * 1024); } while (0)
; #define PG8_MMA(ai, bj, At, Bt) do { __builtin_amdgcn_s_setprio(1); _Pragma("unroll") for (int m = 0; m < 4; ++m) _Pragma("unroll") for (int n = 0; n < 2; ++n) _Pragma("unroll") for (int k = 0; k < 2; ++k) \
;         acc[ai][bj][m][n] = __builtin_amdgcn_mfma_f32_16x16x32_bf16(Bt[n][k], At[m][k], acc[ai][bj][m][n], 0, 0, 0); __builtin_amdgcn_s_setprio(0); } while (0)
; #define PG8_WAIT_V(n) asm volatile("s_waitcnt vmcnt(" #n ")" ::: "memory")
; #define PG8_WAIT_L(n) asm volatile("s_waitcnt lgkmcnt(" #n ")" ::: "memory")
; #define PG8_BAR __builtin_amdgcn_s_barrier()
; #define PG8_SCHED __builtin_amdgcn_sched_barrier(0)
; template <class Epi, class Sched, bool ALIGN_EPI = false, bool SP2 = false>
; __device__ __forceinline__ void gemm_phase(PG8_LAS unsigned char* lds, const Gemm g, const Sched& S, const Epi& E, const int wv) {
;     ...
;             PG8_WAIT_V(8); PG8_WAIT_L(0); PG8_BAR; PG8_MMA(1, 0, At, B0); PG8_MMA(1, 1, At, B1); PG8_BAR; PG8_SCHED;
;             PG8_LDB(B0, 1, 0); PG8_LDB(B1, 1, 1); PG8_SCHED; PG8_LDA(At, 1, 0); PG8_STAGE(PG8_SA(0, 1), a2 + hstepA, voffA);
;             PG8_WAIT_V(8); PG8_WAIT_L(0); PG8_BAR; PG8_MMA(0, 0, At, B0); PG8_MMA(0, 1, At, B1); PG8_BAR; PG8_SCHED;
	s_waitcnt lgkmcnt(0)
	v_mfma_f32_16x16x32_bf16 v[62:65], v[114:117], v[162:165], v[62:65]
	v_mfma_f32_16x16x32_bf16 v[58:61], v[138:141], v[162:165], v[58:61]
	v_mfma_f32_16x16x32_bf16 v[46:49], v[114:117], v[170:173], v[46:49]
	v_mfma_f32_16x16x32_bf16 v[42:45], v[138:141], v[170:173], v[42:45]
	v_mfma_f32_16x16x32_bf16 v[30:33], v[114:117], v[178:181], v[30:33]
	v_mfma_f32_16x16x32_bf16 v[26:29], v[138:141], v[178:181], v[26:29]
	v_mfma_f32_16x16x32_bf16 v[14:17], v[114:117], v[204:207], v[14:17]
	v_mfma_f32_16x16x32_bf16 v[10:13], v[138:141], v[204:207], v[10:13]
	v_mfma_f32_16x16x32_bf16 v[62:65], v[126:129], v[166:169], v[62:65]
	v_mfma_f32_16x16x32_bf16 v[58:61], v[142:145], v[166:169], v[58:61]
	v_mfma_f32_16x16x32_bf16 v[46:49], v[126:129], v[174:177], v[46:49]
	v_mfma_f32_16x16x32_bf16 v[42:45], v[142:145], v[174:177], v[42:45]
	v_mfma_f32_16x16x32_bf16 v[30:33], v[126:129], v[182:185], v[30:33]
	v_mfma_f32_16x16x32_bf16 v[26:29], v[142:145], v[182:185], v[26:29]
	v_mfma_f32_16x16x32_bf16 v[14:17], v[126:129], v[208:211], v[14:17]
	v_mfma_f32_16x16x32_bf16 v[10:13], v[142:145], v[208:211], v[10:13]
	v_mfma_f32_16x16x32_bf16 v[54:57], v[146:149], v[162:165], v[54:57]
	v_mfma_f32_16x16x32_bf16 v[50:53], v[154:157], v[162:165], v[50:53]
	v_mfma_f32_16x16x32_bf16 v[38:41], v[146:149], v[170:173], v[38:41]
	v_mfma_f32_16x16x32_bf16 v[34:37], v[154:157], v[170:173], v[34:37]
	v_mfma_f32_16x16x32_bf16 v[22:25], v[146:149], v[178:181], v[22:25]
	v_mfma_f32_16x16x32_bf16 v[18:21], v[154:157], v[178:181], v[18:21]
	v_mfma_f32_16x16x32_bf16 v[6:9], v[146:149], v[204:207], v[6:9]
	v_mfma_f32_16x16x32_bf16 v[2:5], v[154:157], v[204:207], v[2:5]
	v_mfma_f32_16x16x32_bf16 v[54:57], v[150:153], v[166:169], v[54:57]
	v_mfma_f32_16x16x32_bf16 v[50:53], v[158:161], v[166:169], v[50:53]
	v_mfma_f32_16x16x32_bf16 v[38:41], v[150:153], v[174:177], v[38:41]
	v_mfma_f32_16x16x32_bf16 v[34:37], v[158:161], v[174:177], v[34:37]
	v_mfma_f32_16x16x32_bf16 v[22:25], v[150:153], v[182:185], v[22:25]
	v_mfma_f32_16x16x32_bf16 v[18:21], v[158:161], v[182:185], v[18:21]
	v_mfma_f32_16x16x32_bf16 v[6:9], v[150:153], v[208:211], v[6:9]
	v_mfma_f32_16x16x32_bf16 v[2:5], v[158:161], v[208:211], v[2:5]
	s_barrier
	s_add_i32 s68, 0, 0x18000
	s_add_i32 s69, 0, 0x1c000
	v_add_u32_e32 v142, s68, v230
	v_add_u32_e32 v158, s69, v230
	ds_read_b128 v[114:117], v142
	ds_read_b128 v[126:129], v142 offset:1024
	ds_read_b128 v[138:141], v142 offset:2048
	ds_read_b128 v[142:145], v142 offset:3072
	ds_read_b128 v[146:149], v158
	ds_read_b128 v[150:153], v158 offset:1024
	ds_read_b128 v[154:157], v158 offset:2048
	ds_read_b128 v[158:161], v158 offset:3072
	s_add_u32 s30, s44, 0x180000
	s_addc_u32 s31, s45, 0
	s_mov_b32 m0, s54
	v_lshl_add_u64 v[236:237], s[30:31], 0, v[194:195]
	ds_read_b128 v[162:165], v235 offset:32768
	ds_read_b128 v[166:169], v235 offset:33792
	ds_read_b128 v[170:173], v235 offset:34816
	ds_read_b128 v[174:177], v235 offset:35840
	ds_read_b128 v[178:181], v235 offset:36864
	ds_read_b128 v[182:185], v235 offset:37888
	ds_read_b128 v[204:207], v235 offset:38912
	ds_read_b128 v[208:211], v235 offset:39936
	global_load_lds_dwordx4 v[236:237], off
	v_lshl_add_u64 v[236:237], s[30:31], 0, v[196:197]
	s_mov_b32 m0, s55
	s_nop 0
	global_load_lds_dwordx4 v[236:237], off
	s_waitcnt vmcnt(8)
	s_waitcnt lgkmcnt(0)
	s_barrier
	s_waitcnt lgkmcnt(0)
	v_mfma_f32_16x16x32_bf16 v[134:137], v[114:117], v[162:165], v[134:137]
	v_mfma_f32_16x16x32_bf16 v[130:133], v[138:141], v[162:165], v[130:133]
	v_mfma_f32_16x16x32_bf16 v[110:113], v[114:117], v[170:173], v[110:113]
	v_mfma_f32_16x16x32_bf16 v[106:109], v[138:141], v[170:173], v[106:109]
	v_mfma_f32_16x16x32_bf16 v[94:97], v[114:117], v[178:181], v[94:97]
	v_mfma_f32_16x16x32_bf16 v[90:93], v[138:141], v[178:181], v[90:93]
	v_mfma_f32_16x16x32_bf16 v[78:81], v[114:117], v[204:207], v[78:81]
	v_mfma_f32_16x16x32_bf16 v[74:77], v[138:141], v[204:207], v[74:77]
	v_mfma_f32_16x16x32_bf16 v[134:137], v[126:129], v[166:169], v[134:137]
	v_mfma_f32_16x16x32_bf16 v[130:133], v[142:145], v[166:169], v[130:133]
	v_mfma_f32_16x16x32_bf16 v[110:113], v[126:129], v[174:177], v[110:113]
	v_mfma_f32_16x16x32_bf16 v[106:109], v[142:145], v[174:177], v[106:109]
	v_mfma_f32_16x16x32_bf16 v[94:97], v[126:129], v[182:185], v[94:97]
	v_mfma_f32_16x16x32_bf16 v[90:93], v[142:145], v[182:185], v[90:93]
	v_mfma_f32_16x16x32_bf16 v[78:81], v[126:129], v[208:211], v[78:81]
	v_mfma_f32_16x16x32_bf16 v[74:77], v[142:145], v[208:211], v[74:77]
	v_mfma_f32_16x16x32_bf16 v[122:125], v[146:149], v[162:165], v[122:125]
	v_mfma_f32_16x16x32_bf16 v[118:121], v[154:157], v[162:165], v[118:121]
	v_mfma_f32_16x16x32_bf16 v[102:105], v[146:149], v[170:173], v[102:105]
	v_mfma_f32_16x16x32_bf16 v[98:101], v[154:157], v[170:173], v[98:101]
	v_mfma_f32_16x16x32_bf16 v[86:89], v[146:149], v[178:181], v[86:89]
	v_mfma_f32_16x16x32_bf16 v[82:85], v[154:157], v[178:181], v[82:85]
	v_mfma_f32_16x16x32_bf16 v[70:73], v[146:149], v[204:207], v[70:73]
	v_mfma_f32_16x16x32_bf16 v[66:69], v[154:157], v[204:207], v[66:69]
	v_mfma_f32_16x16x32_bf16 v[122:125], v[150:153], v[166:169], v[122:125]
	v_mfma_f32_16x16x32_bf16 v[118:121], v[158:161], v[166:169], v[118:121]
	v_mfma_f32_16x16x32_bf16 v[102:105], v[150:153], v[174:177], v[102:105]
	v_mfma_f32_16x16x32_bf16 v[98:101], v[158:161], v[174:177], v[98:101]
	v_mfma_f32_16x16x32_bf16 v[86:89], v[150:153], v[182:185], v[86:89]
	v_mfma_f32_16x16x32_bf16 v[82:85], v[158:161], v[182:185], v[82:85]
	v_mfma_f32_16x16x32_bf16 v[70:73], v[150:153], v[208:211], v[70:73]
	v_mfma_f32_16x16x32_bf16 v[66:69], v[158:161], v[208:211], v[66:69]
	s_barrier
; #define PG8_STAGE(bufoff, gbase, voff) do { _Pragma("unroll") for (int _i = 0; _i < 2; ++_i) \
;         __builtin_amdgcn_global_load_lds((const unsigned*)((const char*)(gbase) + (voff)[_i]), (PG8_LAS unsigned*)(lds + (bufoff) + ldsw + _i * 8192), 16, 0, 0); } while (0)
; #define PG8_LDA(dst, b, h) do { _Pragma("unroll") for (int m = 0; m < 4; ++m) _Pragma("unroll") for (int k = 0; k < 2; ++k) dst[m][k] = *(const PG8_LAS bf16x8*)(lds + PG8_SA(b, h) + aoff + m * 2048 + k * 1024); } while (0)
; #define PG8_MMA(ai, bj, At, Bt) do { __builtin_amdgcn_s_setprio(1); _Pragma("unroll") for (int m = 0; m < 4; ++m) _Pragma("unroll") for (int n = 0; n < 2; ++n) _Pragma("unroll") for (int k = 0; k < 2; ++k) \
;         acc[ai][bj][m][n] = __builtin_amdgcn_mfma_f32_16x16x32_bf16(Bt[n][k], At[m][k], acc[ai][bj][m][n], 0, 0, 0); __builtin_amdgcn_s_setprio(0); } while (0)
; #define PG8_WAIT_V(n) asm volatile("s_waitcnt vmcnt(" #n ")" ::: "memory")
; #define PG8_WAIT_L(n) asm volatile("s_waitcnt lgkmcnt(" #n ")" ::: "memory")
; #define PG8_BAR __builtin_amdgcn_s_barrier()
; #define PG8_SCHED __builtin_amdgcn_sched_barrier(0)
; template <class Epi, class Sched, bool ALIGN_EPI = false, bool SP2 = false>
; __device__ __forceinline__ void gemm_phase(PG8_LAS unsigned char* lds, const Gemm g, const Sched& S, const Epi& E, const int wv) {
;     ...
;         for (int t = 0; t < nt; t += 2) {
;             const bool last = (t == nt - 2);
;             const char* a1 = cA + (size_t)(t + 1) * kstep;
;             const char* a2 = last ? nA : cA + (size_t)(t + 2) * kstep; const char* b2 = last ? nB : cB + (size_t)(t + 2) * kstep;
;             const char* a3 = a2 + kstep; const char* b3 = b2 + kstep;
;     ...
;             PG8_LDA(At, 1, 1); PG8_STAGE(PG8_SB(1, 0), b3, voffB); PG8_STAGE(PG8_SB(1, 1), b3 + hstepB, voffB); PG8_STAGE(PG8_SA(1, 0), a3, voffA);
;             PG8_WAIT_V(8); PG8_WAIT_L(0); PG8_BAR; PG8_MMA(1, 0, At, B0); PG8_MMA(1, 1, At, B1); PG8_BAR; PG8_SCHED;
	s_add_i32 s30, s68, s47
	v_lshl_add_u64 v[190:191], v[190:191], 0, s[4:5]
	s_mov_b32 m0, s30
	ds_read_b128 v[162:165], v235 offset:49152
	ds_read_b128 v[166:169], v235 offset:50176
	ds_read_b128 v[170:173], v235 offset:51200
	ds_read_b128 v[174:177], v235 offset:52224
	ds_read_b128 v[178:181], v235 offset:53248
	ds_read_b128 v[182:185], v235 offset:54272
	ds_read_b128 v[204:207], v235 offset:55296
	ds_read_b128 v[208:211], v235 offset:56320
	global_load_lds_dwordx4 v[190:191], off
	v_lshl_add_u64 v[190:191], v[192:193], 0, s[4:5]
	s_add_i32 m0, s30, 0x2000
	s_add_i32 s30, s69, s47
	global_load_lds_dwordx4 v[190:191], off
	v_lshl_add_u64 v[190:191], v[212:213], 0, s[4:5]
	s_mov_b32 m0, s30
	s_nop 0
	global_load_lds_dwordx4 v[190:191], off
	v_lshl_add_u64 v[190:191], v[214:215], 0, s[4:5]
	s_add_i32 m0, s30, 0x2000
	s_nop 0
	global_load_lds_dwordx4 v[190:191], off
	v_lshl_add_u64 v[190:191], v[216:217], 0, s[4:5]
	s_mov_b32 m0, s57
	s_nop 0
	global_load_lds_dwordx4 v[190:191], off
	v_lshl_add_u64 v[190:191], v[218:219], 0, s[4:5]
	s_mov_b32 m0, s58
	s_nop 0
	global_load_lds_dwordx4 v[190:191], off
	s_waitcnt vmcnt(8)
	s_waitcnt lgkmcnt(0)
	s_barrier
	s_waitcnt lgkmcnt(0)
	v_mfma_f32_16x16x32_bf16 v[62:65], v[114:117], v[162:165], v[62:65]
	v_mfma_f32_16x16x32_bf16 v[58:61], v[138:141], v[162:165], v[58:61]
	v_mfma_f32_16x16x32_bf16 v[46:49], v[114:117], v[170:173], v[46:49]
	v_mfma_f32_16x16x32_bf16 v[42:45], v[138:141], v[170:173], v[42:45]
	v_mfma_f32_16x16x32_bf16 v[30:33], v[114:117], v[178:181], v[30:33]
	v_mfma_f32_16x16x32_bf16 v[26:29], v[138:141], v[178:181], v[26:29]
	v_mfma_f32_16x16x32_bf16 v[14:17], v[114:117], v[204:207], v[14:17]
	v_mfma_f32_16x16x32_bf16 v[10:13], v[138:141], v[204:207], v[10:13]
	v_mfma_f32_16x16x32_bf16 v[62:65], v[126:129], v[166:169], v[62:65]
	v_mfma_f32_16x16x32_bf16 v[58:61], v[142:145], v[166:169], v[58:61]
	v_mfma_f32_16x16x32_bf16 v[46:49], v[126:129], v[174:177], v[46:49]
	v_mfma_f32_16x16x32_bf16 v[42:45], v[142:145], v[174:177], v[42:45]
	v_mfma_f32_16x16x32_bf16 v[30:33], v[126:129], v[182:185], v[30:33]
	v_mfma_f32_16x16x32_bf16 v[26:29], v[142:145], v[182:185], v[26:29]
	v_mfma_f32_16x16x32_bf16 v[14:17], v[126:129], v[208:211], v[14:17]
	v_mfma_f32_16x16x32_bf16 v[10:13], v[142:145], v[208:211], v[10:13]
	v_mfma_f32_16x16x32_bf16 v[54:57], v[146:149], v[162:165], v[54:57]
	v_mfma_f32_16x16x32_bf16 v[50:53], v[154:157], v[162:165], v[50:53]
	v_mfma_f32_16x16x32_bf16 v[38:41], v[146:149], v[170:173], v[38:41]
	v_mfma_f32_16x16x32_bf16 v[34:37], v[154:157], v[170:173], v[34:37]
	v_mfma_f32_16x16x32_bf16 v[22:25], v[146:149], v[178:181], v[22:25]
	v_mfma_f32_16x16x32_bf16 v[18:21], v[154:157], v[178:181], v[18:21]
	v_mfma_f32_16x16x32_bf16 v[6:9], v[146:149], v[204:207], v[6:9]
	v_mfma_f32_16x16x32_bf16 v[2:5], v[154:157], v[204:207], v[2:5]
	v_mfma_f32_16x16x32_bf16 v[54:57], v[150:153], v[166:169], v[54:57]
	v_mfma_f32_16x16x32_bf16 v[50:53], v[158:161], v[166:169], v[50:53]
	v_mfma_f32_16x16x32_bf16 v[38:41], v[150:153], v[174:177], v[38:41]
	v_mfma_f32_16x16x32_bf16 v[34:37], v[158:161], v[174:177], v[34:37]
	v_mfma_f32_16x16x32_bf16 v[22:25], v[150:153], v[182:185], v[22:25]
	v_mfma_f32_16x16x32_bf16 v[18:21], v[158:161], v[182:185], v[18:21]
	v_mfma_f32_16x16x32_bf16 v[6:9], v[150:153], v[208:211], v[6:9]
	v_mfma_f32_16x16x32_bf16 v[2:5], v[158:161], v[208:211], v[2:5]
	s_barrier
	s_add_u32 s65, s65, 0x100
	s_addc_u32 s66, s66, 0
	s_cmp_ge_i32 s67, s56
	s_mov_b64 s[30:31], s[34:35]
	s_mov_b32 s44, s67
	s_cbranch_scc0 .LBB0_990
	s_movk_i32 s68, 0x4000
	s_movk_i32 s69, 0x6000
	s_mov_b32 s70, 0x18000
	s_mov_b32 s71, 0x3f317217
	v_readlane_b32 s67, v255, 30
	s_and_b64 vcc, exec, s[28:29]
	s_cbranch_vccz .LBB0_966

; #define PG8_STAGE(bufoff, gbase, voff) do { _Pragma("unroll") for (int _i = 0; _i < 2; ++_i) \
;         __builtin_amdgcn_global_load_lds((const unsigned*)((const char*)(gbase) + (voff)[_i]), (PG8_LAS unsigned*)(lds + (bufoff) + ldsw + _i * 8192), 16, 0, 0); } while (0)
; #define PG8_LDA(dst, b, h) do { _Pragma("unroll") for (int m = 0; m < 4; ++m) _Pragma("unroll") for (int k = 0; k < 2; ++k) dst[m][k] = *(const PG8_LAS bf16x8*)(lds + PG8_SA(b, h) + aoff + m * 2048 + k * 1024); } while (0)
; #define PG8_LDB(dst, b, h) do { _Pragma("unroll") for (int n = 0; n < 2; ++n) _Pragma("unroll") for (int k = 0; k < 2; ++k) dst[n][k] = *(const PG8_LAS bf16x8*)(lds + PG8_SB(b, h) + boff + n * 2048 + k * 1024); } while (0)
; #define PG8_MMA(ai, bj, At, Bt) do { __builtin_amdgcn_s_setprio(1); _Pragma("unroll") for (int m = 0; m < 4; ++m) _Pragma("unroll") for (int n = 0; n < 2; ++n) _Pragma("unroll") for (int k = 0; k < 2; ++k) \
;         acc[ai][bj][m][n] = __builtin_amdgcn_mfma_f32_16x16x32_bf16(Bt[n][k], At[m][k], acc[ai][bj][m][n], 0, 0, 0); __builtin_amdgcn_s_setprio(0); } while (0)
; #define PG8_WAIT_V(n) asm volatile("s_waitcnt vmcnt(" #n ")" ::: "memory")
; #define PG8_WAIT_L(n) asm volatile("s_waitcnt lgkmcnt(" #n ")" ::: "memory")
; #define PG8_BAR __builtin_amdgcn_s_barrier()
; template <class Epi, class Sched, bool ALIGN_EPI = false, bool SP2 = false>
; __device__ __forceinline__ void gemm_phase(PG8_LAS unsigned char* lds, const Gemm g, const Sched& S, const Epi& E, const int wv) {
;     ...
;         for (int t = 0; t < nt; t += 2) {
;             const bool last = (t == nt - 2);
;             const char* a1 = cA + (size_t)(t + 1) * kstep;
;             const char* a2 = last ? nA : cA + (size_t)(t + 2) * kstep; const char* b2 = last ? nB : cB + (size_t)(t + 2) * kstep;
;             const char* a3 = a2 + kstep; const char* b3 = b2 + kstep;
;             if (last && has_next) S.a_ready(nxt);
;             if constexpr (SP2) {
;             PG8_LDB(B0, 0, 0); PG8_LDB(B1, 0, 1); PG8_SCHED; PG8_LDA(At, 0, 0); PG8_STAGE(PG8_SA(1, 1), a1 + hstepA, voffA);
;             PG8_WAIT_V(8); PG8_WAIT_L(0); PG8_BAR; PG8_MMA(0, 0, At, B0); PG8_MMA(0, 1, At, B1); PG8_BAR; PG8_SCHED;
;             PG8_LDA(At, 0, 1); PG8_STAGE(PG8_SB(0, 0), b2, voffB); PG8_STAGE(PG8_SB(0, 1), b2 + hstepB, voffB); PG8_STAGE(PG8_SA(0, 0), a2, voffA);
.LBB0_1074:
	s_add_i32 s63, s30, 2
	s_add_u32 s64, s28, 0xfff80080
	s_addc_u32 s31, s29, -1
	s_add_i32 s66, 0, 0x10000
	s_cmp_eq_u32 s57, s30
	s_cselect_b32 s31, s17, s31
	s_cselect_b32 s30, s40, s64
	v_add_u32_e32 v0, s66, v157
	s_cselect_b32 s65, s19, s62
	s_cselect_b32 s64, s18, s41
	s_add_i32 s67, 0, 0x14000
	ds_read_b128 v[164:167], v0
	ds_read_b128 v[168:171], v0 offset:1024
	ds_read_b128 v[172:175], v0 offset:2048
	ds_read_b128 v[176:179], v0 offset:3072
	v_add_u32_e32 v0, s67, v157
	ds_read_b128 v[180:183], v0
	ds_read_b128 v[194:197], v0 offset:1024
	ds_read_b128 v[198:201], v0 offset:2048
	ds_read_b128 v[202:205], v0 offset:3072
	v_lshl_add_u64 v[150:151], s[28:29], 0, v[146:147]
	s_add_i32 m0, s47, 0xc000
	ds_read_b128 v[206:209], v163
	ds_read_b128 v[210:213], v163 offset:1024
	ds_read_b128 v[214:217], v163 offset:2048
	ds_read_b128 v[228:231], v163 offset:3072
	ds_read_b128 v[232:235], v163 offset:4096
	ds_read_b128 v[236:239], v163 offset:5120
	ds_read_b128 v[240:243], v163 offset:6144
	ds_read_b128 v[244:247], v163 offset:7168
	global_load_lds_dwordx4 v[150:151], off
	v_lshl_add_u64 v[150:151], s[28:29], 0, v[148:149]
	s_add_i32 m0, s47, 0xe000
	s_nop 0
	global_load_lds_dwordx4 v[150:151], off
	s_waitcnt vmcnt(8)
	s_waitcnt lgkmcnt(0)
	s_barrier
	s_waitcnt lgkmcnt(0)
	v_mfma_f32_16x16x32_bf16 v[130:133], v[164:167], v[206:209], v[130:133]
	v_mfma_f32_16x16x32_bf16 v[126:129], v[172:175], v[206:209], v[126:129]
	v_mfma_f32_16x16x32_bf16 v[114:117], v[164:167], v[214:217], v[114:117]
	v_mfma_f32_16x16x32_bf16 v[110:113], v[172:175], v[214:217], v[110:113]
	v_mfma_f32_16x16x32_bf16 v[98:101], v[164:167], v[232:235], v[98:101]
	v_mfma_f32_16x16x32_bf16 v[94:97], v[172:175], v[232:235], v[94:97]
	v_mfma_f32_16x16x32_bf16 v[82:85], v[164:167], v[240:243], v[82:85]
	v_mfma_f32_16x16x32_bf16 v[78:81], v[172:175], v[240:243], v[78:81]
	v_mfma_f32_16x16x32_bf16 v[130:133], v[168:171], v[210:213], v[130:133]
	v_mfma_f32_16x16x32_bf16 v[126:129], v[176:179], v[210:213], v[126:129]
	v_mfma_f32_16x16x32_bf16 v[114:117], v[168:171], v[228:231], v[114:117]
	v_mfma_f32_16x16x32_bf16 v[110:113], v[176:179], v[228:231], v[110:113]
	v_mfma_f32_16x16x32_bf16 v[98:101], v[168:171], v[236:239], v[98:101]
	v_mfma_f32_16x16x32_bf16 v[94:97], v[176:179], v[236:239], v[94:97]
	v_mfma_f32_16x16x32_bf16 v[82:85], v[168:171], v[244:247], v[82:85]
	v_mfma_f32_16x16x32_bf16 v[78:81], v[176:179], v[244:247], v[78:81]
	v_mfma_f32_16x16x32_bf16 v[122:125], v[180:183], v[206:209], v[122:125]
	v_mfma_f32_16x16x32_bf16 v[118:121], v[198:201], v[206:209], v[118:121]
	v_mfma_f32_16x16x32_bf16 v[106:109], v[180:183], v[214:217], v[106:109]
	v_mfma_f32_16x16x32_bf16 v[102:105], v[198:201], v[214:217], v[102:105]
	v_mfma_f32_16x16x32_bf16 v[90:93], v[180:183], v[232:235], v[90:93]
	v_mfma_f32_16x16x32_bf16 v[86:89], v[198:201], v[232:235], v[86:89]
	v_mfma_f32_16x16x32_bf16 v[74:77], v[180:183], v[240:243], v[74:77]
	v_mfma_f32_16x16x32_bf16 v[70:73], v[198:201], v[240:243], v[70:73]
	v_mfma_f32_16x16x32_bf16 v[122:125], v[194:197], v[210:213], v[122:125]
	v_mfma_f32_16x16x32_bf16 v[118:121], v[202:205], v[210:213], v[118:121]
	v_mfma_f32_16x16x32_bf16 v[106:109], v[194:197], v[228:231], v[106:109]
	v_mfma_f32_16x16x32_bf16 v[102:105], v[202:205], v[228:231], v[102:105]
	v_mfma_f32_16x16x32_bf16 v[90:93], v[194:197], v[236:239], v[90:93]
	v_mfma_f32_16x16x32_bf16 v[86:89], v[202:205], v[236:239], v[86:89]
	v_mfma_f32_16x16x32_bf16 v[74:77], v[194:197], v[244:247], v[74:77]
	v_mfma_f32_16x16x32_bf16 v[70:73], v[202:205], v[244:247], v[70:73]
	s_barrier
	s_add_i32 s66, s66, s45
	v_lshl_add_u64 v[150:151], s[64:65], 0, v[138:139]
	s_mov_b32 m0, s66
	ds_read_b128 v[206:209], v163 offset:16384
	ds_read_b128 v[210:213], v163 offset:17408
	ds_read_b128 v[214:217], v163 offset:18432
	ds_read_b128 v[228:231], v163 offset:19456
	ds_read_b128 v[232:235], v163 offset:20480
	ds_read_b128 v[236:239], v163 offset:21504
	ds_read_b128 v[240:243], v163 offset:22528
	ds_read_b128 v[244:247], v163 offset:23552
	global_load_lds_dwordx4 v[150:151], off
	s_add_i32 m0, s66, 0x2000
	v_lshl_add_u64 v[184:185], s[64:65], 0, v[134:135]
	s_add_u32 s64, s64, s0
	s_addc_u32 s65, s65, s1
	s_add_i32 s66, s67, s45
	global_load_lds_dwordx4 v[184:185], off
	v_lshl_add_u64 v[190:191], s[64:65], 0, v[138:139]
	s_mov_b32 m0, s66
	v_lshl_add_u64 v[192:193], s[64:65], 0, v[134:135]
	global_load_lds_dwordx4 v[190:191], off
	s_add_i32 m0, s66, 0x2000
	v_lshl_add_u64 v[218:219], s[30:31], 0, v[140:141]
	global_load_lds_dwordx4 v[192:193], off
	s_mov_b32 m0, s47
	v_lshl_add_u64 v[248:249], s[30:31], 0, v[136:137]
	global_load_lds_dwordx4 v[218:219], off
	s_mov_b32 m0, s48
	s_nop 0
	global_load_lds_dwordx4 v[248:249], off
	s_waitcnt vmcnt(8)
	s_waitcnt lgkmcnt(0)
	s_barrier
; #define PG8_STAGE(bufoff, gbase, voff) do { _Pragma("unroll") for (int _i = 0; _i < 2; ++_i) \
;         __builtin_amdgcn_global_load_lds((const unsigned*)((const char*)(gbase) + (voff)[_i]), (PG8_LAS unsigned*)(lds + (bufoff) + ldsw + _i * 8192), 16, 0, 0); } while (0)
; #define PG8_LDA(dst, b, h) do { _Pragma("unroll") for (int m = 0; m < 4; ++m) _Pragma("unroll") for (int k = 0; k < 2; ++k) dst[m][k] = *(const PG8_LAS bf16x8*)(lds + PG8_SA(b, h) + aoff + m * 2048 + k * 1024); } while (0)
; #define PG8_LDB(dst, b, h) do { _Pragma("unroll") for (int n = 0; n < 2; ++n) _Pragma("unroll") for (int k = 0; k < 2; ++k) dst[n][k] = *(const PG8_LAS bf16x8*)(lds + PG8_SB(b, h) + boff + n * 2048 + k * 1024); } while (0)
; #define PG8_MMA(ai, bj, At, Bt) do { __builtin_amdgcn_s_setprio(1); _Pragma("unroll") for (int m = 0; m < 4; ++m) _Pragma("unroll") for (int n = 0; n < 2; ++n) _Pragma("unroll") for (int k = 0; k < 2; ++k) \
;         acc[ai][bj][m][n] = __builtin_amdgcn_mfma_f32_16x16x32_bf16(Bt[n][k], At[m][k], acc[ai][bj][m][n], 0, 0, 0); __builtin_amdgcn_s_setprio(0); } while (0)
; #define PG8_WAIT_V(n) asm volatile("s_waitcnt vmcnt(" #n ")" ::: "memory")
; #define PG8_WAIT_L(n) asm volatile("s_waitcnt lgkmcnt(" #n ")" ::: "memory")
; #define PG8_BAR __builtin_amdgcn_s_barrier()
; #define PG8_SCHED __builtin_amdgcn_sched_barrier(0)
; template <class Epi, class Sched, bool ALIGN_EPI = false, bool SP2 = false>
; __device__ __forceinline__ void gemm_phase(PG8_LAS unsigned char* lds, const Gemm g, const Sched& S, const Epi& E, const int wv) {
;     ...
;             PG8_WAIT_V(8); PG8_WAIT_L(0); PG8_BAR; PG8_MMA(1, 0, At, B0); PG8_MMA(1, 1, At, B1); PG8_BAR; PG8_SCHED;
;             PG8_LDB(B0, 1, 0); PG8_LDB(B1, 1, 1); PG8_SCHED; PG8_LDA(At, 1, 0); PG8_STAGE(PG8_SA(0, 1), a2 + hstepA, voffA);
;             PG8_WAIT_V(8); PG8_WAIT_L(0); PG8_BAR; PG8_MMA(0, 0, At, B0); PG8_MMA(0, 1, At, B1); PG8_BAR; PG8_SCHED;
	s_waitcnt lgkmcnt(0)
	v_mfma_f32_16x16x32_bf16 v[66:69], v[164:167], v[206:209], v[66:69]
	v_mfma_f32_16x16x32_bf16 v[62:65], v[172:175], v[206:209], v[62:65]
	v_mfma_f32_16x16x32_bf16 v[50:53], v[164:167], v[214:217], v[50:53]
	v_mfma_f32_16x16x32_bf16 v[46:49], v[172:175], v[214:217], v[46:49]
	v_mfma_f32_16x16x32_bf16 v[34:37], v[164:167], v[232:235], v[34:37]
	v_mfma_f32_16x16x32_bf16 v[30:33], v[172:175], v[232:235], v[30:33]
	v_mfma_f32_16x16x32_bf16 v[18:21], v[164:167], v[240:243], v[18:21]
	v_mfma_f32_16x16x32_bf16 v[14:17], v[172:175], v[240:243], v[14:17]
	v_mfma_f32_16x16x32_bf16 v[66:69], v[168:171], v[210:213], v[66:69]
	v_mfma_f32_16x16x32_bf16 v[62:65], v[176:179], v[210:213], v[62:65]
	v_mfma_f32_16x16x32_bf16 v[50:53], v[168:171], v[228:231], v[50:53]
	v_mfma_f32_16x16x32_bf16 v[46:49], v[176:179], v[228:231], v[46:49]
	v_mfma_f32_16x16x32_bf16 v[34:37], v[168:171], v[236:239], v[34:37]
	v_mfma_f32_16x16x32_bf16 v[30:33], v[176:179], v[236:239], v[30:33]
	v_mfma_f32_16x16x32_bf16 v[18:21], v[168:171], v[244:247], v[18:21]
	v_mfma_f32_16x16x32_bf16 v[14:17], v[176:179], v[244:247], v[14:17]
	v_mfma_f32_16x16x32_bf16 v[58:61], v[180:183], v[206:209], v[58:61]
	v_mfma_f32_16x16x32_bf16 v[54:57], v[198:201], v[206:209], v[54:57]
	v_mfma_f32_16x16x32_bf16 v[42:45], v[180:183], v[214:217], v[42:45]
	v_mfma_f32_16x16x32_bf16 v[38:41], v[198:201], v[214:217], v[38:41]
	v_mfma_f32_16x16x32_bf16 v[26:29], v[180:183], v[232:235], v[26:29]
	v_mfma_f32_16x16x32_bf16 v[22:25], v[198:201], v[232:235], v[22:25]
	v_mfma_f32_16x16x32_bf16 v[10:13], v[180:183], v[240:243], v[10:13]
	v_mfma_f32_16x16x32_bf16 v[6:9], v[198:201], v[240:243], v[6:9]
	v_mfma_f32_16x16x32_bf16 v[58:61], v[194:197], v[210:213], v[58:61]
	v_mfma_f32_16x16x32_bf16 v[54:57], v[202:205], v[210:213], v[54:57]
	v_mfma_f32_16x16x32_bf16 v[42:45], v[194:197], v[228:231], v[42:45]
	v_mfma_f32_16x16x32_bf16 v[38:41], v[202:205], v[228:231], v[38:41]
	v_mfma_f32_16x16x32_bf16 v[26:29], v[194:197], v[236:239], v[26:29]
	v_mfma_f32_16x16x32_bf16 v[22:25], v[202:205], v[236:239], v[22:25]
	v_mfma_f32_16x16x32_bf16 v[10:13], v[194:197], v[244:247], v[10:13]
	v_mfma_f32_16x16x32_bf16 v[6:9], v[202:205], v[244:247], v[6:9]
	s_barrier
	s_add_i32 s64, 0, 0x18000
	v_add_u32_e32 v0, s64, v157
	s_add_i32 s65, 0, 0x1c000
	ds_read_b128 v[164:167], v0
	ds_read_b128 v[168:171], v0 offset:1024
	ds_read_b128 v[172:175], v0 offset:2048
	ds_read_b128 v[176:179], v0 offset:3072
	v_add_u32_e32 v0, s65, v157
	ds_read_b128 v[180:183], v0
	ds_read_b128 v[194:197], v0 offset:1024
	ds_read_b128 v[198:201], v0 offset:2048
	ds_read_b128 v[202:205], v0 offset:3072
	s_add_u32 s30, s30, 0x80000
	s_addc_u32 s31, s31, 0
	s_mov_b32 m0, s49
	v_lshl_add_u64 v[250:251], s[30:31], 0, v[140:141]
	ds_read_b128 v[206:209], v163 offset:32768
	ds_read_b128 v[210:213], v163 offset:33792
	ds_read_b128 v[214:217], v163 offset:34816
	ds_read_b128 v[228:231], v163 offset:35840
	ds_read_b128 v[232:235], v163 offset:36864
	ds_read_b128 v[236:239], v163 offset:37888
	ds_read_b128 v[240:243], v163 offset:38912
	ds_read_b128 v[244:247], v163 offset:39936
	global_load_lds_dwordx4 v[250:251], off
	v_lshl_add_u64 v[250:251], s[30:31], 0, v[136:137]
	s_mov_b32 m0, s50
	s_nop 0
	global_load_lds_dwordx4 v[250:251], off
	s_waitcnt vmcnt(8)
	s_waitcnt lgkmcnt(0)
	s_barrier
	s_waitcnt lgkmcnt(0)
	v_mfma_f32_16x16x32_bf16 v[130:133], v[164:167], v[206:209], v[130:133]
	v_mfma_f32_16x16x32_bf16 v[126:129], v[172:175], v[206:209], v[126:129]
	v_mfma_f32_16x16x32_bf16 v[114:117], v[164:167], v[214:217], v[114:117]
	v_mfma_f32_16x16x32_bf16 v[110:113], v[172:175], v[214:217], v[110:113]
	v_mfma_f32_16x16x32_bf16 v[98:101], v[164:167], v[232:235], v[98:101]
	v_mfma_f32_16x16x32_bf16 v[94:97], v[172:175], v[232:235], v[94:97]
	v_mfma_f32_16x16x32_bf16 v[82:85], v[164:167], v[240:243], v[82:85]
	v_mfma_f32_16x16x32_bf16 v[78:81], v[172:175], v[240:243], v[78:81]
	v_mfma_f32_16x16x32_bf16 v[130:133], v[168:171], v[210:213], v[130:133]
	v_mfma_f32_16x16x32_bf16 v[126:129], v[176:179], v[210:213], v[126:129]
	v_mfma_f32_16x16x32_bf16 v[114:117], v[168:171], v[228:231], v[114:117]
	v_mfma_f32_16x16x32_bf16 v[110:113], v[176:179], v[228:231], v[110:113]
	v_mfma_f32_16x16x32_bf16 v[98:101], v[168:171], v[236:239], v[98:101]
	v_mfma_f32_16x16x32_bf16 v[94:97], v[176:179], v[236:239], v[94:97]
	v_mfma_f32_16x16x32_bf16 v[82:85], v[168:171], v[244:247], v[82:85]
	v_mfma_f32_16x16x32_bf16 v[78:81], v[176:179], v[244:247], v[78:81]
	v_mfma_f32_16x16x32_bf16 v[122:125], v[180:183], v[206:209], v[122:125]
	v_mfma_f32_16x16x32_bf16 v[118:121], v[198:201], v[206:209], v[118:121]
	v_mfma_f32_16x16x32_bf16 v[106:109], v[180:183], v[214:217], v[106:109]
	v_mfma_f32_16x16x32_bf16 v[102:105], v[198:201], v[214:217], v[102:105]
	v_mfma_f32_16x16x32_bf16 v[90:93], v[180:183], v[232:235], v[90:93]
	v_mfma_f32_16x16x32_bf16 v[86:89], v[198:201], v[232:235], v[86:89]
	v_mfma_f32_16x16x32_bf16 v[74:77], v[180:183], v[240:243], v[74:77]
	v_mfma_f32_16x16x32_bf16 v[70:73], v[198:201], v[240:243], v[70:73]
	v_mfma_f32_16x16x32_bf16 v[122:125], v[194:197], v[210:213], v[122:125]
	v_mfma_f32_16x16x32_bf16 v[118:121], v[202:205], v[210:213], v[118:121]
	v_mfma_f32_16x16x32_bf16 v[106:109], v[194:197], v[228:231], v[106:109]
	v_mfma_f32_16x16x32_bf16 v[102:105], v[202:205], v[228:231], v[102:105]
	v_mfma_f32_16x16x32_bf16 v[90:93], v[194:197], v[236:239], v[90:93]
	v_mfma_f32_16x16x32_bf16 v[86:89], v[202:205], v[236:239], v[86:89]
	v_mfma_f32_16x16x32_bf16 v[74:77], v[194:197], v[244:247], v[74:77]
	v_mfma_f32_16x16x32_bf16 v[70:73], v[202:205], v[244:247], v[70:73]
	s_barrier
; #define PG8_STAGE(bufoff, gbase, voff) do { _Pragma("unroll") for (int _i = 0; _i < 2; ++_i) \
;         __builtin_amdgcn_global_load_lds((const unsigned*)((const char*)(gbase) + (voff)[_i]), (PG8_LAS unsigned*)(lds + (bufoff) + ldsw + _i * 8192), 16, 0, 0); } while (0)
; #define PG8_LDA(dst, b, h) do { _Pragma("unroll") for (int m = 0; m < 4; ++m) _Pragma("unroll") for (int k = 0; k < 2; ++k) dst[m][k] = *(const PG8_LAS bf16x8*)(lds + PG8_SA(b, h) + aoff + m * 2048 + k * 1024); } while (0)
; #define PG8_MMA(ai, bj, At, Bt) do { __builtin_amdgcn_s_setprio(1); _Pragma("unroll") for (int m = 0; m < 4; ++m) _Pragma("unroll") for (int n = 0; n < 2; ++n) _Pragma("unroll") for (int k = 0; k < 2; ++k) \
;         acc[ai][bj][m][n] = __builtin_amdgcn_mfma_f32_16x16x32_bf16(Bt[n][k], At[m][k], acc[ai][bj][m][n], 0, 0, 0); __builtin_amdgcn_s_setprio(0); } while (0)
; #define PG8_WAIT_V(n) asm volatile("s_waitcnt vmcnt(" #n ")" ::: "memory")
; #define PG8_WAIT_L(n) asm volatile("s_waitcnt lgkmcnt(" #n ")" ::: "memory")
; #define PG8_BAR __builtin_amdgcn_s_barrier()
; #define PG8_SCHED __builtin_amdgcn_sched_barrier(0)
; template <class Epi, class Sched, bool ALIGN_EPI = false, bool SP2 = false>
; __device__ __forceinline__ void gemm_phase(PG8_LAS unsigned char* lds, const Gemm g, const Sched& S, const Epi& E, const int wv) {
;     ...
;         for (int t = 0; t < nt; t += 2) {
;             const bool last = (t == nt - 2);
;             const char* a1 = cA + (size_t)(t + 1) * kstep;
;             const char* a2 = last ? nA : cA + (size_t)(t + 2) * kstep; const char* b2 = last ? nB : cB + (size_t)(t + 2) * kstep;
;     ...
;             PG8_LDA(At, 1, 1); PG8_STAGE(PG8_SB(1, 0), b3, voffB); PG8_STAGE(PG8_SB(1, 1), b3 + hstepB, voffB); PG8_STAGE(PG8_SA(1, 0), a3, voffA);
;             PG8_WAIT_V(8); PG8_WAIT_L(0); PG8_BAR; PG8_MMA(1, 0, At, B0); PG8_MMA(1, 1, At, B1); PG8_BAR; PG8_SCHED;
	s_add_i32 s30, s64, s45
	v_lshl_add_u64 v[150:151], v[150:151], 0, s[4:5]
	s_mov_b32 m0, s30
	ds_read_b128 v[206:209], v163 offset:49152
	ds_read_b128 v[210:213], v163 offset:50176
	ds_read_b128 v[214:217], v163 offset:51200
	ds_read_b128 v[228:231], v163 offset:52224
	ds_read_b128 v[232:235], v163 offset:53248
	ds_read_b128 v[236:239], v163 offset:54272
	ds_read_b128 v[240:243], v163 offset:55296
	ds_read_b128 v[244:247], v163 offset:56320
	global_load_lds_dwordx4 v[150:151], off
	v_lshl_add_u64 v[150:151], v[184:185], 0, s[4:5]
	s_add_i32 m0, s30, 0x2000
	s_add_i32 s30, s65, s45
	global_load_lds_dwordx4 v[150:151], off
	v_lshl_add_u64 v[150:151], v[190:191], 0, s[4:5]
	s_mov_b32 m0, s30
	s_nop 0
	global_load_lds_dwordx4 v[150:151], off
	v_lshl_add_u64 v[150:151], v[192:193], 0, s[4:5]
	s_add_i32 m0, s30, 0x2000
	s_nop 0
	global_load_lds_dwordx4 v[150:151], off
	v_lshl_add_u64 v[150:151], v[218:219], 0, s[4:5]
	s_mov_b32 m0, s53
	s_nop 0
	global_load_lds_dwordx4 v[150:151], off
	v_lshl_add_u64 v[150:151], v[248:249], 0, s[4:5]
	s_mov_b32 m0, s54
	s_nop 0
	global_load_lds_dwordx4 v[150:151], off
	s_waitcnt vmcnt(8)
	s_waitcnt lgkmcnt(0)
	s_barrier
	s_waitcnt lgkmcnt(0)
	v_mfma_f32_16x16x32_bf16 v[66:69], v[164:167], v[206:209], v[66:69]
	v_mfma_f32_16x16x32_bf16 v[62:65], v[172:175], v[206:209], v[62:65]
	v_mfma_f32_16x16x32_bf16 v[50:53], v[164:167], v[214:217], v[50:53]
	v_mfma_f32_16x16x32_bf16 v[46:49], v[172:175], v[214:217], v[46:49]
	v_mfma_f32_16x16x32_bf16 v[34:37], v[164:167], v[232:235], v[34:37]
	v_mfma_f32_16x16x32_bf16 v[30:33], v[172:175], v[232:235], v[30:33]
	v_mfma_f32_16x16x32_bf16 v[18:21], v[164:167], v[240:243], v[18:21]
	v_mfma_f32_16x16x32_bf16 v[14:17], v[172:175], v[240:243], v[14:17]
	v_mfma_f32_16x16x32_bf16 v[66:69], v[168:171], v[210:213], v[66:69]
	v_mfma_f32_16x16x32_bf16 v[62:65], v[176:179], v[210:213], v[62:65]
	v_mfma_f32_16x16x32_bf16 v[50:53], v[168:171], v[228:231], v[50:53]
	v_mfma_f32_16x16x32_bf16 v[46:49], v[176:179], v[228:231], v[46:49]
	v_mfma_f32_16x16x32_bf16 v[34:37], v[168:171], v[236:239], v[34:37]
	v_mfma_f32_16x16x32_bf16 v[30:33], v[176:179], v[236:239], v[30:33]
	v_mfma_f32_16x16x32_bf16 v[18:21], v[168:171], v[244:247], v[18:21]
	v_mfma_f32_16x16x32_bf16 v[14:17], v[176:179], v[244:247], v[14:17]
	v_mfma_f32_16x16x32_bf16 v[58:61], v[180:183], v[206:209], v[58:61]
	v_mfma_f32_16x16x32_bf16 v[54:57], v[198:201], v[206:209], v[54:57]
	v_mfma_f32_16x16x32_bf16 v[42:45], v[180:183], v[214:217], v[42:45]
	v_mfma_f32_16x16x32_bf16 v[38:41], v[198:201], v[214:217], v[38:41]
	v_mfma_f32_16x16x32_bf16 v[26:29], v[180:183], v[232:235], v[26:29]
	v_mfma_f32_16x16x32_bf16 v[22:25], v[198:201], v[232:235], v[22:25]
	v_mfma_f32_16x16x32_bf16 v[10:13], v[180:183], v[240:243], v[10:13]
	v_mfma_f32_16x16x32_bf16 v[6:9], v[198:201], v[240:243], v[6:9]
	v_mfma_f32_16x16x32_bf16 v[58:61], v[194:197], v[210:213], v[58:61]
	v_mfma_f32_16x16x32_bf16 v[54:57], v[202:205], v[210:213], v[54:57]
	v_mfma_f32_16x16x32_bf16 v[42:45], v[194:197], v[228:231], v[42:45]
	v_mfma_f32_16x16x32_bf16 v[38:41], v[202:205], v[228:231], v[38:41]
	v_mfma_f32_16x16x32_bf16 v[26:29], v[194:197], v[236:239], v[26:29]
	v_mfma_f32_16x16x32_bf16 v[22:25], v[202:205], v[236:239], v[22:25]
	v_mfma_f32_16x16x32_bf16 v[10:13], v[194:197], v[244:247], v[10:13]
	v_mfma_f32_16x16x32_bf16 v[6:9], v[202:205], v[244:247], v[6:9]
	s_barrier
	s_add_u32 s28, s28, 0x100
	s_addc_u32 s29, s29, 0
	s_add_u32 s41, s41, 0x100
	s_addc_u32 s62, s62, 0
	s_cmp_ge_i32 s63, s55
	s_mov_b32 s30, s63
	s_cbranch_scc0 .LBB0_1074
	v_readlane_b32 s67, v255, 30

; #define PG8_STAGE(bufoff, gbase, voff) do { _Pragma("unroll") for (int _i = 0; _i < 2; ++_i) \
;         __builtin_amdgcn_global_load_lds((const unsigned*)((const char*)(gbase) + (voff)[_i]), (PG8_LAS unsigned*)(lds + (bufoff) + ldsw + _i * 8192), 16, 0, 0); } while (0)
; #define PG8_LDA(dst, b, h) do { _Pragma("unroll") for (int m = 0; m < 4; ++m) _Pragma("unroll") for (int k = 0; k < 2; ++k) dst[m][k] = *(const PG8_LAS bf16x8*)(lds + PG8_SA(b, h) + aoff + m * 2048 + k * 1024); } while (0)
; #define PG8_LDB(dst, b, h) do { _Pragma("unroll") for (int n = 0; n < 2; ++n) _Pragma("unroll") for (int k = 0; k < 2; ++k) dst[n][k] = *(const PG8_LAS bf16x8*)(lds + PG8_SB(b, h) + boff + n * 2048 + k * 1024); } while (0)
; #define PG8_MMA(ai, bj, At, Bt) do { __builtin_amdgcn_s_setprio(1); _Pragma("unroll") for (int m = 0; m < 4; ++m) _Pragma("unroll") for (int n = 0; n < 2; ++n) _Pragma("unroll") for (int k = 0; k < 2; ++k) \
;         acc[ai][bj][m][n] = __builtin_amdgcn_mfma_f32_16x16x32_bf16(Bt[n][k], At[m][k], acc[ai][bj][m][n], 0, 0, 0); __builtin_amdgcn_s_setprio(0); } while (0)
; #define PG8_WAIT_V(n) asm volatile("s_waitcnt vmcnt(" #n ")" ::: "memory")
; #define PG8_WAIT_L(n) asm volatile("s_waitcnt lgkmcnt(" #n ")" ::: "memory")
; #define PG8_BAR __builtin_amdgcn_s_barrier()
; template <class Epi, class Sched, bool ALIGN_EPI = false, bool SP2 = false>
; __device__ __forceinline__ void gemm_phase(PG8_LAS unsigned char* lds, const Gemm g, const Sched& S, const Epi& E, const int wv) {
;     ...
;         for (int t = 0; t < nt; t += 2) {
;             const bool last = (t == nt - 2);
;             const char* a1 = cA + (size_t)(t + 1) * kstep;
;             const char* a2 = last ? nA : cA + (size_t)(t + 2) * kstep; const char* b2 = last ? nB : cB + (size_t)(t + 2) * kstep;
;             const char* a3 = a2 + kstep; const char* b3 = b2 + kstep;
;             if (last && has_next) S.a_ready(nxt);
;             if constexpr (SP2) {
;             PG8_LDB(B0, 0, 0); PG8_LDB(B1, 0, 1); PG8_SCHED; PG8_LDA(At, 0, 0); PG8_STAGE(PG8_SA(1, 1), a1 + hstepA, voffA);
;             PG8_WAIT_V(8); PG8_WAIT_L(0); PG8_BAR; PG8_MMA(0, 0, At, B0); PG8_MMA(0, 1, At, B1); PG8_BAR; PG8_SCHED;
;             PG8_LDA(At, 0, 1); PG8_STAGE(PG8_SB(0, 0), b2, voffB); PG8_STAGE(PG8_SB(0, 1), b2 + hstepB, voffB); PG8_STAGE(PG8_SA(0, 0), a2, voffA);
.LBB0_1385:
	s_add_i32 s70, s52, 2
	s_add_u32 s71, s44, 0xfffc0080
	s_addc_u32 s53, s45, -1
	s_add_i32 s74, 0, 0x10000
	s_cmp_eq_u32 s65, s52
	s_cselect_b32 s53, s13, s53
	s_cselect_b32 s52, s19, s71
	s_cselect_b32 s73, s15, s55
	s_cselect_b32 s72, s14, s54
	s_add_i32 s71, 0, 0x14000
	v_add_u32_e32 v142, s74, v230
	v_add_u32_e32 v158, s71, v230
	ds_read_b128 v[114:117], v142
	ds_read_b128 v[126:129], v142 offset:1024
	ds_read_b128 v[138:141], v142 offset:2048
	ds_read_b128 v[142:145], v142 offset:3072
	ds_read_b128 v[146:149], v158
	ds_read_b128 v[150:153], v158 offset:1024
	ds_read_b128 v[154:157], v158 offset:2048
	ds_read_b128 v[158:161], v158 offset:3072
	v_lshl_add_u64 v[190:191], s[44:45], 0, v[200:201]
	s_add_i32 m0, s51, 0xc000
	ds_read_b128 v[162:165], v235
	ds_read_b128 v[166:169], v235 offset:1024
	ds_read_b128 v[170:173], v235 offset:2048
	ds_read_b128 v[174:177], v235 offset:3072
	ds_read_b128 v[178:181], v235 offset:4096
	ds_read_b128 v[182:185], v235 offset:5120
	ds_read_b128 v[204:207], v235 offset:6144
	ds_read_b128 v[208:211], v235 offset:7168
	global_load_lds_dwordx4 v[190:191], off
	v_lshl_add_u64 v[190:191], s[44:45], 0, v[202:203]
	s_add_i32 m0, s51, 0xe000
	s_nop 0
	global_load_lds_dwordx4 v[190:191], off
	s_waitcnt vmcnt(8)
	s_waitcnt lgkmcnt(0)
	s_barrier
	s_waitcnt lgkmcnt(0)
	v_mfma_f32_16x16x32_bf16 v[134:137], v[114:117], v[162:165], v[134:137]
	v_mfma_f32_16x16x32_bf16 v[130:133], v[138:141], v[162:165], v[130:133]
	v_mfma_f32_16x16x32_bf16 v[110:113], v[114:117], v[170:173], v[110:113]
	v_mfma_f32_16x16x32_bf16 v[106:109], v[138:141], v[170:173], v[106:109]
	v_mfma_f32_16x16x32_bf16 v[94:97], v[114:117], v[178:181], v[94:97]
	v_mfma_f32_16x16x32_bf16 v[90:93], v[138:141], v[178:181], v[90:93]
	v_mfma_f32_16x16x32_bf16 v[78:81], v[114:117], v[204:207], v[78:81]
	v_mfma_f32_16x16x32_bf16 v[74:77], v[138:141], v[204:207], v[74:77]
	v_mfma_f32_16x16x32_bf16 v[134:137], v[126:129], v[166:169], v[134:137]
	v_mfma_f32_16x16x32_bf16 v[130:133], v[142:145], v[166:169], v[130:133]
	v_mfma_f32_16x16x32_bf16 v[110:113], v[126:129], v[174:177], v[110:113]
	v_mfma_f32_16x16x32_bf16 v[106:109], v[142:145], v[174:177], v[106:109]
	v_mfma_f32_16x16x32_bf16 v[94:97], v[126:129], v[182:185], v[94:97]
	v_mfma_f32_16x16x32_bf16 v[90:93], v[142:145], v[182:185], v[90:93]
	v_mfma_f32_16x16x32_bf16 v[78:81], v[126:129], v[208:211], v[78:81]
	v_mfma_f32_16x16x32_bf16 v[74:77], v[142:145], v[208:211], v[74:77]
	v_mfma_f32_16x16x32_bf16 v[122:125], v[146:149], v[162:165], v[122:125]
	v_mfma_f32_16x16x32_bf16 v[118:121], v[154:157], v[162:165], v[118:121]
	v_mfma_f32_16x16x32_bf16 v[102:105], v[146:149], v[170:173], v[102:105]
	v_mfma_f32_16x16x32_bf16 v[98:101], v[154:157], v[170:173], v[98:101]
	v_mfma_f32_16x16x32_bf16 v[86:89], v[146:149], v[178:181], v[86:89]
	v_mfma_f32_16x16x32_bf16 v[82:85], v[154:157], v[178:181], v[82:85]
	v_mfma_f32_16x16x32_bf16 v[70:73], v[146:149], v[204:207], v[70:73]
	v_mfma_f32_16x16x32_bf16 v[66:69], v[154:157], v[204:207], v[66:69]
	v_mfma_f32_16x16x32_bf16 v[122:125], v[150:153], v[166:169], v[122:125]
	v_mfma_f32_16x16x32_bf16 v[118:121], v[158:161], v[166:169], v[118:121]
	v_mfma_f32_16x16x32_bf16 v[102:105], v[150:153], v[174:177], v[102:105]
	v_mfma_f32_16x16x32_bf16 v[98:101], v[158:161], v[174:177], v[98:101]
	v_mfma_f32_16x16x32_bf16 v[86:89], v[150:153], v[182:185], v[86:89]
	v_mfma_f32_16x16x32_bf16 v[82:85], v[158:161], v[182:185], v[82:85]
	v_mfma_f32_16x16x32_bf16 v[70:73], v[150:153], v[208:211], v[70:73]
	v_mfma_f32_16x16x32_bf16 v[66:69], v[158:161], v[208:211], v[66:69]
	s_barrier
	s_add_i32 s74, s74, s3
	v_lshl_add_u64 v[190:191], s[72:73], 0, v[0:1]
	s_mov_b32 m0, s74
	ds_read_b128 v[162:165], v235 offset:16384
	ds_read_b128 v[166:169], v235 offset:17408
	ds_read_b128 v[170:173], v235 offset:18432
	ds_read_b128 v[174:177], v235 offset:19456
	ds_read_b128 v[178:181], v235 offset:20480
	ds_read_b128 v[182:185], v235 offset:21504
	ds_read_b128 v[204:207], v235 offset:22528
	ds_read_b128 v[208:211], v235 offset:23552
	global_load_lds_dwordx4 v[190:191], off
	s_add_i32 m0, s74, 0x2000
	v_lshl_add_u64 v[192:193], s[72:73], 0, v[198:199]
	s_add_u32 s72, s72, s24
	s_addc_u32 s73, s73, s25
	s_add_i32 s71, s71, s3
	global_load_lds_dwordx4 v[192:193], off
	v_lshl_add_u64 v[212:213], s[72:73], 0, v[0:1]
	s_mov_b32 m0, s71
	v_lshl_add_u64 v[214:215], s[72:73], 0, v[198:199]
	global_load_lds_dwordx4 v[212:213], off
	s_add_i32 m0, s71, 0x2000
	v_lshl_add_u64 v[216:217], s[52:53], 0, v[194:195]
	global_load_lds_dwordx4 v[214:215], off
	s_mov_b32 m0, s51
	v_lshl_add_u64 v[218:219], s[52:53], 0, v[196:197]
	global_load_lds_dwordx4 v[216:217], off
	s_mov_b32 m0, s59
	s_nop 0
	global_load_lds_dwordx4 v[218:219], off
	s_waitcnt vmcnt(8)
	s_waitcnt lgkmcnt(0)
	s_barrier
; #define PG8_STAGE(bufoff, gbase, voff) do { _Pragma("unroll") for (int _i = 0; _i < 2; ++_i) \
;         __builtin_amdgcn_global_load_lds((const unsigned*)((const char*)(gbase) + (voff)[_i]), (PG8_LAS unsigned*)(lds + (bufoff) + ldsw + _i * 8192), 16, 0, 0); } while (0)
; #define PG8_LDA(dst, b, h) do { _Pragma("unroll") for (int m = 0; m < 4; ++m) _Pragma("unroll") for (int k = 0; k < 2; ++k) dst[m][k] = *(const PG8_LAS bf16x8*)(lds + PG8_SA(b, h) + aoff + m * 2048 + k * 1024); } while (0)
; #define PG8_LDB(dst, b, h) do { _Pragma("unroll") for (int n = 0; n < 2; ++n) _Pragma("unroll") for (int k = 0; k < 2; ++k) dst[n][k] = *(const PG8_LAS bf16x8*)(lds + PG8_SB(b, h) + boff + n * 2048 + k * 1024); } while (0)
; #define PG8_MMA(ai, bj, At, Bt) do { __builtin_amdgcn_s_setprio(1); _Pragma("unroll") for (int m = 0; m < 4; ++m) _Pragma("unroll") for (int n = 0; n < 2; ++n) _Pragma("unroll") for (int k = 0; k < 2; ++k) \
;         acc[ai][bj][m][n] = __builtin_amdgcn_mfma_f32_16x16x32_bf16(Bt[n][k], At[m][k], acc[ai][bj][m][n], 0, 0, 0); __builtin_amdgcn_s_setprio(0); } while (0)
; #define PG8_WAIT_V(n) asm volatile("s_waitcnt vmcnt(" #n ")" ::: "memory")
; #define PG8_WAIT_L(n) asm volatile("s_waitcnt lgkmcnt(" #n ")" ::: "memory")
; #define PG8_BAR __builtin_amdgcn_s_barrier()
; #define PG8_SCHED __builtin_amdgcn_sched_barrier(0)
; template <class Epi, class Sched, bool ALIGN_EPI = false, bool SP2 = false>
; __device__ __forceinline__ void gemm_phase(PG8_LAS unsigned char* lds, const Gemm g, const Sched& S, const Epi& E, const int wv) {
;     ...
;             PG8_WAIT_V(8); PG8_WAIT_L(0); PG8_BAR; PG8_MMA(1, 0, At, B0); PG8_MMA(1, 1, At, B1); PG8_BAR; PG8_SCHED;
;             PG8_LDB(B0, 1, 0); PG8_LDB(B1, 1, 1); PG8_SCHED; PG8_LDA(At, 1, 0); PG8_STAGE(PG8_SA(0, 1), a2 + hstepA, voffA);
;             PG8_WAIT_V(8); PG8_WAIT_L(0); PG8_BAR; PG8_MMA(0, 0, At, B0); PG8_MMA(0, 1, At, B1); PG8_BAR; PG8_SCHED;
	s_waitcnt lgkmcnt(0)
	v_mfma_f32_16x16x32_bf16 v[62:65], v[114:117], v[162:165], v[62:65]
	v_mfma_f32_16x16x32_bf16 v[58:61], v[138:141], v[162:165], v[58:61]
	v_mfma_f32_16x16x32_bf16 v[46:49], v[114:117], v[170:173], v[46:49]
	v_mfma_f32_16x16x32_bf16 v[42:45], v[138:141], v[170:173], v[42:45]
	v_mfma_f32_16x16x32_bf16 v[30:33], v[114:117], v[178:181], v[30:33]
	v_mfma_f32_16x16x32_bf16 v[26:29], v[138:141], v[178:181], v[26:29]
	v_mfma_f32_16x16x32_bf16 v[14:17], v[114:117], v[204:207], v[14:17]
	v_mfma_f32_16x16x32_bf16 v[10:13], v[138:141], v[204:207], v[10:13]
	v_mfma_f32_16x16x32_bf16 v[62:65], v[126:129], v[166:169], v[62:65]
	v_mfma_f32_16x16x32_bf16 v[58:61], v[142:145], v[166:169], v[58:61]
	v_mfma_f32_16x16x32_bf16 v[46:49], v[126:129], v[174:177], v[46:49]
	v_mfma_f32_16x16x32_bf16 v[42:45], v[142:145], v[174:177], v[42:45]
	v_mfma_f32_16x16x32_bf16 v[30:33], v[126:129], v[182:185], v[30:33]
	v_mfma_f32_16x16x32_bf16 v[26:29], v[142:145], v[182:185], v[26:29]
	v_mfma_f32_16x16x32_bf16 v[14:17], v[126:129], v[208:211], v[14:17]
	v_mfma_f32_16x16x32_bf16 v[10:13], v[142:145], v[208:211], v[10:13]
	v_mfma_f32_16x16x32_bf16 v[54:57], v[146:149], v[162:165], v[54:57]
	v_mfma_f32_16x16x32_bf16 v[50:53], v[154:157], v[162:165], v[50:53]
	v_mfma_f32_16x16x32_bf16 v[38:41], v[146:149], v[170:173], v[38:41]
	v_mfma_f32_16x16x32_bf16 v[34:37], v[154:157], v[170:173], v[34:37]
	v_mfma_f32_16x16x32_bf16 v[22:25], v[146:149], v[178:181], v[22:25]
	v_mfma_f32_16x16x32_bf16 v[18:21], v[154:157], v[178:181], v[18:21]
	v_mfma_f32_16x16x32_bf16 v[6:9], v[146:149], v[204:207], v[6:9]
	v_mfma_f32_16x16x32_bf16 v[2:5], v[154:157], v[204:207], v[2:5]
	v_mfma_f32_16x16x32_bf16 v[54:57], v[150:153], v[166:169], v[54:57]
	v_mfma_f32_16x16x32_bf16 v[50:53], v[158:161], v[166:169], v[50:53]
	v_mfma_f32_16x16x32_bf16 v[38:41], v[150:153], v[174:177], v[38:41]
	v_mfma_f32_16x16x32_bf16 v[34:37], v[158:161], v[174:177], v[34:37]
	v_mfma_f32_16x16x32_bf16 v[22:25], v[150:153], v[182:185], v[22:25]
	v_mfma_f32_16x16x32_bf16 v[18:21], v[158:161], v[182:185], v[18:21]
	v_mfma_f32_16x16x32_bf16 v[6:9], v[150:153], v[208:211], v[6:9]
	v_mfma_f32_16x16x32_bf16 v[2:5], v[158:161], v[208:211], v[2:5]
	s_barrier
	s_add_i32 s71, 0, 0x18000
	s_add_i32 s72, 0, 0x1c000
	v_add_u32_e32 v142, s71, v230
	v_add_u32_e32 v158, s72, v230
	ds_read_b128 v[114:117], v142
	ds_read_b128 v[126:129], v142 offset:1024
	ds_read_b128 v[138:141], v142 offset:2048
	ds_read_b128 v[142:145], v142 offset:3072
	ds_read_b128 v[146:149], v158
	ds_read_b128 v[150:153], v158 offset:1024
	ds_read_b128 v[154:157], v158 offset:2048
	ds_read_b128 v[158:161], v158 offset:3072
	s_add_u32 s52, s52, 0x40000
	s_addc_u32 s53, s53, 0
	s_mov_b32 m0, s60
	v_lshl_add_u64 v[236:237], s[52:53], 0, v[194:195]
	ds_read_b128 v[162:165], v235 offset:32768
	ds_read_b128 v[166:169], v235 offset:33792
	ds_read_b128 v[170:173], v235 offset:34816
	ds_read_b128 v[174:177], v235 offset:35840
	ds_read_b128 v[178:181], v235 offset:36864
	ds_read_b128 v[182:185], v235 offset:37888
	ds_read_b128 v[204:207], v235 offset:38912
	ds_read_b128 v[208:211], v235 offset:39936
	global_load_lds_dwordx4 v[236:237], off
	v_lshl_add_u64 v[236:237], s[52:53], 0, v[196:197]
	s_mov_b32 m0, s61
	s_nop 0
	global_load_lds_dwordx4 v[236:237], off
	s_waitcnt vmcnt(8)
	s_waitcnt lgkmcnt(0)
	s_barrier
	s_waitcnt lgkmcnt(0)
	v_mfma_f32_16x16x32_bf16 v[134:137], v[114:117], v[162:165], v[134:137]
	v_mfma_f32_16x16x32_bf16 v[130:133], v[138:141], v[162:165], v[130:133]
	v_mfma_f32_16x16x32_bf16 v[110:113], v[114:117], v[170:173], v[110:113]
	v_mfma_f32_16x16x32_bf16 v[106:109], v[138:141], v[170:173], v[106:109]
	v_mfma_f32_16x16x32_bf16 v[94:97], v[114:117], v[178:181], v[94:97]
	v_mfma_f32_16x16x32_bf16 v[90:93], v[138:141], v[178:181], v[90:93]
	v_mfma_f32_16x16x32_bf16 v[78:81], v[114:117], v[204:207], v[78:81]
	v_mfma_f32_16x16x32_bf16 v[74:77], v[138:141], v[204:207], v[74:77]
	v_mfma_f32_16x16x32_bf16 v[134:137], v[126:129], v[166:169], v[134:137]
	v_mfma_f32_16x16x32_bf16 v[130:133], v[142:145], v[166:169], v[130:133]
	v_mfma_f32_16x16x32_bf16 v[110:113], v[126:129], v[174:177], v[110:113]
	v_mfma_f32_16x16x32_bf16 v[106:109], v[142:145], v[174:177], v[106:109]
	v_mfma_f32_16x16x32_bf16 v[94:97], v[126:129], v[182:185], v[94:97]
	v_mfma_f32_16x16x32_bf16 v[90:93], v[142:145], v[182:185], v[90:93]
	v_mfma_f32_16x16x32_bf16 v[78:81], v[126:129], v[208:211], v[78:81]
	v_mfma_f32_16x16x32_bf16 v[74:77], v[142:145], v[208:211], v[74:77]
	v_mfma_f32_16x16x32_bf16 v[122:125], v[146:149], v[162:165], v[122:125]
	v_mfma_f32_16x16x32_bf16 v[118:121], v[154:157], v[162:165], v[118:121]
	v_mfma_f32_16x16x32_bf16 v[102:105], v[146:149], v[170:173], v[102:105]
	v_mfma_f32_16x16x32_bf16 v[98:101], v[154:157], v[170:173], v[98:101]
	v_mfma_f32_16x16x32_bf16 v[86:89], v[146:149], v[178:181], v[86:89]
	v_mfma_f32_16x16x32_bf16 v[82:85], v[154:157], v[178:181], v[82:85]
	v_mfma_f32_16x16x32_bf16 v[70:73], v[146:149], v[204:207], v[70:73]
	v_mfma_f32_16x16x32_bf16 v[66:69], v[154:157], v[204:207], v[66:69]
	v_mfma_f32_16x16x32_bf16 v[122:125], v[150:153], v[166:169], v[122:125]
	v_mfma_f32_16x16x32_bf16 v[118:121], v[158:161], v[166:169], v[118:121]
	v_mfma_f32_16x16x32_bf16 v[102:105], v[150:153], v[174:177], v[102:105]
	v_mfma_f32_16x16x32_bf16 v[98:101], v[158:161], v[174:177], v[98:101]
	v_mfma_f32_16x16x32_bf16 v[86:89], v[150:153], v[182:185], v[86:89]
	v_mfma_f32_16x16x32_bf16 v[82:85], v[158:161], v[182:185], v[82:85]
	v_mfma_f32_16x16x32_bf16 v[70:73], v[150:153], v[208:211], v[70:73]
	v_mfma_f32_16x16x32_bf16 v[66:69], v[158:161], v[208:211], v[66:69]
	s_barrier
; #define PG8_STAGE(bufoff, gbase, voff) do { _Pragma("unroll") for (int _i = 0; _i < 2; ++_i) \
;         __builtin_amdgcn_global_load_lds((const unsigned*)((const char*)(gbase) + (voff)[_i]), (PG8_LAS unsigned*)(lds + (bufoff) + ldsw + _i * 8192), 16, 0, 0); } while (0)
; #define PG8_LDA(dst, b, h) do { _Pragma("unroll") for (int m = 0; m < 4; ++m) _Pragma("unroll") for (int k = 0; k < 2; ++k) dst[m][k] = *(const PG8_LAS bf16x8*)(lds + PG8_SA(b, h) + aoff + m * 2048 + k * 1024); } while (0)
; #define PG8_MMA(ai, bj, At, Bt) do { __builtin_amdgcn_s_setprio(1); _Pragma("unroll") for (int m = 0; m < 4; ++m) _Pragma("unroll") for (int n = 0; n < 2; ++n) _Pragma("unroll") for (int k = 0; k < 2; ++k) \
;         acc[ai][bj][m][n] = __builtin_amdgcn_mfma_f32_16x16x32_bf16(Bt[n][k], At[m][k], acc[ai][bj][m][n], 0, 0, 0); __builtin_amdgcn_s_setprio(0); } while (0)
; #define PG8_WAIT_V(n) asm volatile("s_waitcnt vmcnt(" #n ")" ::: "memory")
; #define PG8_WAIT_L(n) asm volatile("s_waitcnt lgkmcnt(" #n ")" ::: "memory")
; #define PG8_BAR __builtin_amdgcn_s_barrier()
; #define PG8_SCHED __builtin_amdgcn_sched_barrier(0)
; template <class Epi, class Sched, bool ALIGN_EPI = false, bool SP2 = false>
; __device__ __forceinline__ void gemm_phase(PG8_LAS unsigned char* lds, const Gemm g, const Sched& S, const Epi& E, const int wv) {
;     ...
;         for (int t = 0; t < nt; t += 2) {
;             const bool last = (t == nt - 2);
;             const char* a1 = cA + (size_t)(t + 1) * kstep;
;             const char* a2 = last ? nA : cA + (size_t)(t + 2) * kstep; const char* b2 = last ? nB : cB + (size_t)(t + 2) * kstep;
;     ...
;             PG8_LDA(At, 1, 1); PG8_STAGE(PG8_SB(1, 0), b3, voffB); PG8_STAGE(PG8_SB(1, 1), b3 + hstepB, voffB); PG8_STAGE(PG8_SA(1, 0), a3, voffA);
;             PG8_WAIT_V(8); PG8_WAIT_L(0); PG8_BAR; PG8_MMA(1, 0, At, B0); PG8_MMA(1, 1, At, B1); PG8_BAR; PG8_SCHED;
	s_add_i32 s52, s71, s3
	v_lshl_add_u64 v[190:191], v[190:191], 0, s[4:5]
	s_mov_b32 m0, s52
	ds_read_b128 v[162:165], v235 offset:49152
	ds_read_b128 v[166:169], v235 offset:50176
	ds_read_b128 v[170:173], v235 offset:51200
	ds_read_b128 v[174:177], v235 offset:52224
	ds_read_b128 v[178:181], v235 offset:53248
	ds_read_b128 v[182:185], v235 offset:54272
	ds_read_b128 v[204:207], v235 offset:55296
	ds_read_b128 v[208:211], v235 offset:56320
	global_load_lds_dwordx4 v[190:191], off
	v_lshl_add_u64 v[190:191], v[192:193], 0, s[4:5]
	s_add_i32 m0, s52, 0x2000
	s_add_i32 s52, s72, s3
	global_load_lds_dwordx4 v[190:191], off
	v_lshl_add_u64 v[190:191], v[212:213], 0, s[4:5]
	s_mov_b32 m0, s52
	s_nop 0
	global_load_lds_dwordx4 v[190:191], off
	v_lshl_add_u64 v[190:191], v[214:215], 0, s[4:5]
	s_add_i32 m0, s52, 0x2000
	s_nop 0
	global_load_lds_dwordx4 v[190:191], off
	v_lshl_add_u64 v[190:191], v[216:217], 0, s[4:5]
	s_mov_b32 m0, s63
	s_nop 0
	global_load_lds_dwordx4 v[190:191], off
	v_lshl_add_u64 v[190:191], v[218:219], 0, s[4:5]
	s_mov_b32 m0, s64
	s_nop 0
	global_load_lds_dwordx4 v[190:191], off
	s_waitcnt vmcnt(8)
	s_waitcnt lgkmcnt(0)
	s_barrier
	s_waitcnt lgkmcnt(0)
	v_mfma_f32_16x16x32_bf16 v[62:65], v[114:117], v[162:165], v[62:65]
	v_mfma_f32_16x16x32_bf16 v[58:61], v[138:141], v[162:165], v[58:61]
	v_mfma_f32_16x16x32_bf16 v[46:49], v[114:117], v[170:173], v[46:49]
	v_mfma_f32_16x16x32_bf16 v[42:45], v[138:141], v[170:173], v[42:45]
	v_mfma_f32_16x16x32_bf16 v[30:33], v[114:117], v[178:181], v[30:33]
	v_mfma_f32_16x16x32_bf16 v[26:29], v[138:141], v[178:181], v[26:29]
	v_mfma_f32_16x16x32_bf16 v[14:17], v[114:117], v[204:207], v[14:17]
	v_mfma_f32_16x16x32_bf16 v[10:13], v[138:141], v[204:207], v[10:13]
	v_mfma_f32_16x16x32_bf16 v[62:65], v[126:129], v[166:169], v[62:65]
	v_mfma_f32_16x16x32_bf16 v[58:61], v[142:145], v[166:169], v[58:61]
	v_mfma_f32_16x16x32_bf16 v[46:49], v[126:129], v[174:177], v[46:49]
	v_mfma_f32_16x16x32_bf16 v[42:45], v[142:145], v[174:177], v[42:45]
	v_mfma_f32_16x16x32_bf16 v[30:33], v[126:129], v[182:185], v[30:33]
	v_mfma_f32_16x16x32_bf16 v[26:29], v[142:145], v[182:185], v[26:29]
	v_mfma_f32_16x16x32_bf16 v[14:17], v[126:129], v[208:211], v[14:17]
	v_mfma_f32_16x16x32_bf16 v[10:13], v[142:145], v[208:211], v[10:13]
	v_mfma_f32_16x16x32_bf16 v[54:57], v[146:149], v[162:165], v[54:57]
	v_mfma_f32_16x16x32_bf16 v[50:53], v[154:157], v[162:165], v[50:53]
	v_mfma_f32_16x16x32_bf16 v[38:41], v[146:149], v[170:173], v[38:41]
	v_mfma_f32_16x16x32_bf16 v[34:37], v[154:157], v[170:173], v[34:37]
	v_mfma_f32_16x16x32_bf16 v[22:25], v[146:149], v[178:181], v[22:25]
	v_mfma_f32_16x16x32_bf16 v[18:21], v[154:157], v[178:181], v[18:21]
	v_mfma_f32_16x16x32_bf16 v[6:9], v[146:149], v[204:207], v[6:9]
	v_mfma_f32_16x16x32_bf16 v[2:5], v[154:157], v[204:207], v[2:5]
	v_mfma_f32_16x16x32_bf16 v[54:57], v[150:153], v[166:169], v[54:57]
	v_mfma_f32_16x16x32_bf16 v[50:53], v[158:161], v[166:169], v[50:53]
	v_mfma_f32_16x16x32_bf16 v[38:41], v[150:153], v[174:177], v[38:41]
	v_mfma_f32_16x16x32_bf16 v[34:37], v[158:161], v[174:177], v[34:37]
	v_mfma_f32_16x16x32_bf16 v[22:25], v[150:153], v[182:185], v[22:25]
	v_mfma_f32_16x16x32_bf16 v[18:21], v[158:161], v[182:185], v[18:21]
	v_mfma_f32_16x16x32_bf16 v[6:9], v[150:153], v[208:211], v[6:9]
	v_mfma_f32_16x16x32_bf16 v[2:5], v[158:161], v[208:211], v[2:5]
	s_barrier
	s_add_u32 s44, s44, 0x100
	s_addc_u32 s45, s45, 0
	s_add_u32 s54, s54, 0x100
	s_addc_u32 s55, s55, 0
	s_cmp_ge_i32 s70, s62
	s_mov_b32 s52, s70
	s_cbranch_scc0 .LBB0_1385
	s_mov_b32 s72, 0x10000
	s_mov_b32 s73, 0x12000
	s_mov_b32 s74, 0x14000
	s_mov_b32 s70, 0x18000
	s_mov_b32 s71, 0x3f317217
	s_and_b64 vcc, exec, s[46:47]
	s_cbranch_vccz .LBB0_1361

; #define PG8_STAGE(bufoff, gbase, voff) do { _Pragma("unroll") for (int _i = 0; _i < 2; ++_i) \
;         __builtin_amdgcn_global_load_lds((const unsigned*)((const char*)(gbase) + (voff)[_i]), (PG8_LAS unsigned*)(lds + (bufoff) + ldsw + _i * 8192), 16, 0, 0); } while (0)
; #define PG8_LDA(dst, b, h) do { _Pragma("unroll") for (int m = 0; m < 4; ++m) _Pragma("unroll") for (int k = 0; k < 2; ++k) dst[m][k] = *(const PG8_LAS bf16x8*)(lds + PG8_SA(b, h) + aoff + m * 2048 + k * 1024); } while (0)
; #define PG8_LDB(dst, b, h) do { _Pragma("unroll") for (int n = 0; n < 2; ++n) _Pragma("unroll") for (int k = 0; k < 2; ++k) dst[n][k] = *(const PG8_LAS bf16x8*)(lds + PG8_SB(b, h) + boff + n * 2048 + k * 1024); } while (0)
; #define PG8_MMA(ai, bj, At, Bt) do { __builtin_amdgcn_s_setprio(1); _Pragma("unroll") for (int m = 0; m < 4; ++m) _Pragma("unroll") for (int n = 0; n < 2; ++n) _Pragma("unroll") for (int k = 0; k < 2; ++k) \
;         acc[ai][bj][m][n] = __builtin_amdgcn_mfma_f32_16x16x32_bf16(Bt[n][k], At[m][k], acc[ai][bj][m][n], 0, 0, 0); __builtin_amdgcn_s_setprio(0); } while (0)
; #define PG8_WAIT_V(n) asm volatile("s_waitcnt vmcnt(" #n ")" ::: "memory")
; #define PG8_WAIT_L(n) asm volatile("s_waitcnt lgkmcnt(" #n ")" ::: "memory")
; #define PG8_BAR __builtin_amdgcn_s_barrier()
; template <class Epi, class Sched, bool ALIGN_EPI = false, bool SP2 = false>
; __device__ __forceinline__ void gemm_phase(PG8_LAS unsigned char* lds, const Gemm g, const Sched& S, const Epi& E, const int wv) {
;     ...
;         for (int t = 0; t < nt; t += 2) {
;             const bool last = (t == nt - 2);
;             const char* a1 = cA + (size_t)(t + 1) * kstep;
;             const char* a2 = last ? nA : cA + (size_t)(t + 2) * kstep; const char* b2 = last ? nB : cB + (size_t)(t + 2) * kstep;
;             const char* a3 = a2 + kstep; const char* b3 = b2 + kstep;
;             if (last && has_next) S.a_ready(nxt);
;             if constexpr (SP2) {
;             PG8_LDB(B0, 0, 0); PG8_LDB(B1, 0, 1); PG8_SCHED; PG8_LDA(At, 0, 0); PG8_STAGE(PG8_SA(1, 1), a1 + hstepA, voffA);
;             PG8_WAIT_V(8); PG8_WAIT_L(0); PG8_BAR; PG8_MMA(0, 0, At, B0); PG8_MMA(0, 1, At, B1); PG8_BAR; PG8_SCHED;
;             PG8_LDA(At, 0, 1); PG8_STAGE(PG8_SB(0, 0), b2, voffB); PG8_STAGE(PG8_SB(0, 1), b2 + hstepB, voffB); PG8_STAGE(PG8_SA(0, 0), a2, voffA);
.LBB0_1495:
	s_add_i32 s52, s46, 2
	s_add_u32 s14, s48, 0x100
	s_addc_u32 s15, s49, 0
	s_add_i32 s53, 0, 0x10000
	s_cmp_eq_u32 s72, s46
	s_cselect_b32 s47, s11, s15
	s_cselect_b32 s46, s13, s14
	s_cselect_b32 s77, s87, s51
	s_cselect_b32 s76, s86, s35
	s_add_i32 s78, 0, 0x14000
	v_add_u32_e32 v150, s53, v208
	v_add_u32_e32 v166, s78, v208
	ds_read_b128 v[138:141], v150
	ds_read_b128 v[142:145], v150 offset:1024
	ds_read_b128 v[146:149], v150 offset:2048
	ds_read_b128 v[150:153], v150 offset:3072
	ds_read_b128 v[154:157], v166
	ds_read_b128 v[158:161], v166 offset:1024
	ds_read_b128 v[162:165], v166 offset:2048
	ds_read_b128 v[166:169], v166 offset:3072
	v_lshl_add_u64 v[190:191], s[48:49], 0, v[182:183]
	s_add_i32 m0, s64, 0xc000
	ds_read_b128 v[194:197], v211
	ds_read_b128 v[198:201], v211 offset:1024
	ds_read_b128 v[202:205], v211 offset:2048
	ds_read_b128 v[214:217], v211 offset:3072
	ds_read_b128 v[228:231], v211 offset:4096
	ds_read_b128 v[232:235], v211 offset:5120
	ds_read_b128 v[236:239], v211 offset:6144
	ds_read_b128 v[240:243], v211 offset:7168
	global_load_lds_dwordx4 v[190:191], off
	v_lshl_add_u64 v[190:191], s[48:49], 0, v[184:185]
	s_add_i32 m0, s64, 0xe000
	s_nop 0
	global_load_lds_dwordx4 v[190:191], off
	s_waitcnt vmcnt(8)
	s_waitcnt lgkmcnt(0)
	s_barrier
	s_waitcnt lgkmcnt(0)
	v_mfma_f32_16x16x32_bf16 v[118:121], v[138:141], v[194:197], v[118:121]
	v_mfma_f32_16x16x32_bf16 v[46:49], v[146:149], v[194:197], v[46:49]
	v_mfma_f32_16x16x32_bf16 v[110:113], v[138:141], v[202:205], v[110:113]
	v_mfma_f32_16x16x32_bf16 v[38:41], v[146:149], v[202:205], v[38:41]
	v_mfma_f32_16x16x32_bf16 v[134:137], v[138:141], v[228:231], v[134:137]
	v_mfma_f32_16x16x32_bf16 v[62:65], v[146:149], v[228:231], v[62:65]
	v_mfma_f32_16x16x32_bf16 v[130:133], v[138:141], v[236:239], v[130:133]
	v_mfma_f32_16x16x32_bf16 v[58:61], v[146:149], v[236:239], v[58:61]
	v_mfma_f32_16x16x32_bf16 v[118:121], v[142:145], v[198:201], v[118:121]
	v_mfma_f32_16x16x32_bf16 v[46:49], v[150:153], v[198:201], v[46:49]
	v_mfma_f32_16x16x32_bf16 v[110:113], v[142:145], v[214:217], v[110:113]
	v_mfma_f32_16x16x32_bf16 v[38:41], v[150:153], v[214:217], v[38:41]
	v_mfma_f32_16x16x32_bf16 v[134:137], v[142:145], v[232:235], v[134:137]
	v_mfma_f32_16x16x32_bf16 v[62:65], v[150:153], v[232:235], v[62:65]
	v_mfma_f32_16x16x32_bf16 v[130:133], v[142:145], v[240:243], v[130:133]
	v_mfma_f32_16x16x32_bf16 v[58:61], v[150:153], v[240:243], v[58:61]
	v_mfma_f32_16x16x32_bf16 v[114:117], v[154:157], v[194:197], v[114:117]
	v_mfma_f32_16x16x32_bf16 v[42:45], v[162:165], v[194:197], v[42:45]
	v_mfma_f32_16x16x32_bf16 v[106:109], v[154:157], v[202:205], v[106:109]
	v_mfma_f32_16x16x32_bf16 v[34:37], v[162:165], v[202:205], v[34:37]
	v_mfma_f32_16x16x32_bf16 v[126:129], v[154:157], v[228:231], v[126:129]
	v_mfma_f32_16x16x32_bf16 v[54:57], v[162:165], v[228:231], v[54:57]
	v_mfma_f32_16x16x32_bf16 v[122:125], v[154:157], v[236:239], v[122:125]
	v_mfma_f32_16x16x32_bf16 v[50:53], v[162:165], v[236:239], v[50:53]
	v_mfma_f32_16x16x32_bf16 v[114:117], v[158:161], v[198:201], v[114:117]
	v_mfma_f32_16x16x32_bf16 v[42:45], v[166:169], v[198:201], v[42:45]
	v_mfma_f32_16x16x32_bf16 v[106:109], v[158:161], v[214:217], v[106:109]
	v_mfma_f32_16x16x32_bf16 v[34:37], v[166:169], v[214:217], v[34:37]
	v_mfma_f32_16x16x32_bf16 v[126:129], v[158:161], v[232:235], v[126:129]
	v_mfma_f32_16x16x32_bf16 v[54:57], v[166:169], v[232:235], v[54:57]
	v_mfma_f32_16x16x32_bf16 v[122:125], v[158:161], v[240:243], v[122:125]
	v_mfma_f32_16x16x32_bf16 v[50:53], v[166:169], v[240:243], v[50:53]
	s_barrier
	s_add_i32 s48, s53, s63
	v_lshl_add_u64 v[190:191], s[76:77], 0, v[0:1]
	s_mov_b32 m0, s48
	ds_read_b128 v[194:197], v211 offset:16384
	ds_read_b128 v[198:201], v211 offset:17408
	ds_read_b128 v[202:205], v211 offset:18432
	ds_read_b128 v[214:217], v211 offset:19456
	ds_read_b128 v[228:231], v211 offset:20480
	ds_read_b128 v[232:235], v211 offset:21504
	ds_read_b128 v[236:239], v211 offset:22528
	ds_read_b128 v[240:243], v211 offset:23552
	global_load_lds_dwordx4 v[190:191], off
	s_add_i32 m0, s48, 0x2000
	s_add_u32 s48, s76, s16
	v_lshl_add_u64 v[192:193], s[76:77], 0, v[174:175]
	s_addc_u32 s49, s77, s17
	s_add_i32 s53, s78, s63
	global_load_lds_dwordx4 v[192:193], off
	v_lshl_add_u64 v[218:219], s[48:49], 0, v[0:1]
	s_mov_b32 m0, s53
	v_lshl_add_u64 v[244:245], s[48:49], 0, v[174:175]
	global_load_lds_dwordx4 v[218:219], off
	s_add_i32 m0, s53, 0x2000
	v_lshl_add_u64 v[246:247], s[46:47], 0, v[170:171]
	global_load_lds_dwordx4 v[244:245], off
	s_mov_b32 m0, s64
	v_lshl_add_u64 v[248:249], s[46:47], 0, v[172:173]
	global_load_lds_dwordx4 v[246:247], off
	s_mov_b32 m0, s65
	s_nop 0
	global_load_lds_dwordx4 v[248:249], off
	s_waitcnt vmcnt(8)
	s_waitcnt lgkmcnt(0)
	s_barrier
; #define PG8_STAGE(bufoff, gbase, voff) do { _Pragma("unroll") for (int _i = 0; _i < 2; ++_i) \
;         __builtin_amdgcn_global_load_lds((const unsigned*)((const char*)(gbase) + (voff)[_i]), (PG8_LAS unsigned*)(lds + (bufoff) + ldsw + _i * 8192), 16, 0, 0); } while (0)
; #define PG8_LDA(dst, b, h) do { _Pragma("unroll") for (int m = 0; m < 4; ++m) _Pragma("unroll") for (int k = 0; k < 2; ++k) dst[m][k] = *(const PG8_LAS bf16x8*)(lds + PG8_SA(b, h) + aoff + m * 2048 + k * 1024); } while (0)
; #define PG8_LDB(dst, b, h) do { _Pragma("unroll") for (int n = 0; n < 2; ++n) _Pragma("unroll") for (int k = 0; k < 2; ++k) dst[n][k] = *(const PG8_LAS bf16x8*)(lds + PG8_SB(b, h) + boff + n * 2048 + k * 1024); } while (0)
; #define PG8_MMA(ai, bj, At, Bt) do { __builtin_amdgcn_s_setprio(1); _Pragma("unroll") for (int m = 0; m < 4; ++m) _Pragma("unroll") for (int n = 0; n < 2; ++n) _Pragma("unroll") for (int k = 0; k < 2; ++k) \
;         acc[ai][bj][m][n] = __builtin_amdgcn_mfma_f32_16x16x32_bf16(Bt[n][k], At[m][k], acc[ai][bj][m][n], 0, 0, 0); __builtin_amdgcn_s_setprio(0); } while (0)
; #define PG8_WAIT_V(n) asm volatile("s_waitcnt vmcnt(" #n ")" ::: "memory")
; #define PG8_WAIT_L(n) asm volatile("s_waitcnt lgkmcnt(" #n ")" ::: "memory")
; #define PG8_BAR __builtin_amdgcn_s_barrier()
; #define PG8_SCHED __builtin_amdgcn_sched_barrier(0)
; template <class Epi, class Sched, bool ALIGN_EPI = false, bool SP2 = false>
; __device__ __forceinline__ void gemm_phase(PG8_LAS unsigned char* lds, const Gemm g, const Sched& S, const Epi& E, const int wv) {
;     ...
;             PG8_WAIT_V(8); PG8_WAIT_L(0); PG8_BAR; PG8_MMA(1, 0, At, B0); PG8_MMA(1, 1, At, B1); PG8_BAR; PG8_SCHED;
;             PG8_LDB(B0, 1, 0); PG8_LDB(B1, 1, 1); PG8_SCHED; PG8_LDA(At, 1, 0); PG8_STAGE(PG8_SA(0, 1), a2 + hstepA, voffA);
;             PG8_WAIT_V(8); PG8_WAIT_L(0); PG8_BAR; PG8_MMA(0, 0, At, B0); PG8_MMA(0, 1, At, B1); PG8_BAR; PG8_SCHED;
	s_waitcnt lgkmcnt(0)
	v_mfma_f32_16x16x32_bf16 v[86:89], v[138:141], v[194:197], v[86:89]
	v_mfma_f32_16x16x32_bf16 v[14:17], v[146:149], v[194:197], v[14:17]
	v_mfma_f32_16x16x32_bf16 v[70:73], v[138:141], v[202:205], v[70:73]
	v_mfma_f32_16x16x32_bf16 v[6:9], v[146:149], v[202:205], v[6:9]
	v_mfma_f32_16x16x32_bf16 v[102:105], v[138:141], v[228:231], v[102:105]
	v_mfma_f32_16x16x32_bf16 v[30:33], v[146:149], v[228:231], v[30:33]
	v_mfma_f32_16x16x32_bf16 v[98:101], v[138:141], v[236:239], v[98:101]
	v_mfma_f32_16x16x32_bf16 v[26:29], v[146:149], v[236:239], v[26:29]
	v_mfma_f32_16x16x32_bf16 v[86:89], v[142:145], v[198:201], v[86:89]
	v_mfma_f32_16x16x32_bf16 v[14:17], v[150:153], v[198:201], v[14:17]
	v_mfma_f32_16x16x32_bf16 v[70:73], v[142:145], v[214:217], v[70:73]
	v_mfma_f32_16x16x32_bf16 v[6:9], v[150:153], v[214:217], v[6:9]
	v_mfma_f32_16x16x32_bf16 v[102:105], v[142:145], v[232:235], v[102:105]
	v_mfma_f32_16x16x32_bf16 v[30:33], v[150:153], v[232:235], v[30:33]
	v_mfma_f32_16x16x32_bf16 v[98:101], v[142:145], v[240:243], v[98:101]
	v_mfma_f32_16x16x32_bf16 v[26:29], v[150:153], v[240:243], v[26:29]
	v_mfma_f32_16x16x32_bf16 v[82:85], v[154:157], v[194:197], v[82:85]
	v_mfma_f32_16x16x32_bf16 v[10:13], v[162:165], v[194:197], v[10:13]
	v_mfma_f32_16x16x32_bf16 v[66:69], v[154:157], v[202:205], v[66:69]
	v_mfma_f32_16x16x32_bf16 v[2:5], v[162:165], v[202:205], v[2:5]
	v_mfma_f32_16x16x32_bf16 v[94:97], v[154:157], v[228:231], v[94:97]
	v_mfma_f32_16x16x32_bf16 v[22:25], v[162:165], v[228:231], v[22:25]
	v_mfma_f32_16x16x32_bf16 v[90:93], v[154:157], v[236:239], v[90:93]
	v_mfma_f32_16x16x32_bf16 v[18:21], v[162:165], v[236:239], v[18:21]
	v_mfma_f32_16x16x32_bf16 v[82:85], v[158:161], v[198:201], v[82:85]
	v_mfma_f32_16x16x32_bf16 v[10:13], v[166:169], v[198:201], v[10:13]
	v_mfma_f32_16x16x32_bf16 v[66:69], v[158:161], v[214:217], v[66:69]
	v_mfma_f32_16x16x32_bf16 v[2:5], v[166:169], v[214:217], v[2:5]
	v_mfma_f32_16x16x32_bf16 v[94:97], v[158:161], v[232:235], v[94:97]
	v_mfma_f32_16x16x32_bf16 v[22:25], v[166:169], v[232:235], v[22:25]
	v_mfma_f32_16x16x32_bf16 v[90:93], v[158:161], v[240:243], v[90:93]
	v_mfma_f32_16x16x32_bf16 v[18:21], v[166:169], v[240:243], v[18:21]
	s_barrier
	s_add_i32 s48, 0, 0x18000
	s_add_i32 s49, 0, 0x1c000
	v_add_u32_e32 v150, s48, v208
	v_add_u32_e32 v166, s49, v208
	ds_read_b128 v[138:141], v150
	ds_read_b128 v[142:145], v150 offset:1024
	ds_read_b128 v[146:149], v150 offset:2048
	ds_read_b128 v[150:153], v150 offset:3072
	ds_read_b128 v[154:157], v166
	ds_read_b128 v[158:161], v166 offset:1024
	ds_read_b128 v[162:165], v166 offset:2048
	ds_read_b128 v[166:169], v166 offset:3072
	s_add_u32 s46, s46, 0x80000
	s_addc_u32 s47, s47, 0
	s_mov_b32 m0, s66
	v_lshl_add_u64 v[250:251], s[46:47], 0, v[170:171]
	ds_read_b128 v[194:197], v211 offset:32768
	ds_read_b128 v[198:201], v211 offset:33792
	ds_read_b128 v[202:205], v211 offset:34816
	ds_read_b128 v[214:217], v211 offset:35840
	ds_read_b128 v[228:231], v211 offset:36864
	ds_read_b128 v[232:235], v211 offset:37888
	ds_read_b128 v[236:239], v211 offset:38912
	ds_read_b128 v[240:243], v211 offset:39936
	global_load_lds_dwordx4 v[250:251], off
	v_lshl_add_u64 v[250:251], s[46:47], 0, v[172:173]
	s_mov_b32 m0, s67
	s_nop 0
	global_load_lds_dwordx4 v[250:251], off
	s_waitcnt vmcnt(8)
	s_waitcnt lgkmcnt(0)
	s_barrier
	s_waitcnt lgkmcnt(0)
	v_mfma_f32_16x16x32_bf16 v[118:121], v[138:141], v[194:197], v[118:121]
	v_mfma_f32_16x16x32_bf16 v[46:49], v[146:149], v[194:197], v[46:49]
	v_mfma_f32_16x16x32_bf16 v[110:113], v[138:141], v[202:205], v[110:113]
	v_mfma_f32_16x16x32_bf16 v[38:41], v[146:149], v[202:205], v[38:41]
	v_mfma_f32_16x16x32_bf16 v[134:137], v[138:141], v[228:231], v[134:137]
	v_mfma_f32_16x16x32_bf16 v[62:65], v[146:149], v[228:231], v[62:65]
	v_mfma_f32_16x16x32_bf16 v[130:133], v[138:141], v[236:239], v[130:133]
	v_mfma_f32_16x16x32_bf16 v[58:61], v[146:149], v[236:239], v[58:61]
	v_mfma_f32_16x16x32_bf16 v[118:121], v[142:145], v[198:201], v[118:121]
	v_mfma_f32_16x16x32_bf16 v[46:49], v[150:153], v[198:201], v[46:49]
	v_mfma_f32_16x16x32_bf16 v[110:113], v[142:145], v[214:217], v[110:113]
	v_mfma_f32_16x16x32_bf16 v[38:41], v[150:153], v[214:217], v[38:41]
	v_mfma_f32_16x16x32_bf16 v[134:137], v[142:145], v[232:235], v[134:137]
	v_mfma_f32_16x16x32_bf16 v[62:65], v[150:153], v[232:235], v[62:65]
	v_mfma_f32_16x16x32_bf16 v[130:133], v[142:145], v[240:243], v[130:133]
	v_mfma_f32_16x16x32_bf16 v[58:61], v[150:153], v[240:243], v[58:61]
	v_mfma_f32_16x16x32_bf16 v[114:117], v[154:157], v[194:197], v[114:117]
	v_mfma_f32_16x16x32_bf16 v[42:45], v[162:165], v[194:197], v[42:45]
	v_mfma_f32_16x16x32_bf16 v[106:109], v[154:157], v[202:205], v[106:109]
	v_mfma_f32_16x16x32_bf16 v[34:37], v[162:165], v[202:205], v[34:37]
	v_mfma_f32_16x16x32_bf16 v[126:129], v[154:157], v[228:231], v[126:129]
	v_mfma_f32_16x16x32_bf16 v[54:57], v[162:165], v[228:231], v[54:57]
	v_mfma_f32_16x16x32_bf16 v[122:125], v[154:157], v[236:239], v[122:125]
	v_mfma_f32_16x16x32_bf16 v[50:53], v[162:165], v[236:239], v[50:53]
	v_mfma_f32_16x16x32_bf16 v[114:117], v[158:161], v[198:201], v[114:117]
	v_mfma_f32_16x16x32_bf16 v[42:45], v[166:169], v[198:201], v[42:45]
	v_mfma_f32_16x16x32_bf16 v[106:109], v[158:161], v[214:217], v[106:109]
	v_mfma_f32_16x16x32_bf16 v[34:37], v[166:169], v[214:217], v[34:37]
	v_mfma_f32_16x16x32_bf16 v[126:129], v[158:161], v[232:235], v[126:129]
	v_mfma_f32_16x16x32_bf16 v[54:57], v[166:169], v[232:235], v[54:57]
	v_mfma_f32_16x16x32_bf16 v[122:125], v[158:161], v[240:243], v[122:125]
	v_mfma_f32_16x16x32_bf16 v[50:53], v[166:169], v[240:243], v[50:53]
	s_barrier
; #define PG8_STAGE(bufoff, gbase, voff) do { _Pragma("unroll") for (int _i = 0; _i < 2; ++_i) \
;         __builtin_amdgcn_global_load_lds((const unsigned*)((const char*)(gbase) + (voff)[_i]), (PG8_LAS unsigned*)(lds + (bufoff) + ldsw + _i * 8192), 16, 0, 0); } while (0)
; #define PG8_LDA(dst, b, h) do { _Pragma("unroll") for (int m = 0; m < 4; ++m) _Pragma("unroll") for (int k = 0; k < 2; ++k) dst[m][k] = *(const PG8_LAS bf16x8*)(lds + PG8_SA(b, h) + aoff + m * 2048 + k * 1024); } while (0)
; #define PG8_MMA(ai, bj, At, Bt) do { __builtin_amdgcn_s_setprio(1); _Pragma("unroll") for (int m = 0; m < 4; ++m) _Pragma("unroll") for (int n = 0; n < 2; ++n) _Pragma("unroll") for (int k = 0; k < 2; ++k) \
;         acc[ai][bj][m][n] = __builtin_amdgcn_mfma_f32_16x16x32_bf16(Bt[n][k], At[m][k], acc[ai][bj][m][n], 0, 0, 0); __builtin_amdgcn_s_setprio(0); } while (0)
; #define PG8_WAIT_V(n) asm volatile("s_waitcnt vmcnt(" #n ")" ::: "memory")
; #define PG8_WAIT_L(n) asm volatile("s_waitcnt lgkmcnt(" #n ")" ::: "memory")
; #define PG8_BAR __builtin_amdgcn_s_barrier()
; #define PG8_SCHED __builtin_amdgcn_sched_barrier(0)
; template <class Epi, class Sched, bool ALIGN_EPI = false, bool SP2 = false>
; __device__ __forceinline__ void gemm_phase(PG8_LAS unsigned char* lds, const Gemm g, const Sched& S, const Epi& E, const int wv) {
;     ...
;         for (int t = 0; t < nt; t += 2) {
;             const bool last = (t == nt - 2);
;             const char* a1 = cA + (size_t)(t + 1) * kstep;
;             const char* a2 = last ? nA : cA + (size_t)(t + 2) * kstep; const char* b2 = last ? nB : cB + (size_t)(t + 2) * kstep;
;     ...
;             PG8_LDA(At, 1, 1); PG8_STAGE(PG8_SB(1, 0), b3, voffB); PG8_STAGE(PG8_SB(1, 1), b3 + hstepB, voffB); PG8_STAGE(PG8_SA(1, 0), a3, voffA);
;             PG8_WAIT_V(8); PG8_WAIT_L(0); PG8_BAR; PG8_MMA(1, 0, At, B0); PG8_MMA(1, 1, At, B1); PG8_BAR; PG8_SCHED;
	s_add_i32 s46, s48, s63
	v_lshl_add_u64 v[190:191], v[190:191], 0, s[4:5]
	s_mov_b32 m0, s46
	ds_read_b128 v[194:197], v211 offset:49152
	ds_read_b128 v[198:201], v211 offset:50176
	ds_read_b128 v[202:205], v211 offset:51200
	ds_read_b128 v[214:217], v211 offset:52224
	ds_read_b128 v[228:231], v211 offset:53248
	ds_read_b128 v[232:235], v211 offset:54272
	ds_read_b128 v[236:239], v211 offset:55296
	ds_read_b128 v[240:243], v211 offset:56320
	global_load_lds_dwordx4 v[190:191], off
	v_lshl_add_u64 v[190:191], v[192:193], 0, s[4:5]
	s_add_i32 m0, s46, 0x2000
	s_add_i32 s46, s49, s63
	global_load_lds_dwordx4 v[190:191], off
	v_lshl_add_u64 v[190:191], v[218:219], 0, s[4:5]
	s_mov_b32 m0, s46
	s_nop 0
	global_load_lds_dwordx4 v[190:191], off
	v_lshl_add_u64 v[190:191], v[244:245], 0, s[4:5]
	s_add_i32 m0, s46, 0x2000
	s_nop 0
	global_load_lds_dwordx4 v[190:191], off
	v_lshl_add_u64 v[190:191], v[246:247], 0, s[4:5]
	s_mov_b32 m0, s70
	s_nop 0
	global_load_lds_dwordx4 v[190:191], off
	v_lshl_add_u64 v[190:191], v[248:249], 0, s[4:5]
	s_mov_b32 m0, s71
	s_nop 0
	global_load_lds_dwordx4 v[190:191], off
	s_waitcnt vmcnt(8)
	s_waitcnt lgkmcnt(0)
	s_barrier
	s_waitcnt lgkmcnt(0)
	v_mfma_f32_16x16x32_bf16 v[86:89], v[138:141], v[194:197], v[86:89]
	v_mfma_f32_16x16x32_bf16 v[14:17], v[146:149], v[194:197], v[14:17]
	v_mfma_f32_16x16x32_bf16 v[70:73], v[138:141], v[202:205], v[70:73]
	v_mfma_f32_16x16x32_bf16 v[6:9], v[146:149], v[202:205], v[6:9]
	v_mfma_f32_16x16x32_bf16 v[102:105], v[138:141], v[228:231], v[102:105]
	v_mfma_f32_16x16x32_bf16 v[30:33], v[146:149], v[228:231], v[30:33]
	v_mfma_f32_16x16x32_bf16 v[98:101], v[138:141], v[236:239], v[98:101]
	v_mfma_f32_16x16x32_bf16 v[26:29], v[146:149], v[236:239], v[26:29]
	v_mfma_f32_16x16x32_bf16 v[86:89], v[142:145], v[198:201], v[86:89]
	v_mfma_f32_16x16x32_bf16 v[14:17], v[150:153], v[198:201], v[14:17]
	v_mfma_f32_16x16x32_bf16 v[70:73], v[142:145], v[214:217], v[70:73]
	v_mfma_f32_16x16x32_bf16 v[6:9], v[150:153], v[214:217], v[6:9]
	v_mfma_f32_16x16x32_bf16 v[102:105], v[142:145], v[232:235], v[102:105]
	v_mfma_f32_16x16x32_bf16 v[30:33], v[150:153], v[232:235], v[30:33]
	v_mfma_f32_16x16x32_bf16 v[98:101], v[142:145], v[240:243], v[98:101]
	v_mfma_f32_16x16x32_bf16 v[26:29], v[150:153], v[240:243], v[26:29]
	v_mfma_f32_16x16x32_bf16 v[82:85], v[154:157], v[194:197], v[82:85]
	v_mfma_f32_16x16x32_bf16 v[10:13], v[162:165], v[194:197], v[10:13]
	v_mfma_f32_16x16x32_bf16 v[66:69], v[154:157], v[202:205], v[66:69]
	v_mfma_f32_16x16x32_bf16 v[2:5], v[162:165], v[202:205], v[2:5]
	v_mfma_f32_16x16x32_bf16 v[94:97], v[154:157], v[228:231], v[94:97]
	v_mfma_f32_16x16x32_bf16 v[22:25], v[162:165], v[228:231], v[22:25]
	v_mfma_f32_16x16x32_bf16 v[90:93], v[154:157], v[236:239], v[90:93]
	v_mfma_f32_16x16x32_bf16 v[18:21], v[162:165], v[236:239], v[18:21]
	v_mfma_f32_16x16x32_bf16 v[82:85], v[158:161], v[198:201], v[82:85]
	v_mfma_f32_16x16x32_bf16 v[10:13], v[166:169], v[198:201], v[10:13]
	v_mfma_f32_16x16x32_bf16 v[66:69], v[158:161], v[214:217], v[66:69]
	v_mfma_f32_16x16x32_bf16 v[2:5], v[166:169], v[214:217], v[2:5]
	v_mfma_f32_16x16x32_bf16 v[94:97], v[158:161], v[232:235], v[94:97]
	v_mfma_f32_16x16x32_bf16 v[22:25], v[166:169], v[232:235], v[22:25]
	v_mfma_f32_16x16x32_bf16 v[90:93], v[158:161], v[240:243], v[90:93]
	v_mfma_f32_16x16x32_bf16 v[18:21], v[166:169], v[240:243], v[18:21]
	s_barrier
	s_add_u32 s35, s35, 0x100
	s_addc_u32 s51, s51, 0
	s_cmp_ge_i32 s52, s68
	s_mov_b64 s[48:49], s[14:15]
	s_mov_b32 s46, s52
	s_cbranch_scc0 .LBB0_1495
	s_movk_i32 s78, 0x7ff
	s_movk_i32 s76, 0x3000
	s_and_b64 vcc, exec, s[30:31]
	s_cbranch_vccz .LBB0_1470

; #define PG8_STAGE(bufoff, gbase, voff) do { _Pragma("unroll") for (int _i = 0; _i < 2; ++_i) \
;         __builtin_amdgcn_global_load_lds((const unsigned*)((const char*)(gbase) + (voff)[_i]), (PG8_LAS unsigned*)(lds + (bufoff) + ldsw + _i * 8192), 16, 0, 0); } while (0)
; #define PG8_LDA(dst, b, h) do { _Pragma("unroll") for (int m = 0; m < 4; ++m) _Pragma("unroll") for (int k = 0; k < 2; ++k) dst[m][k] = *(const PG8_LAS bf16x8*)(lds + PG8_SA(b, h) + aoff + m * 2048 + k * 1024); } while (0)
; #define PG8_LDB(dst, b, h) do { _Pragma("unroll") for (int n = 0; n < 2; ++n) _Pragma("unroll") for (int k = 0; k < 2; ++k) dst[n][k] = *(const PG8_LAS bf16x8*)(lds + PG8_SB(b, h) + boff + n * 2048 + k * 1024); } while (0)
; #define PG8_MMA(ai, bj, At, Bt) do { __builtin_amdgcn_s_setprio(1); _Pragma("unroll") for (int m = 0; m < 4; ++m) _Pragma("unroll") for (int n = 0; n < 2; ++n) _Pragma("unroll") for (int k = 0; k < 2; ++k) \
;         acc[ai][bj][m][n] = __builtin_amdgcn_mfma_f32_16x16x32_bf16(Bt[n][k], At[m][k], acc[ai][bj][m][n], 0, 0, 0); __builtin_amdgcn_s_setprio(0); } while (0)
; #define PG8_WAIT_V(n) asm volatile("s_waitcnt vmcnt(" #n ")" ::: "memory")
; #define PG8_WAIT_L(n) asm volatile("s_waitcnt lgkmcnt(" #n ")" ::: "memory")
; #define PG8_BAR __builtin_amdgcn_s_barrier()
; template <class Epi, class Sched, bool ALIGN_EPI = false, bool SP2 = false>
; __device__ __forceinline__ void gemm_phase(PG8_LAS unsigned char* lds, const Gemm g, const Sched& S, const Epi& E, const int wv) {
;     ...
;         for (int t = 0; t < nt; t += 2) {
;             const bool last = (t == nt - 2);
;             const char* a1 = cA + (size_t)(t + 1) * kstep;
;             const char* a2 = last ? nA : cA + (size_t)(t + 2) * kstep; const char* b2 = last ? nB : cB + (size_t)(t + 2) * kstep;
;             const char* a3 = a2 + kstep; const char* b3 = b2 + kstep;
;             if (last && has_next) S.a_ready(nxt);
;             if constexpr (SP2) {
;             PG8_LDB(B0, 0, 0); PG8_LDB(B1, 0, 1); PG8_SCHED; PG8_LDA(At, 0, 0); PG8_STAGE(PG8_SA(1, 1), a1 + hstepA, voffA);
;             PG8_WAIT_V(8); PG8_WAIT_L(0); PG8_BAR; PG8_MMA(0, 0, At, B0); PG8_MMA(0, 1, At, B1); PG8_BAR; PG8_SCHED;
;             PG8_LDA(At, 0, 1); PG8_STAGE(PG8_SB(0, 0), b2, voffB); PG8_STAGE(PG8_SB(0, 1), b2 + hstepB, voffB); PG8_STAGE(PG8_SA(0, 0), a2, voffA);
.LBB0_1676:
	s_add_i32 s67, s44, 2
	s_add_u32 s34, s30, 0x100
	s_addc_u32 s35, s31, 0
	s_add_i32 s70, 0, 0x10000
	s_cmp_eq_u32 s59, s44
	s_cselect_b32 s45, s13, s35
	s_cselect_b32 s44, s12, s34
	s_cselect_b32 s69, s15, s66
	s_cselect_b32 s68, s14, s65
	s_add_i32 s71, 0, 0x14000
	v_add_u32_e32 v142, s70, v230
	v_add_u32_e32 v158, s71, v230
	ds_read_b128 v[114:117], v142
	ds_read_b128 v[126:129], v142 offset:1024
	ds_read_b128 v[138:141], v142 offset:2048
	ds_read_b128 v[142:145], v142 offset:3072
	ds_read_b128 v[146:149], v158
	ds_read_b128 v[150:153], v158 offset:1024
	ds_read_b128 v[154:157], v158 offset:2048
	ds_read_b128 v[158:161], v158 offset:3072
	v_lshl_add_u64 v[190:191], s[30:31], 0, v[200:201]
	s_add_i32 m0, s52, 0xc000
	ds_read_b128 v[162:165], v235
	ds_read_b128 v[166:169], v235 offset:1024
	ds_read_b128 v[170:173], v235 offset:2048
	ds_read_b128 v[174:177], v235 offset:3072
	ds_read_b128 v[178:181], v235 offset:4096
	ds_read_b128 v[182:185], v235 offset:5120
	ds_read_b128 v[204:207], v235 offset:6144
	ds_read_b128 v[208:211], v235 offset:7168
	global_load_lds_dwordx4 v[190:191], off
	v_lshl_add_u64 v[190:191], s[30:31], 0, v[202:203]
	s_add_i32 m0, s52, 0xe000
	s_nop 0
	global_load_lds_dwordx4 v[190:191], off
	s_waitcnt vmcnt(8)
	s_waitcnt lgkmcnt(0)
	s_barrier
	s_waitcnt lgkmcnt(0)
	v_mfma_f32_16x16x32_bf16 v[134:137], v[114:117], v[162:165], v[134:137]
	v_mfma_f32_16x16x32_bf16 v[130:133], v[138:141], v[162:165], v[130:133]
	v_mfma_f32_16x16x32_bf16 v[110:113], v[114:117], v[170:173], v[110:113]
	v_mfma_f32_16x16x32_bf16 v[106:109], v[138:141], v[170:173], v[106:109]
	v_mfma_f32_16x16x32_bf16 v[94:97], v[114:117], v[178:181], v[94:97]
	v_mfma_f32_16x16x32_bf16 v[90:93], v[138:141], v[178:181], v[90:93]
	v_mfma_f32_16x16x32_bf16 v[78:81], v[114:117], v[204:207], v[78:81]
	v_mfma_f32_16x16x32_bf16 v[74:77], v[138:141], v[204:207], v[74:77]
	v_mfma_f32_16x16x32_bf16 v[134:137], v[126:129], v[166:169], v[134:137]
	v_mfma_f32_16x16x32_bf16 v[130:133], v[142:145], v[166:169], v[130:133]
	v_mfma_f32_16x16x32_bf16 v[110:113], v[126:129], v[174:177], v[110:113]
	v_mfma_f32_16x16x32_bf16 v[106:109], v[142:145], v[174:177], v[106:109]
	v_mfma_f32_16x16x32_bf16 v[94:97], v[126:129], v[182:185], v[94:97]
	v_mfma_f32_16x16x32_bf16 v[90:93], v[142:145], v[182:185], v[90:93]
	v_mfma_f32_16x16x32_bf16 v[78:81], v[126:129], v[208:211], v[78:81]
	v_mfma_f32_16x16x32_bf16 v[74:77], v[142:145], v[208:211], v[74:77]
	v_mfma_f32_16x16x32_bf16 v[122:125], v[146:149], v[162:165], v[122:125]
	v_mfma_f32_16x16x32_bf16 v[118:121], v[154:157], v[162:165], v[118:121]
	v_mfma_f32_16x16x32_bf16 v[102:105], v[146:149], v[170:173], v[102:105]
	v_mfma_f32_16x16x32_bf16 v[98:101], v[154:157], v[170:173], v[98:101]
	v_mfma_f32_16x16x32_bf16 v[86:89], v[146:149], v[178:181], v[86:89]
	v_mfma_f32_16x16x32_bf16 v[82:85], v[154:157], v[178:181], v[82:85]
	v_mfma_f32_16x16x32_bf16 v[70:73], v[146:149], v[204:207], v[70:73]
	v_mfma_f32_16x16x32_bf16 v[66:69], v[154:157], v[204:207], v[66:69]
	v_mfma_f32_16x16x32_bf16 v[122:125], v[150:153], v[166:169], v[122:125]
	v_mfma_f32_16x16x32_bf16 v[118:121], v[158:161], v[166:169], v[118:121]
	v_mfma_f32_16x16x32_bf16 v[102:105], v[150:153], v[174:177], v[102:105]
	v_mfma_f32_16x16x32_bf16 v[98:101], v[158:161], v[174:177], v[98:101]
	v_mfma_f32_16x16x32_bf16 v[86:89], v[150:153], v[182:185], v[86:89]
	v_mfma_f32_16x16x32_bf16 v[82:85], v[158:161], v[182:185], v[82:85]
	v_mfma_f32_16x16x32_bf16 v[70:73], v[150:153], v[208:211], v[70:73]
	v_mfma_f32_16x16x32_bf16 v[66:69], v[158:161], v[208:211], v[66:69]
	s_barrier
	s_add_i32 s30, s70, s47
	v_lshl_add_u64 v[190:191], s[68:69], 0, v[0:1]
	s_mov_b32 m0, s30
	ds_read_b128 v[162:165], v235 offset:16384
	ds_read_b128 v[166:169], v235 offset:17408
	ds_read_b128 v[170:173], v235 offset:18432
	ds_read_b128 v[174:177], v235 offset:19456
	ds_read_b128 v[178:181], v235 offset:20480
	ds_read_b128 v[182:185], v235 offset:21504
	ds_read_b128 v[204:207], v235 offset:22528
	ds_read_b128 v[208:211], v235 offset:23552
	global_load_lds_dwordx4 v[190:191], off
	s_add_i32 m0, s30, 0x2000
	s_add_u32 s30, s68, s2
	v_lshl_add_u64 v[192:193], s[68:69], 0, v[198:199]
	s_addc_u32 s31, s69, s3
	s_add_i32 s68, s71, s47
	global_load_lds_dwordx4 v[192:193], off
	v_lshl_add_u64 v[212:213], s[30:31], 0, v[0:1]
	s_mov_b32 m0, s68
	v_lshl_add_u64 v[214:215], s[30:31], 0, v[198:199]
	global_load_lds_dwordx4 v[212:213], off
	s_add_i32 m0, s68, 0x2000
	v_lshl_add_u64 v[216:217], s[44:45], 0, v[194:195]
	global_load_lds_dwordx4 v[214:215], off
	s_mov_b32 m0, s52
	v_lshl_add_u64 v[218:219], s[44:45], 0, v[196:197]
	global_load_lds_dwordx4 v[216:217], off
	s_mov_b32 m0, s53
	s_nop 0
	global_load_lds_dwordx4 v[218:219], off
	s_waitcnt vmcnt(8)
	s_waitcnt lgkmcnt(0)
	s_barrier
; #define PG8_STAGE(bufoff, gbase, voff) do { _Pragma("unroll") for (int _i = 0; _i < 2; ++_i) \
;         __builtin_amdgcn_global_load_lds((const unsigned*)((const char*)(gbase) + (voff)[_i]), (PG8_LAS unsigned*)(lds + (bufoff) + ldsw + _i * 8192), 16, 0, 0); } while (0)
; #define PG8_LDA(dst, b, h) do { _Pragma("unroll") for (int m = 0; m < 4; ++m) _Pragma("unroll") for (int k = 0; k < 2; ++k) dst[m][k] = *(const PG8_LAS bf16x8*)(lds + PG8_SA(b, h) + aoff + m * 2048 + k * 1024); } while (0)
; #define PG8_LDB(dst, b, h) do { _Pragma("unroll") for (int n = 0; n < 2; ++n) _Pragma("unroll") for (int k = 0; k < 2; ++k) dst[n][k] = *(const PG8_LAS bf16x8*)(lds + PG8_SB(b, h) + boff + n * 2048 + k * 1024); } while (0)
; #define PG8_MMA(ai, bj, At, Bt) do { __builtin_amdgcn_s_setprio(1); _Pragma("unroll") for (int m = 0; m < 4; ++m) _Pragma("unroll") for (int n = 0; n < 2; ++n) _Pragma("unroll") for (int k = 0; k < 2; ++k) \
;         acc[ai][bj][m][n] = __builtin_amdgcn_mfma_f32_16x16x32_bf16(Bt[n][k], At[m][k], acc[ai][bj][m][n], 0, 0, 0); __builtin_amdgcn_s_setprio(0); } while (0)
; #define PG8_WAIT_V(n) asm volatile("s_waitcnt vmcnt(" #n ")" ::: "memory")
; #define PG8_WAIT_L(n) asm volatile("s_waitcnt lgkmcnt(" #n ")" ::: "memory")
; #define PG8_BAR __builtin_amdgcn_s_barrier()
; #define PG8_SCHED __builtin_amdgcn_sched_barrier(0)
; template <class Epi, class Sched, bool ALIGN_EPI = false, bool SP2 = false>
; __device__ __forceinline__ void gemm_phase(PG8_LAS unsigned char* lds, const Gemm g, const Sched& S, const Epi& E, const int wv) {
;     ...
;             PG8_WAIT_V(8); PG8_WAIT_L(0); PG8_BAR; PG8_MMA(1, 0, At, B0); PG8_MMA(1, 1, At, B1); PG8_BAR; PG8_SCHED;
;             PG8_LDB(B0, 1, 0); PG8_LDB(B1, 1, 1); PG8_SCHED; PG8_LDA(At, 1, 0); PG8_STAGE(PG8_SA(0, 1), a2 + hstepA, voffA);
;             PG8_WAIT_V(8); PG8_WAIT_L(0); PG8_BAR; PG8_MMA(0, 0, At, B0); PG8_MMA(0, 1, At, B1); PG8_BAR; PG8_SCHED;
	s_waitcnt lgkmcnt(0)
	v_mfma_f32_16x16x32_bf16 v[62:65], v[114:117], v[162:165], v[62:65]
	v_mfma_f32_16x16x32_bf16 v[58:61], v[138:141], v[162:165], v[58:61]
	v_mfma_f32_16x16x32_bf16 v[46:49], v[114:117], v[170:173], v[46:49]
	v_mfma_f32_16x16x32_bf16 v[42:45], v[138:141], v[170:173], v[42:45]
	v_mfma_f32_16x16x32_bf16 v[30:33], v[114:117], v[178:181], v[30:33]
	v_mfma_f32_16x16x32_bf16 v[26:29], v[138:141], v[178:181], v[26:29]
	v_mfma_f32_16x16x32_bf16 v[14:17], v[114:117], v[204:207], v[14:17]
	v_mfma_f32_16x16x32_bf16 v[10:13], v[138:141], v[204:207], v[10:13]
	v_mfma_f32_16x16x32_bf16 v[62:65], v[126:129], v[166:169], v[62:65]
	v_mfma_f32_16x16x32_bf16 v[58:61], v[142:145], v[166:169], v[58:61]
	v_mfma_f32_16x16x32_bf16 v[46:49], v[126:129], v[174:177], v[46:49]
	v_mfma_f32_16x16x32_bf16 v[42:45], v[142:145], v[174:177], v[42:45]
	v_mfma_f32_16x16x32_bf16 v[30:33], v[126:129], v[182:185], v[30:33]
	v_mfma_f32_16x16x32_bf16 v[26:29], v[142:145], v[182:185], v[26:29]
	v_mfma_f32_16x16x32_bf16 v[14:17], v[126:129], v[208:211], v[14:17]
	v_mfma_f32_16x16x32_bf16 v[10:13], v[142:145], v[208:211], v[10:13]
	v_mfma_f32_16x16x32_bf16 v[54:57], v[146:149], v[162:165], v[54:57]
	v_mfma_f32_16x16x32_bf16 v[50:53], v[154:157], v[162:165], v[50:53]
	v_mfma_f32_16x16x32_bf16 v[38:41], v[146:149], v[170:173], v[38:41]
	v_mfma_f32_16x16x32_bf16 v[34:37], v[154:157], v[170:173], v[34:37]
	v_mfma_f32_16x16x32_bf16 v[22:25], v[146:149], v[178:181], v[22:25]
	v_mfma_f32_16x16x32_bf16 v[18:21], v[154:157], v[178:181], v[18:21]
	v_mfma_f32_16x16x32_bf16 v[6:9], v[146:149], v[204:207], v[6:9]
	v_mfma_f32_16x16x32_bf16 v[2:5], v[154:157], v[204:207], v[2:5]
	v_mfma_f32_16x16x32_bf16 v[54:57], v[150:153], v[166:169], v[54:57]
	v_mfma_f32_16x16x32_bf16 v[50:53], v[158:161], v[166:169], v[50:53]
	v_mfma_f32_16x16x32_bf16 v[38:41], v[150:153], v[174:177], v[38:41]
	v_mfma_f32_16x16x32_bf16 v[34:37], v[158:161], v[174:177], v[34:37]
	v_mfma_f32_16x16x32_bf16 v[22:25], v[150:153], v[182:185], v[22:25]
	v_mfma_f32_16x16x32_bf16 v[18:21], v[158:161], v[182:185], v[18:21]
	v_mfma_f32_16x16x32_bf16 v[6:9], v[150:153], v[208:211], v[6:9]
	v_mfma_f32_16x16x32_bf16 v[2:5], v[158:161], v[208:211], v[2:5]
	s_barrier
	s_add_i32 s68, 0, 0x18000
	s_add_i32 s69, 0, 0x1c000
	v_add_u32_e32 v142, s68, v230
	v_add_u32_e32 v158, s69, v230
	ds_read_b128 v[114:117], v142
	ds_read_b128 v[126:129], v142 offset:1024
	ds_read_b128 v[138:141], v142 offset:2048
	ds_read_b128 v[142:145], v142 offset:3072
	ds_read_b128 v[146:149], v158
	ds_read_b128 v[150:153], v158 offset:1024
	ds_read_b128 v[154:157], v158 offset:2048
	ds_read_b128 v[158:161], v158 offset:3072
	s_add_u32 s30, s44, 0x180000
	s_addc_u32 s31, s45, 0
	s_mov_b32 m0, s54
	v_lshl_add_u64 v[236:237], s[30:31], 0, v[194:195]
	ds_read_b128 v[162:165], v235 offset:32768
	ds_read_b128 v[166:169], v235 offset:33792
	ds_read_b128 v[170:173], v235 offset:34816
	ds_read_b128 v[174:177], v235 offset:35840
	ds_read_b128 v[178:181], v235 offset:36864
	ds_read_b128 v[182:185], v235 offset:37888
	ds_read_b128 v[204:207], v235 offset:38912
	ds_read_b128 v[208:211], v235 offset:39936
	global_load_lds_dwordx4 v[236:237], off
	v_lshl_add_u64 v[236:237], s[30:31], 0, v[196:197]
	s_mov_b32 m0, s55
	s_nop 0
	global_load_lds_dwordx4 v[236:237], off
	s_waitcnt vmcnt(8)
	s_waitcnt lgkmcnt(0)
	s_barrier
	s_waitcnt lgkmcnt(0)
	v_mfma_f32_16x16x32_bf16 v[134:137], v[114:117], v[162:165], v[134:137]
	v_mfma_f32_16x16x32_bf16 v[130:133], v[138:141], v[162:165], v[130:133]
	v_mfma_f32_16x16x32_bf16 v[110:113], v[114:117], v[170:173], v[110:113]
	v_mfma_f32_16x16x32_bf16 v[106:109], v[138:141], v[170:173], v[106:109]
	v_mfma_f32_16x16x32_bf16 v[94:97], v[114:117], v[178:181], v[94:97]
	v_mfma_f32_16x16x32_bf16 v[90:93], v[138:141], v[178:181], v[90:93]
	v_mfma_f32_16x16x32_bf16 v[78:81], v[114:117], v[204:207], v[78:81]
	v_mfma_f32_16x16x32_bf16 v[74:77], v[138:141], v[204:207], v[74:77]
	v_mfma_f32_16x16x32_bf16 v[134:137], v[126:129], v[166:169], v[134:137]
	v_mfma_f32_16x16x32_bf16 v[130:133], v[142:145], v[166:169], v[130:133]
	v_mfma_f32_16x16x32_bf16 v[110:113], v[126:129], v[174:177], v[110:113]
	v_mfma_f32_16x16x32_bf16 v[106:109], v[142:145], v[174:177], v[106:109]
	v_mfma_f32_16x16x32_bf16 v[94:97], v[126:129], v[182:185], v[94:97]
	v_mfma_f32_16x16x32_bf16 v[90:93], v[142:145], v[182:185], v[90:93]
	v_mfma_f32_16x16x32_bf16 v[78:81], v[126:129], v[208:211], v[78:81]
	v_mfma_f32_16x16x32_bf16 v[74:77], v[142:145], v[208:211], v[74:77]
	v_mfma_f32_16x16x32_bf16 v[122:125], v[146:149], v[162:165], v[122:125]
	v_mfma_f32_16x16x32_bf16 v[118:121], v[154:157], v[162:165], v[118:121]
	v_mfma_f32_16x16x32_bf16 v[102:105], v[146:149], v[170:173], v[102:105]
	v_mfma_f32_16x16x32_bf16 v[98:101], v[154:157], v[170:173], v[98:101]
	v_mfma_f32_16x16x32_bf16 v[86:89], v[146:149], v[178:181], v[86:89]
	v_mfma_f32_16x16x32_bf16 v[82:85], v[154:157], v[178:181], v[82:85]
	v_mfma_f32_16x16x32_bf16 v[70:73], v[146:149], v[204:207], v[70:73]
	v_mfma_f32_16x16x32_bf16 v[66:69], v[154:157], v[204:207], v[66:69]
	v_mfma_f32_16x16x32_bf16 v[122:125], v[150:153], v[166:169], v[122:125]
	v_mfma_f32_16x16x32_bf16 v[118:121], v[158:161], v[166:169], v[118:121]
	v_mfma_f32_16x16x32_bf16 v[102:105], v[150:153], v[174:177], v[102:105]
	v_mfma_f32_16x16x32_bf16 v[98:101], v[158:161], v[174:177], v[98:101]
	v_mfma_f32_16x16x32_bf16 v[86:89], v[150:153], v[182:185], v[86:89]
	v_mfma_f32_16x16x32_bf16 v[82:85], v[158:161], v[182:185], v[82:85]
	v_mfma_f32_16x16x32_bf16 v[70:73], v[150:153], v[208:211], v[70:73]
	v_mfma_f32_16x16x32_bf16 v[66:69], v[158:161], v[208:211], v[66:69]
	s_barrier
; #define PG8_STAGE(bufoff, gbase, voff) do { _Pragma("unroll") for (int _i = 0; _i < 2; ++_i) \
;         __builtin_amdgcn_global_load_lds((const unsigned*)((const char*)(gbase) + (voff)[_i]), (PG8_LAS unsigned*)(lds + (bufoff) + ldsw + _i * 8192), 16, 0, 0); } while (0)
; #define PG8_LDA(dst, b, h) do { _Pragma("unroll") for (int m = 0; m < 4; ++m) _Pragma("unroll") for (int k = 0; k < 2; ++k) dst[m][k] = *(const PG8_LAS bf16x8*)(lds + PG8_SA(b, h) + aoff + m * 2048 + k * 1024); } while (0)
; #define PG8_MMA(ai, bj, At, Bt) do { __builtin_amdgcn_s_setprio(1); _Pragma("unroll") for (int m = 0; m < 4; ++m) _Pragma("unroll") for (int n = 0; n < 2; ++n) _Pragma("unroll") for (int k = 0; k < 2; ++k) \
;         acc[ai][bj][m][n] = __builtin_amdgcn_mfma_f32_16x16x32_bf16(Bt[n][k], At[m][k], acc[ai][bj][m][n], 0, 0, 0); __builtin_amdgcn_s_setprio(0); } while (0)
; #define PG8_WAIT_V(n) asm volatile("s_waitcnt vmcnt(" #n ")" ::: "memory")
; #define PG8_WAIT_L(n) asm volatile("s_waitcnt lgkmcnt(" #n ")" ::: "memory")
; #define PG8_BAR __builtin_amdgcn_s_barrier()
; #define PG8_SCHED __builtin_amdgcn_sched_barrier(0)
; template <class Epi, class Sched, bool ALIGN_EPI = false, bool SP2 = false>
; __device__ __forceinline__ void gemm_phase(PG8_LAS unsigned char* lds, const Gemm g, const Sched& S, const Epi& E, const int wv) {
;     ...
;         for (int t = 0; t < nt; t += 2) {
;             const bool last = (t == nt - 2);
;             const char* a1 = cA + (size_t)(t + 1) * kstep;
;             const char* a2 = last ? nA : cA + (size_t)(t + 2) * kstep; const char* b2 = last ? nB : cB + (size_t)(t + 2) * kstep;
;     ...
;             PG8_LDA(At, 1, 1); PG8_STAGE(PG8_SB(1, 0), b3, voffB); PG8_STAGE(PG8_SB(1, 1), b3 + hstepB, voffB); PG8_STAGE(PG8_SA(1, 0), a3, voffA);
;             PG8_WAIT_V(8); PG8_WAIT_L(0); PG8_BAR; PG8_MMA(1, 0, At, B0); PG8_MMA(1, 1, At, B1); PG8_BAR; PG8_SCHED;
	s_add_i32 s30, s68, s47
	v_lshl_add_u64 v[190:191], v[190:191], 0, s[4:5]
	s_mov_b32 m0, s30
	ds_read_b128 v[162:165], v235 offset:49152
	ds_read_b128 v[166:169], v235 offset:50176
	ds_read_b128 v[170:173], v235 offset:51200
	ds_read_b128 v[174:177], v235 offset:52224
	ds_read_b128 v[178:181], v235 offset:53248
	ds_read_b128 v[182:185], v235 offset:54272
	ds_read_b128 v[204:207], v235 offset:55296
	ds_read_b128 v[208:211], v235 offset:56320
	global_load_lds_dwordx4 v[190:191], off
	v_lshl_add_u64 v[190:191], v[192:193], 0, s[4:5]
	s_add_i32 m0, s30, 0x2000
	s_add_i32 s30, s69, s47
	global_load_lds_dwordx4 v[190:191], off
	v_lshl_add_u64 v[190:191], v[212:213], 0, s[4:5]
	s_mov_b32 m0, s30
	s_nop 0
	global_load_lds_dwordx4 v[190:191], off
	v_lshl_add_u64 v[190:191], v[214:215], 0, s[4:5]
	s_add_i32 m0, s30, 0x2000
	s_nop 0
	global_load_lds_dwordx4 v[190:191], off
	v_lshl_add_u64 v[190:191], v[216:217], 0, s[4:5]
	s_mov_b32 m0, s57
	s_nop 0
	global_load_lds_dwordx4 v[190:191], off
	v_lshl_add_u64 v[190:191], v[218:219], 0, s[4:5]
	s_mov_b32 m0, s58
	s_nop 0
	global_load_lds_dwordx4 v[190:191], off
	s_waitcnt vmcnt(8)
	s_waitcnt lgkmcnt(0)
	s_barrier
	s_waitcnt lgkmcnt(0)
	v_mfma_f32_16x16x32_bf16 v[62:65], v[114:117], v[162:165], v[62:65]
	v_mfma_f32_16x16x32_bf16 v[58:61], v[138:141], v[162:165], v[58:61]
	v_mfma_f32_16x16x32_bf16 v[46:49], v[114:117], v[170:173], v[46:49]
	v_mfma_f32_16x16x32_bf16 v[42:45], v[138:141], v[170:173], v[42:45]
	v_mfma_f32_16x16x32_bf16 v[30:33], v[114:117], v[178:181], v[30:33]
	v_mfma_f32_16x16x32_bf16 v[26:29], v[138:141], v[178:181], v[26:29]
	v_mfma_f32_16x16x32_bf16 v[14:17], v[114:117], v[204:207], v[14:17]
	v_mfma_f32_16x16x32_bf16 v[10:13], v[138:141], v[204:207], v[10:13]
	v_mfma_f32_16x16x32_bf16 v[62:65], v[126:129], v[166:169], v[62:65]
	v_mfma_f32_16x16x32_bf16 v[58:61], v[142:145], v[166:169], v[58:61]
	v_mfma_f32_16x16x32_bf16 v[46:49], v[126:129], v[174:177], v[46:49]
	v_mfma_f32_16x16x32_bf16 v[42:45], v[142:145], v[174:177], v[42:45]
	v_mfma_f32_16x16x32_bf16 v[30:33], v[126:129], v[182:185], v[30:33]
	v_mfma_f32_16x16x32_bf16 v[26:29], v[142:145], v[182:185], v[26:29]
	v_mfma_f32_16x16x32_bf16 v[14:17], v[126:129], v[208:211], v[14:17]
	v_mfma_f32_16x16x32_bf16 v[10:13], v[142:145], v[208:211], v[10:13]
	v_mfma_f32_16x16x32_bf16 v[54:57], v[146:149], v[162:165], v[54:57]
	v_mfma_f32_16x16x32_bf16 v[50:53], v[154:157], v[162:165], v[50:53]
	v_mfma_f32_16x16x32_bf16 v[38:41], v[146:149], v[170:173], v[38:41]
	v_mfma_f32_16x16x32_bf16 v[34:37], v[154:157], v[170:173], v[34:37]
	v_mfma_f32_16x16x32_bf16 v[22:25], v[146:149], v[178:181], v[22:25]
	v_mfma_f32_16x16x32_bf16 v[18:21], v[154:157], v[178:181], v[18:21]
	v_mfma_f32_16x16x32_bf16 v[6:9], v[146:149], v[204:207], v[6:9]
	v_mfma_f32_16x16x32_bf16 v[2:5], v[154:157], v[204:207], v[2:5]
	v_mfma_f32_16x16x32_bf16 v[54:57], v[150:153], v[166:169], v[54:57]
	v_mfma_f32_16x16x32_bf16 v[50:53], v[158:161], v[166:169], v[50:53]
	v_mfma_f32_16x16x32_bf16 v[38:41], v[150:153], v[174:177], v[38:41]
	v_mfma_f32_16x16x32_bf16 v[34:37], v[158:161], v[174:177], v[34:37]
	v_mfma_f32_16x16x32_bf16 v[22:25], v[150:153], v[182:185], v[22:25]
	v_mfma_f32_16x16x32_bf16 v[18:21], v[158:161], v[182:185], v[18:21]
	v_mfma_f32_16x16x32_bf16 v[6:9], v[150:153], v[208:211], v[6:9]
	v_mfma_f32_16x16x32_bf16 v[2:5], v[158:161], v[208:211], v[2:5]
	s_barrier
	s_add_u32 s65, s65, 0x100
	s_addc_u32 s66, s66, 0
	s_cmp_ge_i32 s67, s56
	s_mov_b64 s[30:31], s[34:35]
	s_mov_b32 s44, s67
	s_cbranch_scc0 .LBB0_1676
	s_movk_i32 s68, 0x4000
	s_movk_i32 s69, 0x6000
	s_mov_b32 s70, 0x18000
	s_mov_b32 s71, 0x3f317217
	s_and_b64 vcc, exec, s[28:29]
	s_cbranch_vccz .LBB0_1652
